# in-proj epilogue fully hand-specialised per column type (adds rope64, rope32, qk-norm(+rope) paths with DPP reductions and hoisted sin/cos tables); compiler's generic divergent epilogue removed
# speedup vs baseline: 1.3524x; 1.0414x over previous
; template <int EPI>
; DI bool tile_coords(int j, int mpx, int& m0, int& n0) {
;   const int x = blockIdx.x & 7, s = blockIdx.x >> 3, ns = gridDim.x >> 3;
;   const int q = s + ns * j;
;   if constexpr (EPI == 0) {
;     if (q >= mpx * 15) return false;
;     const int panel = q / 90, i = q % 90;
;     const int nt = i / 6, mi = i % 6;
;     m0 = (x * mpx + panel * 6 + mi) * 256;
;     n0 = nt * 256;
;   } else {
;     if (q >= mpx * 4) return false;
;     m0 = (x * mpx + (q >> 2)) * 256;
;     n0 = (q & 3) * 256;
;   }
.Ltile_l1_c:
	s_sub_i32 s2, s2, 0xf0
	s_cmp_ge_u32 s2, 7
	s_cselect_b32 s42, 1, 0
	s_cselect_b32 s43, 7, 0
	s_sub_i32 s2, s2, s43
	s_lshl_b32 s2, s2, 2
	s_mov_b32 s43, 0xa875321
	s_lshr_b32 s43, s43, s2
	s_and_b32 s43, s43, 15
	s_lshl_b32 s44, s44, 1
	s_add_i32 s42, s42, s44
	s_addk_i32 s42, 0x80
	s_lshl_b32 s56, s42, 8
	s_lshl_b32 s51, s43, 8
	s_branch .LBB0_81
.LBB0_79:
	s_add_i32 s26, s26, 1
	s_mul_i32 s2, s26, s27
	s_add_i32 s2, s2, s84
	s_movk_i32 s42, 0x10d
	s_cmp_eq_u32 s50, 1
	s_cselect_b32 s42, 0xfd, s42
	s_cmp_gt_u32 s2, s42
	s_cselect_b64 s[54:55], -1, 0
	s_and_b64 vcc, exec, s[54:55]
	s_mov_b32 s51, 0
	s_mov_b32 s56, 0
	s_cbranch_vccnz .LBB0_81
	s_cmp_eq_u32 s50, 1
	s_cbranch_scc1 .Ltile_l1
	s_and_b32 s42, s2, 0xffff
	s_mulk_i32 s42, 0x2d83
	s_lshr_b32 s42, s42, 20
	s_mul_i32 s43, s42, 0x5a
	s_sub_i32 s2, s2, s43
	s_mul_i32 s43, s2, 0xab
	s_bfe_u32 s43, s43, 0x6000a
	s_mul_i32 s44, s43, 6
	s_sub_i32 s2, s2, s44
	s_mul_i32 s42, s42, 6
	v_readlane_b32 s44, v254, 12
	s_and_b32 s2, s2, 0xff
	s_add_i32 s42, s44, s42
	s_add_i32 s42, s42, s2
	s_lshl_b32 s56, s42, 8
	s_lshl_b32 s51, s43, 8

; #define GCOMPUTE(AS, BS) GCOMPUTE_KS(AS, BS, 0) GCOMPUTE_KS(AS, BS, 1)
; template <int EPI>
; DI void gemm_phase(const P& p, int l, const u16* __restrict__ A, const u16* __restrict__ Bt, int mpx, char* lds) {
;     ...
;   __syncthreads();
;   __builtin_amdgcn_sched_barrier(0);
;   GCOMPUTE(As1, Bs1)
;   __builtin_amdgcn_sched_barrier(0);
.Lgemm_in_exit:
	v_mfma_f32_16x16x32_bf16 v[102:105], v[246:249], v[162:165], v[102:105]
	v_mfma_f32_16x16x32_bf16 v[106:109], v[246:249], v[166:169], v[106:109]
	v_mfma_f32_16x16x32_bf16 v[110:113], v[246:249], v[170:173], v[110:113]
	v_mfma_f32_16x16x32_bf16 v[114:117], v[246:249], v[174:177], v[114:117]
	v_mfma_f32_16x16x32_bf16 v[118:121], v[250:253], v[162:165], v[118:121]
	v_mfma_f32_16x16x32_bf16 v[122:125], v[250:253], v[166:169], v[122:125]
	v_mfma_f32_16x16x32_bf16 v[126:129], v[250:253], v[170:173], v[126:129]
	v_mfma_f32_16x16x32_bf16 v[2:5], v[250:253], v[174:177], v[2:5]
	s_barrier
	ds_read_b128 v[162:165], v199
	ds_read_b128 v[166:169], v198
	ds_read_b128 v[170:173], v198 offset:2048
	ds_read_b128 v[174:177], v198 offset:4096
	ds_read_b128 v[178:181], v198 offset:6144
	s_waitcnt lgkmcnt(3)
	v_mfma_f32_16x16x32_bf16 v[6:9], v[162:165], v[166:169], v[6:9]
	s_waitcnt lgkmcnt(2)
	v_mfma_f32_16x16x32_bf16 v[10:13], v[162:165], v[170:173], v[10:13]
	s_waitcnt lgkmcnt(1)
	v_mfma_f32_16x16x32_bf16 v[14:17], v[162:165], v[174:177], v[14:17]
	s_waitcnt lgkmcnt(0)
	v_mfma_f32_16x16x32_bf16 v[18:21], v[162:165], v[178:181], v[18:21]
	ds_read_b128 v[162:165], v199 offset:2048
	s_waitcnt lgkmcnt(0)
	v_mfma_f32_16x16x32_bf16 v[22:25], v[162:165], v[166:169], v[22:25]
	v_mfma_f32_16x16x32_bf16 v[26:29], v[162:165], v[170:173], v[26:29]
	v_mfma_f32_16x16x32_bf16 v[30:33], v[162:165], v[174:177], v[30:33]
	v_mfma_f32_16x16x32_bf16 v[34:37], v[162:165], v[178:181], v[34:37]
	ds_read_b128 v[162:165], v199 offset:4096
	s_waitcnt lgkmcnt(0)
	v_mfma_f32_16x16x32_bf16 v[38:41], v[162:165], v[166:169], v[38:41]
	v_mfma_f32_16x16x32_bf16 v[42:45], v[162:165], v[170:173], v[42:45]
	v_mfma_f32_16x16x32_bf16 v[46:49], v[162:165], v[174:177], v[46:49]
	v_mfma_f32_16x16x32_bf16 v[50:53], v[162:165], v[178:181], v[50:53]
	ds_read_b128 v[162:165], v199 offset:6144
	s_waitcnt lgkmcnt(0)
	v_mfma_f32_16x16x32_bf16 v[54:57], v[162:165], v[166:169], v[54:57]
	v_mfma_f32_16x16x32_bf16 v[58:61], v[162:165], v[170:173], v[58:61]
	v_mfma_f32_16x16x32_bf16 v[62:65], v[162:165], v[174:177], v[62:65]
	v_mfma_f32_16x16x32_bf16 v[66:69], v[162:165], v[178:181], v[66:69]
	ds_read_b128 v[162:165], v199 offset:8192
	s_waitcnt lgkmcnt(0)
	v_mfma_f32_16x16x32_bf16 v[182:185], v[162:165], v[166:169], v[70:73]
	s_nop 2
	ds_read_b128 v[70:73], v199 offset:10240
	v_mfma_f32_16x16x32_bf16 v[186:189], v[162:165], v[170:173], v[74:77]
	s_nop 2
	ds_read_b128 v[74:77], v233
	s_waitcnt lgkmcnt(1)
	v_mfma_f32_16x16x32_bf16 v[212:215], v[70:73], v[166:169], v[86:89]
	v_mfma_f32_16x16x32_bf16 v[216:219], v[70:73], v[170:173], v[90:93]
	v_mfma_f32_16x16x32_bf16 v[220:223], v[70:73], v[174:177], v[94:97]
	v_mfma_f32_16x16x32_bf16 v[234:237], v[70:73], v[178:181], v[98:101]
	ds_read_b128 v[70:73], v199 offset:12288
	s_waitcnt lgkmcnt(0)
	v_mfma_f32_16x16x32_bf16 v[238:241], v[70:73], v[166:169], v[102:105]
	v_mfma_f32_16x16x32_bf16 v[242:245], v[70:73], v[170:173], v[106:109]
	v_mfma_f32_16x16x32_bf16 v[246:249], v[70:73], v[174:177], v[110:113]
	v_mfma_f32_16x16x32_bf16 v[250:253], v[70:73], v[178:181], v[114:117]
	ds_read_b128 v[70:73], v199 offset:14336
	v_mfma_f32_16x16x32_bf16 v[190:193], v[162:165], v[174:177], v[78:81]
	v_mfma_f32_16x16x32_bf16 v[162:165], v[162:165], v[178:181], v[82:85]
	s_waitcnt lgkmcnt(0)
	v_mfma_f32_16x16x32_bf16 v[178:181], v[70:73], v[178:181], v[2:5]
	s_nop 2
	ds_read_b128 v[2:5], v200
	v_mfma_f32_16x16x32_bf16 v[174:177], v[70:73], v[174:177], v[126:129]
	s_waitcnt lgkmcnt(0)
	v_mfma_f32_16x16x32_bf16 v[126:129], v[74:77], v[2:5], v[6:9]
	s_nop 2
	ds_read_b128 v[6:9], v200 offset:2048
	v_mfma_f32_16x16x32_bf16 v[170:173], v[70:73], v[170:173], v[122:125]
	s_waitcnt lgkmcnt(0)
	v_mfma_f32_16x16x32_bf16 v[122:125], v[74:77], v[6:9], v[10:13]
	s_nop 2
	ds_read_b128 v[10:13], v200 offset:4096
	v_mfma_f32_16x16x32_bf16 v[166:169], v[70:73], v[166:169], v[118:121]
	s_waitcnt lgkmcnt(0)
	v_mfma_f32_16x16x32_bf16 v[118:121], v[74:77], v[10:13], v[14:17]
	s_nop 2
	ds_read_b128 v[14:17], v200 offset:6144
	s_waitcnt lgkmcnt(0)
	v_mfma_f32_16x16x32_bf16 v[114:117], v[74:77], v[14:17], v[18:21]
	s_nop 2
	ds_read_b128 v[18:21], v233 offset:2048
	s_waitcnt lgkmcnt(0)
	v_mfma_f32_16x16x32_bf16 v[110:113], v[18:21], v[2:5], v[22:25]
	v_mfma_f32_16x16x32_bf16 v[106:109], v[18:21], v[6:9], v[26:29]
	v_mfma_f32_16x16x32_bf16 v[102:105], v[18:21], v[10:13], v[30:33]
	v_mfma_f32_16x16x32_bf16 v[98:101], v[18:21], v[14:17], v[34:37]
	ds_read_b128 v[18:21], v233 offset:4096
	s_waitcnt lgkmcnt(0)
	v_mfma_f32_16x16x32_bf16 v[94:97], v[18:21], v[2:5], v[38:41]
	v_mfma_f32_16x16x32_bf16 v[90:93], v[18:21], v[6:9], v[42:45]
	v_mfma_f32_16x16x32_bf16 v[86:89], v[18:21], v[10:13], v[46:49]
	v_mfma_f32_16x16x32_bf16 v[82:85], v[18:21], v[14:17], v[50:53]
	ds_read_b128 v[18:21], v233 offset:6144
	s_waitcnt lgkmcnt(0)
	v_mfma_f32_16x16x32_bf16 v[78:81], v[18:21], v[2:5], v[54:57]
	v_mfma_f32_16x16x32_bf16 v[74:77], v[18:21], v[6:9], v[58:61]
	v_mfma_f32_16x16x32_bf16 v[70:73], v[18:21], v[10:13], v[62:65]
	v_mfma_f32_16x16x32_bf16 v[66:69], v[18:21], v[14:17], v[66:69]
	ds_read_b128 v[18:21], v233 offset:8192
	s_waitcnt lgkmcnt(0)
	v_mfma_f32_16x16x32_bf16 v[62:65], v[18:21], v[2:5], v[182:185]
	s_nop 2
	ds_read_b128 v[182:185], v233 offset:14336
	v_mfma_f32_16x16x32_bf16 v[58:61], v[18:21], v[6:9], v[186:189]
	v_mfma_f32_16x16x32_bf16 v[54:57], v[18:21], v[10:13], v[190:193]
	v_mfma_f32_16x16x32_bf16 v[50:53], v[18:21], v[14:17], v[162:165]
	ds_read_b128 v[18:21], v233 offset:10240
	s_waitcnt lgkmcnt(0)
	v_mfma_f32_16x16x32_bf16 v[46:49], v[18:21], v[2:5], v[212:215]
	v_mfma_f32_16x16x32_bf16 v[42:45], v[18:21], v[6:9], v[216:219]
	v_mfma_f32_16x16x32_bf16 v[38:41], v[18:21], v[10:13], v[220:223]
	v_mfma_f32_16x16x32_bf16 v[34:37], v[18:21], v[14:17], v[234:237]
	ds_read_b128 v[18:21], v233 offset:12288
	s_waitcnt lgkmcnt(0)
	v_mfma_f32_16x16x32_bf16 v[30:33], v[18:21], v[2:5], v[238:241]
	v_mfma_f32_16x16x32_bf16 v[26:29], v[18:21], v[6:9], v[242:245]
	v_mfma_f32_16x16x32_bf16 v[22:25], v[18:21], v[10:13], v[246:249]
	v_mfma_f32_16x16x32_bf16 v[18:21], v[18:21], v[14:17], v[250:253]
	v_mfma_f32_16x16x32_bf16 v[166:169], v[182:185], v[2:5], v[166:169]
	v_mfma_f32_16x16x32_bf16 v[162:165], v[182:185], v[6:9], v[170:173]
	v_mfma_f32_16x16x32_bf16 v[2:5], v[182:185], v[10:13], v[174:177]
	v_mfma_f32_16x16x32_bf16 v[6:9], v[182:185], v[14:17], v[178:181]
	s_barrier
; DI int tidx() { int t = threadIdx.x; asm volatile("" : "+v"(t)); return t; }
; template <int EPI>
; DI void gemm_phase(const P& p, int l, const u16* __restrict__ A, const u16* __restrict__ Bt, int mpx, char* lds) {
;     ...
;   GSTORE(As0, Bs0)
;   const int tid_e = tidx();
;   const int lane = tid_e & 63, w = tid_e >> 6, r = lane & 15, g = lane >> 4, wm = w >> 2, wn = w & 3;
;     ...
;     if (cb >= 2816) { kind = 2; tr = 1; }
;     else if (cb < 256) tr = 1;
;     else if (cb < 512) tr = 0;
;     else if (cb < 1024) tr = 2;
;     else if (cb < 1408) { tr = 3; donorm = true; }
;     else if (cb < 1536) kind = 1;
;     else if (cb < 2048) tr = isctx ? 0 : 4;
;     else if (cb < 2304) kind = 1;
;     else if (cb < 2688) tr = isctx ? 0 : 3;
;     else kind = 1;
;     const float* gw = (cb < 1280 ? p.ga_qn : p.ga_kn) + l * 64;
;     float gv0 = 1.f, gv1 = 1.f, gv2 = 1.f, gv3 = 1.f;
;     if (donorm) { gv0 = gw[r]; gv1 = gw[16 + r]; gv2 = gw[32 + r]; gv3 = gw[48 + r]; }
;     const bool dorope = (tr == 3) && !isctx;
;     const float invf64 = exp2f(-13.287712379549449f * (float)r * (1.f / 16.f));
;     const float invf32 = exp2f(-13.287712379549449f * (float)(r & 7) * (1.f / 8.f));
;     const bool lo8 = r < 8;
;     u16* dst;
;     size_t rstride;
;     if (kind == 2) {
;       dst = p.G + (size_t)(m0 + wm * 128) * 1024 + (cb - 2816);
;       rstride = 1024;
;     } else if (kind == 1) {
;       dst = slab_ptr(p, cb >> 6, b) + tokw;
;       rstride = T;
;     } else {
;       dst = slab_ptr(p, cb >> 6, b) + (size_t)tokw * 64;
;       rstride = 64;
;     }
	s_waitcnt vmcnt(7)
	ds_write_b128 v201, v[130:133]
	s_waitcnt vmcnt(5)
	ds_write_b128 v201, v[134:137] offset:8192
	s_waitcnt vmcnt(4)
	ds_write_b128 v201, v[138:141] offset:16384
	s_waitcnt vmcnt(3)
	ds_write_b128 v201, v[142:145] offset:24576
	ds_write_b128 v201, v[146:149] offset:32768
	s_waitcnt vmcnt(2)
	ds_write_b128 v201, v[150:153] offset:40960
	s_waitcnt vmcnt(1)
	ds_write_b128 v201, v[154:157] offset:49152
	s_waitcnt vmcnt(0)
	ds_write_b128 v201, v[158:161] offset:57344
	v_readfirstlane_b32 s40, v195
	s_lshr_b32 s40, s40, 6
	s_and_b32 s41, s40, 3
	s_lshr_b32 s42, s40, 2
	s_lshr_b32 s43, s46, 6
	s_add_i32 s43, s43, s41
	s_cmp_ge_u32 s66, 0x8000
	s_cselect_b32 s67, 1, 0
	s_mov_b32 s44, 0xffff
	s_mov_b32 s45, 0
	s_bitcmp1_b64 s[44:45], s43
	s_cbranch_scc1 .Lfe_kind0
	s_mov_b32 s44, 0xc00000
	s_mov_b32 s45, 0xc0f
	s_bitcmp1_b64 s[44:45], s43
	s_cbranch_scc1 .Lfe_kind1
	s_cmp_ge_u32 s43, 44
	s_cbranch_scc1 .Lfe_kind2
	s_branch .Lfe_kind0
.Lfe_kind0:
	s_sub_u32 s68, s66, 0x8000
	s_lshr_b32 s68, s68, 8
	s_lshr_b32 s69, s66, 11
	s_and_b32 s70, s66, 0x7ff
	s_cmp_eq_u32 s67, 0
	s_cselect_b32 s68, s69, s68
	s_cselect_b32 s69, s70, 0x800
	s_lshl_b32 s70, s42, 7
	s_add_i32 s69, s69, s70
	s_mul_i32 s70, s40, 0x2400
	s_add_i32 s70, s70, s78
	v_and_b32_e32 v173, 15, v226
	v_lshrrev_b32_e32 v0, 4, v226
	v_mul_u32_u24_e32 v170, 0x240, v0
	v_lshl_add_u32 v170, v173, 1, v170
	v_add_u32_e32 v170, s70, v170
	v_lshrrev_b32_e32 v0, 3, v226
	v_and_b32_e32 v173, 7, v226
	v_mul_u32_u24_e32 v171, 0x90, v0
	v_lshl_add_u32 v171, v173, 4, v171
	v_add_u32_e32 v171, s70, v171
	v_lshlrev_b32_e32 v172, 4, v226
	s_lshl_b32 s70, s43, 4
	s_add_i32 s70, s70, s68
	s_mul_hi_u32 s71, s70, 0x48000
	s_mul_i32 s70, s70, 0x48000
	s_add_u32 s44, s18, s70
	s_addc_u32 s45, s19, s71
	s_lshl_b32 s70, s69, 7
	s_add_u32 s44, s44, s70
	s_addc_u32 s45, s45, 0
	s_cmp_lt_u32 s43, 4
	s_cbranch_scc1 .Lfe_k0_silu
	s_cmp_lt_u32 s43, 8
	s_cbranch_scc1 .Lfe_k0_plain
	s_cmp_lt_u32 s43, 16
	s_cbranch_scc1 .Lfe_k0_fp16
	s_cmp_lt_u32 s43, 22
	s_cbranch_scc1 .Lfe_k0_nr
	s_cmp_eq_u32 s67, 0
	s_cbranch_scc0 .Lfe_k0_plain
	s_cmp_lt_u32 s43, 32
	s_cbranch_scc1 .Lfe_k0_rope32
	s_branch .Lfe_k0_rope64
.Lfe_k0_nr:
	s_cmp_eq_u32 s67, 0
	s_cbranch_scc1 .Lfe_k0_normrope
	s_branch .Lfe_k0_norm

; DI void sincos_rev(float ang, float& s, float& c) {
;   float rev = ang * 0.15915494309189535f;
;   rev -= rintf(rev);
;   s = __builtin_amdgcn_sinf(rev);
;   c = __builtin_amdgcn_cosf(rev);
; }
; template <int EPI>
; DI void gemm_phase(const P& p, int l, const u16* __restrict__ A, const u16* __restrict__ Bt, int mpx, char* lds) {
;     ...
;             if (dorope) {
;               float sr, cr, sc, cc;
;               sincos_rev((float)(s >> 6) * invf64, sr, cr);
;               sincos_rev((float)(s & 63) * invf64, sc, cc);
;               const float a1 = v0, a2 = v1, b1 = v2, b2 = v3;
;               v0 = a1 * cr - a2 * sr;
;               v1 = a2 * cr + a1 * sr;
;               v2 = b1 * cc - b2 * sc;
;               v3 = b2 * cc + b1 * sc;
;             }
.Lfe_k0_rope64:
	v_and_b32_e32 v0, 15, v226
	v_cvt_f32_ubyte0_e32 v0, v0
	v_mul_f32_e32 v0, 0xc1549a78, v0
	v_mul_f32_e32 v0, 0x3d800000, v0
	v_exp_f32_e32 v174, v0
	v_lshrrev_b32_e32 v0, 4, v226
	v_lshlrev_b32_e32 v0, 2, v0
	v_add_u32_e32 v182, 0, v0
	v_cvt_f32_i32_e32 v182, v182
	v_mul_f32_e32 v182, v174, v182
	v_mul_f32_e32 v183, 0.15915494, v182
	v_rndne_f32_e32 v183, v183
	v_fma_f32 v183, v182, 0.15915494, -v183
	v_sin_f32_e32 v212, v183
	v_cos_f32_e32 v238, v183
	v_add_u32_e32 v182, 1, v0
	v_cvt_f32_i32_e32 v182, v182
	v_mul_f32_e32 v182, v174, v182
	v_mul_f32_e32 v183, 0.15915494, v182
	v_rndne_f32_e32 v183, v183
	v_fma_f32 v183, v182, 0.15915494, -v183
	v_sin_f32_e32 v213, v183
	v_cos_f32_e32 v239, v183
	v_add_u32_e32 v182, 2, v0
	v_cvt_f32_i32_e32 v182, v182
	v_mul_f32_e32 v182, v174, v182
	v_mul_f32_e32 v183, 0.15915494, v182
	v_rndne_f32_e32 v183, v183
	v_fma_f32 v183, v182, 0.15915494, -v183
	v_sin_f32_e32 v214, v183
	v_cos_f32_e32 v240, v183
	v_add_u32_e32 v182, 3, v0
	v_cvt_f32_i32_e32 v182, v182
	v_mul_f32_e32 v182, v174, v182
	v_mul_f32_e32 v183, 0.15915494, v182
	v_rndne_f32_e32 v183, v183
	v_fma_f32 v183, v182, 0.15915494, -v183
	v_sin_f32_e32 v215, v183
	v_cos_f32_e32 v241, v183
	v_add_u32_e32 v182, 16, v0
	v_cvt_f32_i32_e32 v182, v182
	v_mul_f32_e32 v182, v174, v182
	v_mul_f32_e32 v183, 0.15915494, v182
	v_rndne_f32_e32 v183, v183
	v_fma_f32 v183, v182, 0.15915494, -v183
	v_sin_f32_e32 v216, v183
	v_cos_f32_e32 v242, v183
	v_add_u32_e32 v182, 17, v0
	v_cvt_f32_i32_e32 v182, v182
	v_mul_f32_e32 v182, v174, v182
	v_mul_f32_e32 v183, 0.15915494, v182
	v_rndne_f32_e32 v183, v183
	v_fma_f32 v183, v182, 0.15915494, -v183
	v_sin_f32_e32 v217, v183
	v_cos_f32_e32 v243, v183
	v_add_u32_e32 v182, 18, v0
	v_cvt_f32_i32_e32 v182, v182
	v_mul_f32_e32 v182, v174, v182
	v_mul_f32_e32 v183, 0.15915494, v182
	v_rndne_f32_e32 v183, v183
	v_fma_f32 v183, v182, 0.15915494, -v183
	v_sin_f32_e32 v218, v183
	v_cos_f32_e32 v244, v183
	v_add_u32_e32 v182, 19, v0
	v_cvt_f32_i32_e32 v182, v182
	v_mul_f32_e32 v182, v174, v182
	v_mul_f32_e32 v183, 0.15915494, v182
	v_rndne_f32_e32 v183, v183
	v_fma_f32 v183, v182, 0.15915494, -v183
	v_sin_f32_e32 v219, v183
	v_cos_f32_e32 v245, v183
	v_add_u32_e32 v182, 32, v0
	v_cvt_f32_i32_e32 v182, v182
	v_mul_f32_e32 v182, v174, v182
	v_mul_f32_e32 v183, 0.15915494, v182
	v_rndne_f32_e32 v183, v183
	v_fma_f32 v183, v182, 0.15915494, -v183
	v_sin_f32_e32 v220, v183
	v_cos_f32_e32 v246, v183
	v_add_u32_e32 v182, 33, v0
	v_cvt_f32_i32_e32 v182, v182
	v_mul_f32_e32 v182, v174, v182
	v_mul_f32_e32 v183, 0.15915494, v182
	v_rndne_f32_e32 v183, v183
	v_fma_f32 v183, v182, 0.15915494, -v183
	v_sin_f32_e32 v221, v183
	v_cos_f32_e32 v247, v183
	v_add_u32_e32 v182, 34, v0
	v_cvt_f32_i32_e32 v182, v182
	v_mul_f32_e32 v182, v174, v182
	v_mul_f32_e32 v183, 0.15915494, v182
	v_rndne_f32_e32 v183, v183
	v_fma_f32 v183, v182, 0.15915494, -v183
	v_sin_f32_e32 v222, v183
	v_cos_f32_e32 v248, v183
	v_add_u32_e32 v182, 35, v0
	v_cvt_f32_i32_e32 v182, v182
	v_mul_f32_e32 v182, v174, v182
	v_mul_f32_e32 v183, 0.15915494, v182
	v_rndne_f32_e32 v183, v183
	v_fma_f32 v183, v182, 0.15915494, -v183
	v_sin_f32_e32 v223, v183
	v_cos_f32_e32 v249, v183
	v_add_u32_e32 v182, 48, v0
	v_cvt_f32_i32_e32 v182, v182
	v_mul_f32_e32 v182, v174, v182
	v_mul_f32_e32 v183, 0.15915494, v182
	v_rndne_f32_e32 v183, v183
	v_fma_f32 v183, v182, 0.15915494, -v183
	v_sin_f32_e32 v234, v183
	v_cos_f32_e32 v250, v183
	v_add_u32_e32 v182, 49, v0
	v_cvt_f32_i32_e32 v182, v182
	v_mul_f32_e32 v182, v174, v182
	v_mul_f32_e32 v183, 0.15915494, v182
	v_rndne_f32_e32 v183, v183
	v_fma_f32 v183, v182, 0.15915494, -v183
	v_sin_f32_e32 v235, v183
	v_cos_f32_e32 v251, v183
	v_add_u32_e32 v182, 50, v0
	v_cvt_f32_i32_e32 v182, v182
	v_mul_f32_e32 v182, v174, v182
	v_mul_f32_e32 v183, 0.15915494, v182
	v_rndne_f32_e32 v183, v183
	v_fma_f32 v183, v182, 0.15915494, -v183
	v_sin_f32_e32 v236, v183
	v_cos_f32_e32 v252, v183
	v_add_u32_e32 v182, 51, v0
	v_cvt_f32_i32_e32 v182, v182
	v_mul_f32_e32 v182, v174, v182
	v_mul_f32_e32 v183, 0.15915494, v182
	v_rndne_f32_e32 v183, v183
	v_fma_f32 v183, v182, 0.15915494, -v183
	v_sin_f32_e32 v237, v183
	v_cos_f32_e32 v253, v183
	s_add_u32 s62, s44, 0x1000
	s_addc_u32 s63, s45, 0
	s_lshr_b32 s70, s69, 6
	v_cvt_f32_i32_e32 v182, s70
	v_mul_f32_e32 v182, v174, v182
	v_mul_f32_e32 v183, 0.15915494, v182
	v_rndne_f32_e32 v183, v183
	v_fma_f32 v183, v182, 0.15915494, -v183
	v_sin_f32_e32 v175, v183
	v_cos_f32_e32 v176, v183
	v_mul_f32_e32 v186, v175, v122
	v_mul_f32_e32 v187, v176, v122
	v_fma_f32 v188, v176, v126, -v186
	v_fma_f32 v189, v175, v126, v187
	v_mul_f32_e32 v186, v212, v114
	v_mul_f32_e32 v187, v238, v114
	v_fma_f32 v190, v238, v118, -v186
	v_fma_f32 v191, v212, v118, v187
	v_cvt_pk_bf16_f32 v192, v188, v189
	v_cvt_pk_bf16_f32 v193, v190, v191
	ds_write_b16 v170, v192 offset:0
	ds_write_b16_d16_hi v170, v192 offset:32
	ds_write_b16 v170, v193 offset:64
	ds_write_b16_d16_hi v170, v193 offset:96
	v_mul_f32_e32 v186, v175, v123
	v_mul_f32_e32 v187, v176, v123
	v_fma_f32 v188, v176, v127, -v186
	v_fma_f32 v189, v175, v127, v187
	v_mul_f32_e32 v186, v213, v115
	v_mul_f32_e32 v187, v239, v115
	v_fma_f32 v190, v239, v119, -v186
	v_fma_f32 v191, v213, v119, v187
	v_cvt_pk_bf16_f32 v192, v188, v189
	v_cvt_pk_bf16_f32 v193, v190, v191
	ds_write_b16 v170, v192 offset:144
	ds_write_b16_d16_hi v170, v192 offset:176
	ds_write_b16 v170, v193 offset:208
	ds_write_b16_d16_hi v170, v193 offset:240
	v_mul_f32_e32 v186, v175, v124
	v_mul_f32_e32 v187, v176, v124
	v_fma_f32 v188, v176, v128, -v186
	v_fma_f32 v189, v175, v128, v187
	v_mul_f32_e32 v186, v214, v116
; template <int EPI>
; DI void gemm_phase(const P& p, int l, const u16* __restrict__ A, const u16* __restrict__ Bt, int mpx, char* lds) {
;     ...
;             if (dorope) {
;               float sr, cr, sc, cc;
;               sincos_rev((float)(s >> 6) * invf64, sr, cr);
;               sincos_rev((float)(s & 63) * invf64, sc, cc);
;               const float a1 = v0, a2 = v1, b1 = v2, b2 = v3;
;               v0 = a1 * cr - a2 * sr;
;               v1 = a2 * cr + a1 * sr;
;               v2 = b1 * cc - b2 * sc;
;               v3 = b2 * cc + b1 * sc;
;             }
;     ...
;             Tl[rowl * 72 + 0 * 16 + r] = (u16)u01;
;             Tl[rowl * 72 + 1 * 16 + r] = (u16)(u01 >> 16);
;             Tl[rowl * 72 + 2 * 16 + r] = (u16)u23;
;             Tl[rowl * 72 + 3 * 16 + r] = (u16)(u23 >> 16);
	v_mul_f32_e32 v187, v240, v116
	v_fma_f32 v190, v240, v120, -v186
	v_fma_f32 v191, v214, v120, v187
	v_cvt_pk_bf16_f32 v192, v188, v189
	v_cvt_pk_bf16_f32 v193, v190, v191
	ds_write_b16 v170, v192 offset:288
	ds_write_b16_d16_hi v170, v192 offset:320
	ds_write_b16 v170, v193 offset:352
	ds_write_b16_d16_hi v170, v193 offset:384
	v_mul_f32_e32 v186, v175, v125
	v_mul_f32_e32 v187, v176, v125
	v_fma_f32 v188, v176, v129, -v186
	v_fma_f32 v189, v175, v129, v187
	v_mul_f32_e32 v186, v215, v117
	v_mul_f32_e32 v187, v241, v117
	v_fma_f32 v190, v241, v121, -v186
	v_fma_f32 v191, v215, v121, v187
	v_cvt_pk_bf16_f32 v192, v188, v189
	v_cvt_pk_bf16_f32 v193, v190, v191
	ds_write_b16 v170, v192 offset:432
	ds_write_b16_d16_hi v170, v192 offset:464
	ds_write_b16 v170, v193 offset:496
	ds_write_b16_d16_hi v170, v193 offset:528
	v_mul_f32_e32 v186, v175, v106
	v_mul_f32_e32 v187, v176, v106
	v_fma_f32 v188, v176, v110, -v186
	v_fma_f32 v189, v175, v110, v187
	v_mul_f32_e32 v186, v216, v98
	v_mul_f32_e32 v187, v242, v98
	v_fma_f32 v190, v242, v102, -v186
	v_fma_f32 v191, v216, v102, v187
	v_cvt_pk_bf16_f32 v192, v188, v189
	v_cvt_pk_bf16_f32 v193, v190, v191
	ds_write_b16 v170, v192 offset:2304
	ds_write_b16_d16_hi v170, v192 offset:2336
	ds_write_b16 v170, v193 offset:2368
	ds_write_b16_d16_hi v170, v193 offset:2400
	v_mul_f32_e32 v186, v175, v107
	v_mul_f32_e32 v187, v176, v107
	v_fma_f32 v188, v176, v111, -v186
	v_fma_f32 v189, v175, v111, v187
	v_mul_f32_e32 v186, v217, v99
	v_mul_f32_e32 v187, v243, v99
	v_fma_f32 v190, v243, v103, -v186
	v_fma_f32 v191, v217, v103, v187
	v_cvt_pk_bf16_f32 v192, v188, v189
	v_cvt_pk_bf16_f32 v193, v190, v191
	ds_write_b16 v170, v192 offset:2448
	ds_write_b16_d16_hi v170, v192 offset:2480
	ds_write_b16 v170, v193 offset:2512
	ds_write_b16_d16_hi v170, v193 offset:2544
	v_mul_f32_e32 v186, v175, v108
	v_mul_f32_e32 v187, v176, v108
	v_fma_f32 v188, v176, v112, -v186
	v_fma_f32 v189, v175, v112, v187
	v_mul_f32_e32 v186, v218, v100
	v_mul_f32_e32 v187, v244, v100
	v_fma_f32 v190, v244, v104, -v186
	v_fma_f32 v191, v218, v104, v187
	v_cvt_pk_bf16_f32 v192, v188, v189
	v_cvt_pk_bf16_f32 v193, v190, v191
	ds_write_b16 v170, v192 offset:2592
	ds_write_b16_d16_hi v170, v192 offset:2624
	ds_write_b16 v170, v193 offset:2656
	ds_write_b16_d16_hi v170, v193 offset:2688
	v_mul_f32_e32 v186, v175, v109
	v_mul_f32_e32 v187, v176, v109
	v_fma_f32 v188, v176, v113, -v186
	v_fma_f32 v189, v175, v113, v187
	v_mul_f32_e32 v186, v219, v101
	v_mul_f32_e32 v187, v245, v101
	v_fma_f32 v190, v245, v105, -v186
	v_fma_f32 v191, v219, v105, v187
	v_cvt_pk_bf16_f32 v192, v188, v189
	v_cvt_pk_bf16_f32 v193, v190, v191
	ds_write_b16 v170, v192 offset:2736
	ds_write_b16_d16_hi v170, v192 offset:2768
	ds_write_b16 v170, v193 offset:2800
	ds_write_b16_d16_hi v170, v193 offset:2832
	v_mul_f32_e32 v186, v175, v90
	v_mul_f32_e32 v187, v176, v90
	v_fma_f32 v188, v176, v94, -v186
	v_fma_f32 v189, v175, v94, v187
	v_mul_f32_e32 v186, v220, v82
	v_mul_f32_e32 v187, v246, v82
	v_fma_f32 v190, v246, v86, -v186
	v_fma_f32 v191, v220, v86, v187
	v_cvt_pk_bf16_f32 v192, v188, v189
	v_cvt_pk_bf16_f32 v193, v190, v191
	ds_write_b16 v170, v192 offset:4608
	ds_write_b16_d16_hi v170, v192 offset:4640
	ds_write_b16 v170, v193 offset:4672
	ds_write_b16_d16_hi v170, v193 offset:4704
	v_mul_f32_e32 v186, v175, v91
	v_mul_f32_e32 v187, v176, v91
	v_fma_f32 v188, v176, v95, -v186
	v_fma_f32 v189, v175, v95, v187
	v_mul_f32_e32 v186, v221, v83
	v_mul_f32_e32 v187, v247, v83
	v_fma_f32 v190, v247, v87, -v186
	v_fma_f32 v191, v221, v87, v187
	v_cvt_pk_bf16_f32 v192, v188, v189
	v_cvt_pk_bf16_f32 v193, v190, v191
	ds_write_b16 v170, v192 offset:4752
	ds_write_b16_d16_hi v170, v192 offset:4784
	ds_write_b16 v170, v193 offset:4816
	ds_write_b16_d16_hi v170, v193 offset:4848
	v_mul_f32_e32 v186, v175, v92
	v_mul_f32_e32 v187, v176, v92
	v_fma_f32 v188, v176, v96, -v186
	v_fma_f32 v189, v175, v96, v187
	v_mul_f32_e32 v186, v222, v84
	v_mul_f32_e32 v187, v248, v84
	v_fma_f32 v190, v248, v88, -v186
	v_fma_f32 v191, v222, v88, v187
	v_cvt_pk_bf16_f32 v192, v188, v189
	v_cvt_pk_bf16_f32 v193, v190, v191
	ds_write_b16 v170, v192 offset:4896
	ds_write_b16_d16_hi v170, v192 offset:4928
	ds_write_b16 v170, v193 offset:4960
	ds_write_b16_d16_hi v170, v193 offset:4992
	v_mul_f32_e32 v186, v175, v93
	v_mul_f32_e32 v187, v176, v93
	v_fma_f32 v188, v176, v97, -v186
	v_fma_f32 v189, v175, v97, v187
	v_mul_f32_e32 v186, v223, v85
	v_mul_f32_e32 v187, v249, v85
	v_fma_f32 v190, v249, v89, -v186
	v_fma_f32 v191, v223, v89, v187
	v_cvt_pk_bf16_f32 v192, v188, v189
	v_cvt_pk_bf16_f32 v193, v190, v191
	ds_write_b16 v170, v192 offset:5040
	ds_write_b16_d16_hi v170, v192 offset:5072
	ds_write_b16 v170, v193 offset:5104
	ds_write_b16_d16_hi v170, v193 offset:5136
	v_mul_f32_e32 v186, v175, v74
	v_mul_f32_e32 v187, v176, v74
	v_fma_f32 v188, v176, v78, -v186
	v_fma_f32 v189, v175, v78, v187
	v_mul_f32_e32 v186, v234, v66
	v_mul_f32_e32 v187, v250, v66
	v_fma_f32 v190, v250, v70, -v186
	v_fma_f32 v191, v234, v70, v187
	v_cvt_pk_bf16_f32 v192, v188, v189
	v_cvt_pk_bf16_f32 v193, v190, v191
	ds_write_b16 v170, v192 offset:6912
	ds_write_b16_d16_hi v170, v192 offset:6944
	ds_write_b16 v170, v193 offset:6976
	ds_write_b16_d16_hi v170, v193 offset:7008
	v_mul_f32_e32 v186, v175, v75
	v_mul_f32_e32 v187, v176, v75
	v_fma_f32 v188, v176, v79, -v186
	v_fma_f32 v189, v175, v79, v187
	v_mul_f32_e32 v186, v235, v67
	v_mul_f32_e32 v187, v251, v67
	v_fma_f32 v190, v251, v71, -v186
	v_fma_f32 v191, v235, v71, v187
	v_cvt_pk_bf16_f32 v192, v188, v189
	v_cvt_pk_bf16_f32 v193, v190, v191
	ds_write_b16 v170, v192 offset:7056
; template <int EPI>
; DI void gemm_phase(const P& p, int l, const u16* __restrict__ A, const u16* __restrict__ Bt, int mpx, char* lds) {
;     ...
;             if (dorope) {
;               float sr, cr, sc, cc;
;               sincos_rev((float)(s >> 6) * invf64, sr, cr);
;               sincos_rev((float)(s & 63) * invf64, sc, cc);
;               const float a1 = v0, a2 = v1, b1 = v2, b2 = v3;
;               v0 = a1 * cr - a2 * sr;
;               v1 = a2 * cr + a1 * sr;
;               v2 = b1 * cc - b2 * sc;
;               v3 = b2 * cc + b1 * sc;
;             }
;     ...
;       __builtin_amdgcn_fence(__ATOMIC_RELEASE, "wavefront");
;       u16* dh = (kind == 1) ? dst + hf * 64 : dst + (size_t)(hf * 64) * rstride;
; #pragma unroll
;       for (int i = 0; i < 8; ++i) {
;         const int c = lane + i * 64;
;         const int row = c >> 3, cc = c & 7;
;         uint4 v = *(const uint4*)&Tl[row * 72 + cc * 8];
;         *(uint4*)(dh + (size_t)row * rstride + cc * 8) = v;
;       }
	ds_write_b16_d16_hi v170, v192 offset:7088
	ds_write_b16 v170, v193 offset:7120
	ds_write_b16_d16_hi v170, v193 offset:7152
	v_mul_f32_e32 v186, v175, v76
	v_mul_f32_e32 v187, v176, v76
	v_fma_f32 v188, v176, v80, -v186
	v_fma_f32 v189, v175, v80, v187
	v_mul_f32_e32 v186, v236, v68
	v_mul_f32_e32 v187, v252, v68
	v_fma_f32 v190, v252, v72, -v186
	v_fma_f32 v191, v236, v72, v187
	v_cvt_pk_bf16_f32 v192, v188, v189
	v_cvt_pk_bf16_f32 v193, v190, v191
	ds_write_b16 v170, v192 offset:7200
	ds_write_b16_d16_hi v170, v192 offset:7232
	ds_write_b16 v170, v193 offset:7264
	ds_write_b16_d16_hi v170, v193 offset:7296
	v_mul_f32_e32 v186, v175, v77
	v_mul_f32_e32 v187, v176, v77
	v_fma_f32 v188, v176, v81, -v186
	v_fma_f32 v189, v175, v81, v187
	v_mul_f32_e32 v186, v237, v69
	v_mul_f32_e32 v187, v253, v69
	v_fma_f32 v190, v253, v73, -v186
	v_fma_f32 v191, v237, v73, v187
	v_cvt_pk_bf16_f32 v192, v188, v189
	v_cvt_pk_bf16_f32 v193, v190, v191
	ds_write_b16 v170, v192 offset:7344
	ds_write_b16_d16_hi v170, v192 offset:7376
	ds_write_b16 v170, v193 offset:7408
	ds_write_b16_d16_hi v170, v193 offset:7440
	ds_read_b128 v[130:133], v171 offset:0
	ds_read_b128 v[134:137], v171 offset:1152
	ds_read_b128 v[138:141], v171 offset:2304
	ds_read_b128 v[142:145], v171 offset:3456
	ds_read_b128 v[146:149], v171 offset:4608
	ds_read_b128 v[150:153], v171 offset:5760
	ds_read_b128 v[154:157], v171 offset:6912
	ds_read_b128 v[158:161], v171 offset:8064
	s_waitcnt lgkmcnt(7)
	global_store_dwordx4 v172, v[130:133], s[44:45] offset:0
	s_waitcnt lgkmcnt(6)
	global_store_dwordx4 v172, v[134:137], s[44:45] offset:1024
	s_waitcnt lgkmcnt(5)
	global_store_dwordx4 v172, v[138:141], s[44:45] offset:2048
	s_waitcnt lgkmcnt(4)
	global_store_dwordx4 v172, v[142:145], s[44:45] offset:3072
	s_waitcnt lgkmcnt(3)
	global_store_dwordx4 v172, v[146:149], s[62:63] offset:0
	s_waitcnt lgkmcnt(2)
	global_store_dwordx4 v172, v[150:153], s[62:63] offset:1024
	s_waitcnt lgkmcnt(1)
	global_store_dwordx4 v172, v[154:157], s[62:63] offset:2048
	s_waitcnt lgkmcnt(0)
	global_store_dwordx4 v172, v[158:161], s[62:63] offset:3072
	s_add_u32 s44, s44, 0x2000
	s_addc_u32 s45, s45, 0
	s_add_u32 s62, s62, 0x2000
	s_addc_u32 s63, s63, 0
	s_lshr_b32 s70, s69, 6
	s_add_i32 s70, s70, 1
	v_cvt_f32_i32_e32 v182, s70
	v_mul_f32_e32 v182, v174, v182
	v_mul_f32_e32 v183, 0.15915494, v182
	v_rndne_f32_e32 v183, v183
	v_fma_f32 v183, v182, 0.15915494, -v183
	v_sin_f32_e32 v175, v183
	v_cos_f32_e32 v176, v183
	v_mul_f32_e32 v186, v175, v58
	v_mul_f32_e32 v187, v176, v58
	v_fma_f32 v188, v176, v62, -v186
	v_fma_f32 v189, v175, v62, v187
	v_mul_f32_e32 v186, v212, v50
	v_mul_f32_e32 v187, v238, v50
	v_fma_f32 v190, v238, v54, -v186
	v_fma_f32 v191, v212, v54, v187
	v_cvt_pk_bf16_f32 v192, v188, v189
	v_cvt_pk_bf16_f32 v193, v190, v191
	ds_write_b16 v170, v192 offset:0
	ds_write_b16_d16_hi v170, v192 offset:32
	ds_write_b16 v170, v193 offset:64
	ds_write_b16_d16_hi v170, v193 offset:96
	v_mul_f32_e32 v186, v175, v59
	v_mul_f32_e32 v187, v176, v59
	v_fma_f32 v188, v176, v63, -v186
	v_fma_f32 v189, v175, v63, v187
	v_mul_f32_e32 v186, v213, v51
	v_mul_f32_e32 v187, v239, v51
	v_fma_f32 v190, v239, v55, -v186
	v_fma_f32 v191, v213, v55, v187
	v_cvt_pk_bf16_f32 v192, v188, v189
	v_cvt_pk_bf16_f32 v193, v190, v191
	ds_write_b16 v170, v192 offset:144
	ds_write_b16_d16_hi v170, v192 offset:176
	ds_write_b16 v170, v193 offset:208
	ds_write_b16_d16_hi v170, v193 offset:240
	v_mul_f32_e32 v186, v175, v60
	v_mul_f32_e32 v187, v176, v60
	v_fma_f32 v188, v176, v64, -v186
	v_fma_f32 v189, v175, v64, v187
	v_mul_f32_e32 v186, v214, v52
	v_mul_f32_e32 v187, v240, v52
	v_fma_f32 v190, v240, v56, -v186
	v_fma_f32 v191, v214, v56, v187
	v_cvt_pk_bf16_f32 v192, v188, v189
	v_cvt_pk_bf16_f32 v193, v190, v191
	ds_write_b16 v170, v192 offset:288
	ds_write_b16_d16_hi v170, v192 offset:320
	ds_write_b16 v170, v193 offset:352
	ds_write_b16_d16_hi v170, v193 offset:384
	v_mul_f32_e32 v186, v175, v61
	v_mul_f32_e32 v187, v176, v61
	v_fma_f32 v188, v176, v65, -v186
	v_fma_f32 v189, v175, v65, v187
	v_mul_f32_e32 v186, v215, v53
	v_mul_f32_e32 v187, v241, v53
	v_fma_f32 v190, v241, v57, -v186
	v_fma_f32 v191, v215, v57, v187
	v_cvt_pk_bf16_f32 v192, v188, v189
	v_cvt_pk_bf16_f32 v193, v190, v191
	ds_write_b16 v170, v192 offset:432
	ds_write_b16_d16_hi v170, v192 offset:464
	ds_write_b16 v170, v193 offset:496
	ds_write_b16_d16_hi v170, v193 offset:528
	v_mul_f32_e32 v186, v175, v42
	v_mul_f32_e32 v187, v176, v42
	v_fma_f32 v188, v176, v46, -v186
	v_fma_f32 v189, v175, v46, v187
	v_mul_f32_e32 v186, v216, v34
	v_mul_f32_e32 v187, v242, v34
	v_fma_f32 v190, v242, v38, -v186
	v_fma_f32 v191, v216, v38, v187
	v_cvt_pk_bf16_f32 v192, v188, v189
	v_cvt_pk_bf16_f32 v193, v190, v191
	ds_write_b16 v170, v192 offset:2304
	ds_write_b16_d16_hi v170, v192 offset:2336
	ds_write_b16 v170, v193 offset:2368
	ds_write_b16_d16_hi v170, v193 offset:2400
	v_mul_f32_e32 v186, v175, v43
	v_mul_f32_e32 v187, v176, v43
	v_fma_f32 v188, v176, v47, -v186
	v_fma_f32 v189, v175, v47, v187
	v_mul_f32_e32 v186, v217, v35
	v_mul_f32_e32 v187, v243, v35
	v_fma_f32 v190, v243, v39, -v186
	v_fma_f32 v191, v217, v39, v187
	v_cvt_pk_bf16_f32 v192, v188, v189
	v_cvt_pk_bf16_f32 v193, v190, v191
	ds_write_b16 v170, v192 offset:2448
	ds_write_b16_d16_hi v170, v192 offset:2480
	ds_write_b16 v170, v193 offset:2512
	ds_write_b16_d16_hi v170, v193 offset:2544
	v_mul_f32_e32 v186, v175, v44
	v_mul_f32_e32 v187, v176, v44
	v_fma_f32 v188, v176, v48, -v186
	v_fma_f32 v189, v175, v48, v187
	v_mul_f32_e32 v186, v218, v36
	v_mul_f32_e32 v187, v244, v36
	v_fma_f32 v190, v244, v40, -v186
; template <int EPI>
; DI void gemm_phase(const P& p, int l, const u16* __restrict__ A, const u16* __restrict__ Bt, int mpx, char* lds) {
;     ...
;             if (dorope) {
;               float sr, cr, sc, cc;
;               sincos_rev((float)(s >> 6) * invf64, sr, cr);
;               sincos_rev((float)(s & 63) * invf64, sc, cc);
;               const float a1 = v0, a2 = v1, b1 = v2, b2 = v3;
;               v0 = a1 * cr - a2 * sr;
;               v1 = a2 * cr + a1 * sr;
;               v2 = b1 * cc - b2 * sc;
;               v3 = b2 * cc + b1 * sc;
;             }
;     ...
;       __builtin_amdgcn_fence(__ATOMIC_RELEASE, "wavefront");
;       u16* dh = (kind == 1) ? dst + hf * 64 : dst + (size_t)(hf * 64) * rstride;
; #pragma unroll
;       for (int i = 0; i < 8; ++i) {
;         const int c = lane + i * 64;
;         const int row = c >> 3, cc = c & 7;
;         uint4 v = *(const uint4*)&Tl[row * 72 + cc * 8];
;         *(uint4*)(dh + (size_t)row * rstride + cc * 8) = v;
;       }
	v_fma_f32 v191, v218, v40, v187
	v_cvt_pk_bf16_f32 v192, v188, v189
	v_cvt_pk_bf16_f32 v193, v190, v191
	ds_write_b16 v170, v192 offset:2592
	ds_write_b16_d16_hi v170, v192 offset:2624
	ds_write_b16 v170, v193 offset:2656
	ds_write_b16_d16_hi v170, v193 offset:2688
	v_mul_f32_e32 v186, v175, v45
	v_mul_f32_e32 v187, v176, v45
	v_fma_f32 v188, v176, v49, -v186
	v_fma_f32 v189, v175, v49, v187
	v_mul_f32_e32 v186, v219, v37
	v_mul_f32_e32 v187, v245, v37
	v_fma_f32 v190, v245, v41, -v186
	v_fma_f32 v191, v219, v41, v187
	v_cvt_pk_bf16_f32 v192, v188, v189
	v_cvt_pk_bf16_f32 v193, v190, v191
	ds_write_b16 v170, v192 offset:2736
	ds_write_b16_d16_hi v170, v192 offset:2768
	ds_write_b16 v170, v193 offset:2800
	ds_write_b16_d16_hi v170, v193 offset:2832
	v_mul_f32_e32 v186, v175, v26
	v_mul_f32_e32 v187, v176, v26
	v_fma_f32 v188, v176, v30, -v186
	v_fma_f32 v189, v175, v30, v187
	v_mul_f32_e32 v186, v220, v18
	v_mul_f32_e32 v187, v246, v18
	v_fma_f32 v190, v246, v22, -v186
	v_fma_f32 v191, v220, v22, v187
	v_cvt_pk_bf16_f32 v192, v188, v189
	v_cvt_pk_bf16_f32 v193, v190, v191
	ds_write_b16 v170, v192 offset:4608
	ds_write_b16_d16_hi v170, v192 offset:4640
	ds_write_b16 v170, v193 offset:4672
	ds_write_b16_d16_hi v170, v193 offset:4704
	v_mul_f32_e32 v186, v175, v27
	v_mul_f32_e32 v187, v176, v27
	v_fma_f32 v188, v176, v31, -v186
	v_fma_f32 v189, v175, v31, v187
	v_mul_f32_e32 v186, v221, v19
	v_mul_f32_e32 v187, v247, v19
	v_fma_f32 v190, v247, v23, -v186
	v_fma_f32 v191, v221, v23, v187
	v_cvt_pk_bf16_f32 v192, v188, v189
	v_cvt_pk_bf16_f32 v193, v190, v191
	ds_write_b16 v170, v192 offset:4752
	ds_write_b16_d16_hi v170, v192 offset:4784
	ds_write_b16 v170, v193 offset:4816
	ds_write_b16_d16_hi v170, v193 offset:4848
	v_mul_f32_e32 v186, v175, v28
	v_mul_f32_e32 v187, v176, v28
	v_fma_f32 v188, v176, v32, -v186
	v_fma_f32 v189, v175, v32, v187
	v_mul_f32_e32 v186, v222, v20
	v_mul_f32_e32 v187, v248, v20
	v_fma_f32 v190, v248, v24, -v186
	v_fma_f32 v191, v222, v24, v187
	v_cvt_pk_bf16_f32 v192, v188, v189
	v_cvt_pk_bf16_f32 v193, v190, v191
	ds_write_b16 v170, v192 offset:4896
	ds_write_b16_d16_hi v170, v192 offset:4928
	ds_write_b16 v170, v193 offset:4960
	ds_write_b16_d16_hi v170, v193 offset:4992
	v_mul_f32_e32 v186, v175, v29
	v_mul_f32_e32 v187, v176, v29
	v_fma_f32 v188, v176, v33, -v186
	v_fma_f32 v189, v175, v33, v187
	v_mul_f32_e32 v186, v223, v21
	v_mul_f32_e32 v187, v249, v21
	v_fma_f32 v190, v249, v25, -v186
	v_fma_f32 v191, v223, v25, v187
	v_cvt_pk_bf16_f32 v192, v188, v189
	v_cvt_pk_bf16_f32 v193, v190, v191
	ds_write_b16 v170, v192 offset:5040
	ds_write_b16_d16_hi v170, v192 offset:5072
	ds_write_b16 v170, v193 offset:5104
	ds_write_b16_d16_hi v170, v193 offset:5136
	v_mul_f32_e32 v186, v175, v162
	v_mul_f32_e32 v187, v176, v162
	v_fma_f32 v188, v176, v166, -v186
	v_fma_f32 v189, v175, v166, v187
	v_mul_f32_e32 v186, v234, v6
	v_mul_f32_e32 v187, v250, v6
	v_fma_f32 v190, v250, v2, -v186
	v_fma_f32 v191, v234, v2, v187
	v_cvt_pk_bf16_f32 v192, v188, v189
	v_cvt_pk_bf16_f32 v193, v190, v191
	ds_write_b16 v170, v192 offset:6912
	ds_write_b16_d16_hi v170, v192 offset:6944
	ds_write_b16 v170, v193 offset:6976
	ds_write_b16_d16_hi v170, v193 offset:7008
	v_mul_f32_e32 v186, v175, v163
	v_mul_f32_e32 v187, v176, v163
	v_fma_f32 v188, v176, v167, -v186
	v_fma_f32 v189, v175, v167, v187
	v_mul_f32_e32 v186, v235, v7
	v_mul_f32_e32 v187, v251, v7
	v_fma_f32 v190, v251, v3, -v186
	v_fma_f32 v191, v235, v3, v187
	v_cvt_pk_bf16_f32 v192, v188, v189
	v_cvt_pk_bf16_f32 v193, v190, v191
	ds_write_b16 v170, v192 offset:7056
	ds_write_b16_d16_hi v170, v192 offset:7088
	ds_write_b16 v170, v193 offset:7120
	ds_write_b16_d16_hi v170, v193 offset:7152
	v_mul_f32_e32 v186, v175, v164
	v_mul_f32_e32 v187, v176, v164
	v_fma_f32 v188, v176, v168, -v186
	v_fma_f32 v189, v175, v168, v187
	v_mul_f32_e32 v186, v236, v8
	v_mul_f32_e32 v187, v252, v8
	v_fma_f32 v190, v252, v4, -v186
	v_fma_f32 v191, v236, v4, v187
	v_cvt_pk_bf16_f32 v192, v188, v189
	v_cvt_pk_bf16_f32 v193, v190, v191
	ds_write_b16 v170, v192 offset:7200
	ds_write_b16_d16_hi v170, v192 offset:7232
	ds_write_b16 v170, v193 offset:7264
	ds_write_b16_d16_hi v170, v193 offset:7296
	v_mul_f32_e32 v186, v175, v165
	v_mul_f32_e32 v187, v176, v165
	v_fma_f32 v188, v176, v169, -v186
	v_fma_f32 v189, v175, v169, v187
	v_mul_f32_e32 v186, v237, v9
	v_mul_f32_e32 v187, v253, v9
	v_fma_f32 v190, v253, v5, -v186
	v_fma_f32 v191, v237, v5, v187
	v_cvt_pk_bf16_f32 v192, v188, v189
	v_cvt_pk_bf16_f32 v193, v190, v191
	ds_write_b16 v170, v192 offset:7344
	ds_write_b16_d16_hi v170, v192 offset:7376
	ds_write_b16 v170, v193 offset:7408
	ds_write_b16_d16_hi v170, v193 offset:7440
	ds_read_b128 v[130:133], v171 offset:0
	ds_read_b128 v[134:137], v171 offset:1152
	ds_read_b128 v[138:141], v171 offset:2304
	ds_read_b128 v[142:145], v171 offset:3456
	ds_read_b128 v[146:149], v171 offset:4608
	ds_read_b128 v[150:153], v171 offset:5760
	ds_read_b128 v[154:157], v171 offset:6912
	ds_read_b128 v[158:161], v171 offset:8064
	s_waitcnt lgkmcnt(7)
	global_store_dwordx4 v172, v[130:133], s[44:45] offset:0
	s_waitcnt lgkmcnt(6)
	global_store_dwordx4 v172, v[134:137], s[44:45] offset:1024
	s_waitcnt lgkmcnt(5)
	global_store_dwordx4 v172, v[138:141], s[44:45] offset:2048
	s_waitcnt lgkmcnt(4)
	global_store_dwordx4 v172, v[142:145], s[44:45] offset:3072
	s_waitcnt lgkmcnt(3)
	global_store_dwordx4 v172, v[146:149], s[62:63] offset:0
	s_waitcnt lgkmcnt(2)
	global_store_dwordx4 v172, v[150:153], s[62:63] offset:1024
	s_waitcnt lgkmcnt(1)
	global_store_dwordx4 v172, v[154:157], s[62:63] offset:2048
	s_waitcnt lgkmcnt(0)
	global_store_dwordx4 v172, v[158:161], s[62:63] offset:3072
	s_branch .Lfe_done
; DI void sincos_rev(float ang, float& s, float& c) {
;   float rev = ang * 0.15915494309189535f;
;   rev -= rintf(rev);
;   s = __builtin_amdgcn_sinf(rev);
;   c = __builtin_amdgcn_cosf(rev);
; }
; template <int EPI>
; DI void gemm_phase(const P& p, int l, const u16* __restrict__ A, const u16* __restrict__ Bt, int mpx, char* lds) {
;     ...
;           } else if (tr == 4) {
;             float sr, cr, sc, cc;
;             sincos_rev((float)(s >> 6) * invf32, sr, cr);
;             sincos_rev((float)(s & 63) * invf32, sc, cc);
;             const float p0 = __shfl_xor(v0, 8), p1 = __shfl_xor(v1, 8), p2 = __shfl_xor(v2, 8), p3 = __shfl_xor(v3, 8);
;             v0 = lo8 ? (v0 * cr - p0 * sr) : (v0 * cr + p0 * sr);
;             v1 = lo8 ? (v1 * cc - p1 * sc) : (v1 * cc + p1 * sc);
;             v2 = lo8 ? (v2 * cr - p2 * sr) : (v2 * cr + p2 * sr);
;             v3 = lo8 ? (v3 * cc - p3 * sc) : (v3 * cc + p3 * sc);
;           }
.Lfe_k0_rope32:
	v_and_b32_e32 v0, 7, v226
	v_cvt_f32_ubyte0_e32 v0, v0
	v_mul_f32_e32 v0, 0xc1549a78, v0
	v_mul_f32_e32 v0, 0x3e000000, v0
	v_exp_f32_e32 v174, v0
	v_lshrrev_b32_e32 v0, 4, v226
	v_lshlrev_b32_e32 v0, 2, v0
	v_add_u32_e32 v182, 0, v0
	v_cvt_f32_i32_e32 v182, v182
	v_mul_f32_e32 v182, v174, v182
	v_mul_f32_e32 v183, 0.15915494, v182
	v_rndne_f32_e32 v183, v183
	v_fma_f32 v183, v182, 0.15915494, -v183
	v_sin_f32_e32 v212, v183
	v_cos_f32_e32 v238, v183
	v_add_u32_e32 v182, 1, v0
	v_cvt_f32_i32_e32 v182, v182
	v_mul_f32_e32 v182, v174, v182
	v_mul_f32_e32 v183, 0.15915494, v182
	v_rndne_f32_e32 v183, v183
	v_fma_f32 v183, v182, 0.15915494, -v183
	v_sin_f32_e32 v213, v183
	v_cos_f32_e32 v239, v183
	v_add_u32_e32 v182, 2, v0
	v_cvt_f32_i32_e32 v182, v182
	v_mul_f32_e32 v182, v174, v182
	v_mul_f32_e32 v183, 0.15915494, v182
	v_rndne_f32_e32 v183, v183
	v_fma_f32 v183, v182, 0.15915494, -v183
	v_sin_f32_e32 v214, v183
	v_cos_f32_e32 v240, v183
	v_add_u32_e32 v182, 3, v0
	v_cvt_f32_i32_e32 v182, v182
	v_mul_f32_e32 v182, v174, v182
	v_mul_f32_e32 v183, 0.15915494, v182
	v_rndne_f32_e32 v183, v183
	v_fma_f32 v183, v182, 0.15915494, -v183
	v_sin_f32_e32 v215, v183
	v_cos_f32_e32 v241, v183
	v_add_u32_e32 v182, 16, v0
	v_cvt_f32_i32_e32 v182, v182
	v_mul_f32_e32 v182, v174, v182
	v_mul_f32_e32 v183, 0.15915494, v182
	v_rndne_f32_e32 v183, v183
	v_fma_f32 v183, v182, 0.15915494, -v183
	v_sin_f32_e32 v216, v183
	v_cos_f32_e32 v242, v183
	v_add_u32_e32 v182, 17, v0
	v_cvt_f32_i32_e32 v182, v182
	v_mul_f32_e32 v182, v174, v182
	v_mul_f32_e32 v183, 0.15915494, v182
	v_rndne_f32_e32 v183, v183
	v_fma_f32 v183, v182, 0.15915494, -v183
	v_sin_f32_e32 v217, v183
	v_cos_f32_e32 v243, v183
	v_add_u32_e32 v182, 18, v0
	v_cvt_f32_i32_e32 v182, v182
	v_mul_f32_e32 v182, v174, v182
	v_mul_f32_e32 v183, 0.15915494, v182
	v_rndne_f32_e32 v183, v183
	v_fma_f32 v183, v182, 0.15915494, -v183
	v_sin_f32_e32 v218, v183
	v_cos_f32_e32 v244, v183
	v_add_u32_e32 v182, 19, v0
	v_cvt_f32_i32_e32 v182, v182
	v_mul_f32_e32 v182, v174, v182
	v_mul_f32_e32 v183, 0.15915494, v182
	v_rndne_f32_e32 v183, v183
	v_fma_f32 v183, v182, 0.15915494, -v183
	v_sin_f32_e32 v219, v183
	v_cos_f32_e32 v245, v183
	v_add_u32_e32 v182, 32, v0
	v_cvt_f32_i32_e32 v182, v182
	v_mul_f32_e32 v182, v174, v182
	v_mul_f32_e32 v183, 0.15915494, v182
	v_rndne_f32_e32 v183, v183
	v_fma_f32 v183, v182, 0.15915494, -v183
	v_sin_f32_e32 v220, v183
	v_cos_f32_e32 v246, v183
	v_add_u32_e32 v182, 33, v0
	v_cvt_f32_i32_e32 v182, v182
	v_mul_f32_e32 v182, v174, v182
	v_mul_f32_e32 v183, 0.15915494, v182
	v_rndne_f32_e32 v183, v183
	v_fma_f32 v183, v182, 0.15915494, -v183
	v_sin_f32_e32 v221, v183
	v_cos_f32_e32 v247, v183
	v_add_u32_e32 v182, 34, v0
	v_cvt_f32_i32_e32 v182, v182
	v_mul_f32_e32 v182, v174, v182
	v_mul_f32_e32 v183, 0.15915494, v182
	v_rndne_f32_e32 v183, v183
	v_fma_f32 v183, v182, 0.15915494, -v183
	v_sin_f32_e32 v222, v183
	v_cos_f32_e32 v248, v183
	v_add_u32_e32 v182, 35, v0
	v_cvt_f32_i32_e32 v182, v182
	v_mul_f32_e32 v182, v174, v182
	v_mul_f32_e32 v183, 0.15915494, v182
	v_rndne_f32_e32 v183, v183
	v_fma_f32 v183, v182, 0.15915494, -v183
	v_sin_f32_e32 v223, v183
	v_cos_f32_e32 v249, v183
	v_add_u32_e32 v182, 48, v0
	v_cvt_f32_i32_e32 v182, v182
	v_mul_f32_e32 v182, v174, v182
	v_mul_f32_e32 v183, 0.15915494, v182
	v_rndne_f32_e32 v183, v183
	v_fma_f32 v183, v182, 0.15915494, -v183
	v_sin_f32_e32 v234, v183
	v_cos_f32_e32 v250, v183
	v_add_u32_e32 v182, 49, v0
	v_cvt_f32_i32_e32 v182, v182
	v_mul_f32_e32 v182, v174, v182
	v_mul_f32_e32 v183, 0.15915494, v182
	v_rndne_f32_e32 v183, v183
	v_fma_f32 v183, v182, 0.15915494, -v183
	v_sin_f32_e32 v235, v183
	v_cos_f32_e32 v251, v183
	v_add_u32_e32 v182, 50, v0
	v_cvt_f32_i32_e32 v182, v182
	v_mul_f32_e32 v182, v174, v182
	v_mul_f32_e32 v183, 0.15915494, v182
	v_rndne_f32_e32 v183, v183
	v_fma_f32 v183, v182, 0.15915494, -v183
	v_sin_f32_e32 v236, v183
	v_cos_f32_e32 v252, v183
	v_add_u32_e32 v182, 51, v0
	v_cvt_f32_i32_e32 v182, v182
	v_mul_f32_e32 v182, v174, v182
	v_mul_f32_e32 v183, 0.15915494, v182
	v_rndne_f32_e32 v183, v183
	v_fma_f32 v183, v182, 0.15915494, -v183
	v_sin_f32_e32 v237, v183
	v_cos_f32_e32 v253, v183
	v_and_b32_e32 v0, 8, v226
	v_cmp_eq_u32_e32 vcc, 0, v0
	s_nop 1
	v_cndmask_b32_e64 v212, v212, -v212, vcc
	v_cndmask_b32_e64 v213, v213, -v213, vcc
	v_cndmask_b32_e64 v214, v214, -v214, vcc
	v_cndmask_b32_e64 v215, v215, -v215, vcc
	v_cndmask_b32_e64 v216, v216, -v216, vcc
	v_cndmask_b32_e64 v217, v217, -v217, vcc
	v_cndmask_b32_e64 v218, v218, -v218, vcc
	v_cndmask_b32_e64 v219, v219, -v219, vcc
	v_cndmask_b32_e64 v220, v220, -v220, vcc
	v_cndmask_b32_e64 v221, v221, -v221, vcc
	v_cndmask_b32_e64 v222, v222, -v222, vcc
	v_cndmask_b32_e64 v223, v223, -v223, vcc
	v_cndmask_b32_e64 v234, v234, -v234, vcc
	v_cndmask_b32_e64 v235, v235, -v235, vcc
	v_cndmask_b32_e64 v236, v236, -v236, vcc
	v_cndmask_b32_e64 v237, v237, -v237, vcc
	s_add_u32 s62, s44, 0x1000
	s_addc_u32 s63, s45, 0
	s_lshr_b32 s70, s69, 6
	v_cvt_f32_i32_e32 v182, s70
	v_mul_f32_e32 v182, v174, v182
	v_mul_f32_e32 v183, 0.15915494, v182
	v_rndne_f32_e32 v183, v183
	v_fma_f32 v183, v182, 0.15915494, -v183
	v_sin_f32_e32 v175, v183
	v_cos_f32_e32 v176, v183
	s_nop 0
	v_cndmask_b32_e64 v177, v175, -v175, vcc
	v_mul_f32_dpp v182, v126, v177 row_ror:8 row_mask:0xf bank_mask:0xf
	v_mul_f32_dpp v183, v122, v212 row_ror:8 row_mask:0xf bank_mask:0xf
	v_mul_f32_dpp v184, v118, v177 row_ror:8 row_mask:0xf bank_mask:0xf
	v_mul_f32_dpp v185, v114, v212 row_ror:8 row_mask:0xf bank_mask:0xf
	v_fma_f32 v186, v126, v176, v182
	v_fma_f32 v187, v122, v238, v183
; template <int EPI>
; DI void gemm_phase(const P& p, int l, const u16* __restrict__ A, const u16* __restrict__ Bt, int mpx, char* lds) {
;     ...
;           } else if (tr == 4) {
;             float sr, cr, sc, cc;
;             sincos_rev((float)(s >> 6) * invf32, sr, cr);
;             sincos_rev((float)(s & 63) * invf32, sc, cc);
;             const float p0 = __shfl_xor(v0, 8), p1 = __shfl_xor(v1, 8), p2 = __shfl_xor(v2, 8), p3 = __shfl_xor(v3, 8);
;             v0 = lo8 ? (v0 * cr - p0 * sr) : (v0 * cr + p0 * sr);
;             v1 = lo8 ? (v1 * cc - p1 * sc) : (v1 * cc + p1 * sc);
;             v2 = lo8 ? (v2 * cr - p2 * sr) : (v2 * cr + p2 * sr);
;             v3 = lo8 ? (v3 * cc - p3 * sc) : (v3 * cc + p3 * sc);
;           }
;     ...
;             Tl[rowl * 72 + 0 * 16 + r] = (u16)u01;
;             Tl[rowl * 72 + 1 * 16 + r] = (u16)(u01 >> 16);
;             Tl[rowl * 72 + 2 * 16 + r] = (u16)u23;
;             Tl[rowl * 72 + 3 * 16 + r] = (u16)(u23 >> 16);
	v_fma_f32 v188, v118, v176, v184
	v_fma_f32 v189, v114, v238, v185
	v_cvt_pk_bf16_f32 v192, v186, v187
	v_cvt_pk_bf16_f32 v193, v188, v189
	ds_write_b16 v170, v192 offset:0
	ds_write_b16_d16_hi v170, v192 offset:32
	ds_write_b16 v170, v193 offset:64
	ds_write_b16_d16_hi v170, v193 offset:96
	v_mul_f32_dpp v182, v127, v177 row_ror:8 row_mask:0xf bank_mask:0xf
	v_mul_f32_dpp v183, v123, v213 row_ror:8 row_mask:0xf bank_mask:0xf
	v_mul_f32_dpp v184, v119, v177 row_ror:8 row_mask:0xf bank_mask:0xf
	v_mul_f32_dpp v185, v115, v213 row_ror:8 row_mask:0xf bank_mask:0xf
	v_fma_f32 v186, v127, v176, v182
	v_fma_f32 v187, v123, v239, v183
	v_fma_f32 v188, v119, v176, v184
	v_fma_f32 v189, v115, v239, v185
	v_cvt_pk_bf16_f32 v192, v186, v187
	v_cvt_pk_bf16_f32 v193, v188, v189
	ds_write_b16 v170, v192 offset:144
	ds_write_b16_d16_hi v170, v192 offset:176
	ds_write_b16 v170, v193 offset:208
	ds_write_b16_d16_hi v170, v193 offset:240
	v_mul_f32_dpp v182, v128, v177 row_ror:8 row_mask:0xf bank_mask:0xf
	v_mul_f32_dpp v183, v124, v214 row_ror:8 row_mask:0xf bank_mask:0xf
	v_mul_f32_dpp v184, v120, v177 row_ror:8 row_mask:0xf bank_mask:0xf
	v_mul_f32_dpp v185, v116, v214 row_ror:8 row_mask:0xf bank_mask:0xf
	v_fma_f32 v186, v128, v176, v182
	v_fma_f32 v187, v124, v240, v183
	v_fma_f32 v188, v120, v176, v184
	v_fma_f32 v189, v116, v240, v185
	v_cvt_pk_bf16_f32 v192, v186, v187
	v_cvt_pk_bf16_f32 v193, v188, v189
	ds_write_b16 v170, v192 offset:288
	ds_write_b16_d16_hi v170, v192 offset:320
	ds_write_b16 v170, v193 offset:352
	ds_write_b16_d16_hi v170, v193 offset:384
	v_mul_f32_dpp v182, v129, v177 row_ror:8 row_mask:0xf bank_mask:0xf
	v_mul_f32_dpp v183, v125, v215 row_ror:8 row_mask:0xf bank_mask:0xf
	v_mul_f32_dpp v184, v121, v177 row_ror:8 row_mask:0xf bank_mask:0xf
	v_mul_f32_dpp v185, v117, v215 row_ror:8 row_mask:0xf bank_mask:0xf
	v_fma_f32 v186, v129, v176, v182
	v_fma_f32 v187, v125, v241, v183
	v_fma_f32 v188, v121, v176, v184
	v_fma_f32 v189, v117, v241, v185
	v_cvt_pk_bf16_f32 v192, v186, v187
	v_cvt_pk_bf16_f32 v193, v188, v189
	ds_write_b16 v170, v192 offset:432
	ds_write_b16_d16_hi v170, v192 offset:464
	ds_write_b16 v170, v193 offset:496
	ds_write_b16_d16_hi v170, v193 offset:528
	v_mul_f32_dpp v182, v110, v177 row_ror:8 row_mask:0xf bank_mask:0xf
	v_mul_f32_dpp v183, v106, v216 row_ror:8 row_mask:0xf bank_mask:0xf
	v_mul_f32_dpp v184, v102, v177 row_ror:8 row_mask:0xf bank_mask:0xf
	v_mul_f32_dpp v185, v98, v216 row_ror:8 row_mask:0xf bank_mask:0xf
	v_fma_f32 v186, v110, v176, v182
	v_fma_f32 v187, v106, v242, v183
	v_fma_f32 v188, v102, v176, v184
	v_fma_f32 v189, v98, v242, v185
	v_cvt_pk_bf16_f32 v192, v186, v187
	v_cvt_pk_bf16_f32 v193, v188, v189
	ds_write_b16 v170, v192 offset:2304
	ds_write_b16_d16_hi v170, v192 offset:2336
	ds_write_b16 v170, v193 offset:2368
	ds_write_b16_d16_hi v170, v193 offset:2400
	v_mul_f32_dpp v182, v111, v177 row_ror:8 row_mask:0xf bank_mask:0xf
	v_mul_f32_dpp v183, v107, v217 row_ror:8 row_mask:0xf bank_mask:0xf
	v_mul_f32_dpp v184, v103, v177 row_ror:8 row_mask:0xf bank_mask:0xf
	v_mul_f32_dpp v185, v99, v217 row_ror:8 row_mask:0xf bank_mask:0xf
	v_fma_f32 v186, v111, v176, v182
	v_fma_f32 v187, v107, v243, v183
	v_fma_f32 v188, v103, v176, v184
	v_fma_f32 v189, v99, v243, v185
	v_cvt_pk_bf16_f32 v192, v186, v187
	v_cvt_pk_bf16_f32 v193, v188, v189
	ds_write_b16 v170, v192 offset:2448
	ds_write_b16_d16_hi v170, v192 offset:2480
	ds_write_b16 v170, v193 offset:2512
	ds_write_b16_d16_hi v170, v193 offset:2544
	v_mul_f32_dpp v182, v112, v177 row_ror:8 row_mask:0xf bank_mask:0xf
	v_mul_f32_dpp v183, v108, v218 row_ror:8 row_mask:0xf bank_mask:0xf
	v_mul_f32_dpp v184, v104, v177 row_ror:8 row_mask:0xf bank_mask:0xf
	v_mul_f32_dpp v185, v100, v218 row_ror:8 row_mask:0xf bank_mask:0xf
	v_fma_f32 v186, v112, v176, v182
	v_fma_f32 v187, v108, v244, v183
	v_fma_f32 v188, v104, v176, v184
	v_fma_f32 v189, v100, v244, v185
	v_cvt_pk_bf16_f32 v192, v186, v187
	v_cvt_pk_bf16_f32 v193, v188, v189
	ds_write_b16 v170, v192 offset:2592
	ds_write_b16_d16_hi v170, v192 offset:2624
	ds_write_b16 v170, v193 offset:2656
	ds_write_b16_d16_hi v170, v193 offset:2688
	v_mul_f32_dpp v182, v113, v177 row_ror:8 row_mask:0xf bank_mask:0xf
	v_mul_f32_dpp v183, v109, v219 row_ror:8 row_mask:0xf bank_mask:0xf
	v_mul_f32_dpp v184, v105, v177 row_ror:8 row_mask:0xf bank_mask:0xf
	v_mul_f32_dpp v185, v101, v219 row_ror:8 row_mask:0xf bank_mask:0xf
	v_fma_f32 v186, v113, v176, v182
	v_fma_f32 v187, v109, v245, v183
	v_fma_f32 v188, v105, v176, v184
	v_fma_f32 v189, v101, v245, v185
	v_cvt_pk_bf16_f32 v192, v186, v187
	v_cvt_pk_bf16_f32 v193, v188, v189
	ds_write_b16 v170, v192 offset:2736
	ds_write_b16_d16_hi v170, v192 offset:2768
	ds_write_b16 v170, v193 offset:2800
	ds_write_b16_d16_hi v170, v193 offset:2832
	v_mul_f32_dpp v182, v94, v177 row_ror:8 row_mask:0xf bank_mask:0xf
	v_mul_f32_dpp v183, v90, v220 row_ror:8 row_mask:0xf bank_mask:0xf
	v_mul_f32_dpp v184, v86, v177 row_ror:8 row_mask:0xf bank_mask:0xf
	v_mul_f32_dpp v185, v82, v220 row_ror:8 row_mask:0xf bank_mask:0xf
	v_fma_f32 v186, v94, v176, v182
	v_fma_f32 v187, v90, v246, v183
	v_fma_f32 v188, v86, v176, v184
	v_fma_f32 v189, v82, v246, v185
	v_cvt_pk_bf16_f32 v192, v186, v187
	v_cvt_pk_bf16_f32 v193, v188, v189
	ds_write_b16 v170, v192 offset:4608
	ds_write_b16_d16_hi v170, v192 offset:4640
	ds_write_b16 v170, v193 offset:4672
	ds_write_b16_d16_hi v170, v193 offset:4704
	v_mul_f32_dpp v182, v95, v177 row_ror:8 row_mask:0xf bank_mask:0xf
	v_mul_f32_dpp v183, v91, v221 row_ror:8 row_mask:0xf bank_mask:0xf
	v_mul_f32_dpp v184, v87, v177 row_ror:8 row_mask:0xf bank_mask:0xf
; template <int EPI>
; DI void gemm_phase(const P& p, int l, const u16* __restrict__ A, const u16* __restrict__ Bt, int mpx, char* lds) {
;     ...
;           } else if (tr == 4) {
;             float sr, cr, sc, cc;
;             sincos_rev((float)(s >> 6) * invf32, sr, cr);
;             sincos_rev((float)(s & 63) * invf32, sc, cc);
;             const float p0 = __shfl_xor(v0, 8), p1 = __shfl_xor(v1, 8), p2 = __shfl_xor(v2, 8), p3 = __shfl_xor(v3, 8);
;             v0 = lo8 ? (v0 * cr - p0 * sr) : (v0 * cr + p0 * sr);
;             v1 = lo8 ? (v1 * cc - p1 * sc) : (v1 * cc + p1 * sc);
;             v2 = lo8 ? (v2 * cr - p2 * sr) : (v2 * cr + p2 * sr);
;             v3 = lo8 ? (v3 * cc - p3 * sc) : (v3 * cc + p3 * sc);
;           }
;     ...
;       __builtin_amdgcn_fence(__ATOMIC_RELEASE, "wavefront");
;       u16* dh = (kind == 1) ? dst + hf * 64 : dst + (size_t)(hf * 64) * rstride;
; #pragma unroll
;       for (int i = 0; i < 8; ++i) {
;         const int c = lane + i * 64;
;         const int row = c >> 3, cc = c & 7;
;         uint4 v = *(const uint4*)&Tl[row * 72 + cc * 8];
;         *(uint4*)(dh + (size_t)row * rstride + cc * 8) = v;
;       }
	v_mul_f32_dpp v185, v83, v221 row_ror:8 row_mask:0xf bank_mask:0xf
	v_fma_f32 v186, v95, v176, v182
	v_fma_f32 v187, v91, v247, v183
	v_fma_f32 v188, v87, v176, v184
	v_fma_f32 v189, v83, v247, v185
	v_cvt_pk_bf16_f32 v192, v186, v187
	v_cvt_pk_bf16_f32 v193, v188, v189
	ds_write_b16 v170, v192 offset:4752
	ds_write_b16_d16_hi v170, v192 offset:4784
	ds_write_b16 v170, v193 offset:4816
	ds_write_b16_d16_hi v170, v193 offset:4848
	v_mul_f32_dpp v182, v96, v177 row_ror:8 row_mask:0xf bank_mask:0xf
	v_mul_f32_dpp v183, v92, v222 row_ror:8 row_mask:0xf bank_mask:0xf
	v_mul_f32_dpp v184, v88, v177 row_ror:8 row_mask:0xf bank_mask:0xf
	v_mul_f32_dpp v185, v84, v222 row_ror:8 row_mask:0xf bank_mask:0xf
	v_fma_f32 v186, v96, v176, v182
	v_fma_f32 v187, v92, v248, v183
	v_fma_f32 v188, v88, v176, v184
	v_fma_f32 v189, v84, v248, v185
	v_cvt_pk_bf16_f32 v192, v186, v187
	v_cvt_pk_bf16_f32 v193, v188, v189
	ds_write_b16 v170, v192 offset:4896
	ds_write_b16_d16_hi v170, v192 offset:4928
	ds_write_b16 v170, v193 offset:4960
	ds_write_b16_d16_hi v170, v193 offset:4992
	v_mul_f32_dpp v182, v97, v177 row_ror:8 row_mask:0xf bank_mask:0xf
	v_mul_f32_dpp v183, v93, v223 row_ror:8 row_mask:0xf bank_mask:0xf
	v_mul_f32_dpp v184, v89, v177 row_ror:8 row_mask:0xf bank_mask:0xf
	v_mul_f32_dpp v185, v85, v223 row_ror:8 row_mask:0xf bank_mask:0xf
	v_fma_f32 v186, v97, v176, v182
	v_fma_f32 v187, v93, v249, v183
	v_fma_f32 v188, v89, v176, v184
	v_fma_f32 v189, v85, v249, v185
	v_cvt_pk_bf16_f32 v192, v186, v187
	v_cvt_pk_bf16_f32 v193, v188, v189
	ds_write_b16 v170, v192 offset:5040
	ds_write_b16_d16_hi v170, v192 offset:5072
	ds_write_b16 v170, v193 offset:5104
	ds_write_b16_d16_hi v170, v193 offset:5136
	v_mul_f32_dpp v182, v78, v177 row_ror:8 row_mask:0xf bank_mask:0xf
	v_mul_f32_dpp v183, v74, v234 row_ror:8 row_mask:0xf bank_mask:0xf
	v_mul_f32_dpp v184, v70, v177 row_ror:8 row_mask:0xf bank_mask:0xf
	v_mul_f32_dpp v185, v66, v234 row_ror:8 row_mask:0xf bank_mask:0xf
	v_fma_f32 v186, v78, v176, v182
	v_fma_f32 v187, v74, v250, v183
	v_fma_f32 v188, v70, v176, v184
	v_fma_f32 v189, v66, v250, v185
	v_cvt_pk_bf16_f32 v192, v186, v187
	v_cvt_pk_bf16_f32 v193, v188, v189
	ds_write_b16 v170, v192 offset:6912
	ds_write_b16_d16_hi v170, v192 offset:6944
	ds_write_b16 v170, v193 offset:6976
	ds_write_b16_d16_hi v170, v193 offset:7008
	v_mul_f32_dpp v182, v79, v177 row_ror:8 row_mask:0xf bank_mask:0xf
	v_mul_f32_dpp v183, v75, v235 row_ror:8 row_mask:0xf bank_mask:0xf
	v_mul_f32_dpp v184, v71, v177 row_ror:8 row_mask:0xf bank_mask:0xf
	v_mul_f32_dpp v185, v67, v235 row_ror:8 row_mask:0xf bank_mask:0xf
	v_fma_f32 v186, v79, v176, v182
	v_fma_f32 v187, v75, v251, v183
	v_fma_f32 v188, v71, v176, v184
	v_fma_f32 v189, v67, v251, v185
	v_cvt_pk_bf16_f32 v192, v186, v187
	v_cvt_pk_bf16_f32 v193, v188, v189
	ds_write_b16 v170, v192 offset:7056
	ds_write_b16_d16_hi v170, v192 offset:7088
	ds_write_b16 v170, v193 offset:7120
	ds_write_b16_d16_hi v170, v193 offset:7152
	v_mul_f32_dpp v182, v80, v177 row_ror:8 row_mask:0xf bank_mask:0xf
	v_mul_f32_dpp v183, v76, v236 row_ror:8 row_mask:0xf bank_mask:0xf
	v_mul_f32_dpp v184, v72, v177 row_ror:8 row_mask:0xf bank_mask:0xf
	v_mul_f32_dpp v185, v68, v236 row_ror:8 row_mask:0xf bank_mask:0xf
	v_fma_f32 v186, v80, v176, v182
	v_fma_f32 v187, v76, v252, v183
	v_fma_f32 v188, v72, v176, v184
	v_fma_f32 v189, v68, v252, v185
	v_cvt_pk_bf16_f32 v192, v186, v187
	v_cvt_pk_bf16_f32 v193, v188, v189
	ds_write_b16 v170, v192 offset:7200
	ds_write_b16_d16_hi v170, v192 offset:7232
	ds_write_b16 v170, v193 offset:7264
	ds_write_b16_d16_hi v170, v193 offset:7296
	v_mul_f32_dpp v182, v81, v177 row_ror:8 row_mask:0xf bank_mask:0xf
	v_mul_f32_dpp v183, v77, v237 row_ror:8 row_mask:0xf bank_mask:0xf
	v_mul_f32_dpp v184, v73, v177 row_ror:8 row_mask:0xf bank_mask:0xf
	v_mul_f32_dpp v185, v69, v237 row_ror:8 row_mask:0xf bank_mask:0xf
	v_fma_f32 v186, v81, v176, v182
	v_fma_f32 v187, v77, v253, v183
	v_fma_f32 v188, v73, v176, v184
	v_fma_f32 v189, v69, v253, v185
	v_cvt_pk_bf16_f32 v192, v186, v187
	v_cvt_pk_bf16_f32 v193, v188, v189
	ds_write_b16 v170, v192 offset:7344
	ds_write_b16_d16_hi v170, v192 offset:7376
	ds_write_b16 v170, v193 offset:7408
	ds_write_b16_d16_hi v170, v193 offset:7440
	ds_read_b128 v[130:133], v171 offset:0
	ds_read_b128 v[134:137], v171 offset:1152
	ds_read_b128 v[138:141], v171 offset:2304
	ds_read_b128 v[142:145], v171 offset:3456
	ds_read_b128 v[146:149], v171 offset:4608
	ds_read_b128 v[150:153], v171 offset:5760
	ds_read_b128 v[154:157], v171 offset:6912
	ds_read_b128 v[158:161], v171 offset:8064
	s_waitcnt lgkmcnt(7)
	global_store_dwordx4 v172, v[130:133], s[44:45] offset:0
	s_waitcnt lgkmcnt(6)
	global_store_dwordx4 v172, v[134:137], s[44:45] offset:1024
	s_waitcnt lgkmcnt(5)
	global_store_dwordx4 v172, v[138:141], s[44:45] offset:2048
	s_waitcnt lgkmcnt(4)
	global_store_dwordx4 v172, v[142:145], s[44:45] offset:3072
	s_waitcnt lgkmcnt(3)
	global_store_dwordx4 v172, v[146:149], s[62:63] offset:0
	s_waitcnt lgkmcnt(2)
	global_store_dwordx4 v172, v[150:153], s[62:63] offset:1024
	s_waitcnt lgkmcnt(1)
	global_store_dwordx4 v172, v[154:157], s[62:63] offset:2048
	s_waitcnt lgkmcnt(0)
; template <int EPI>
; DI void gemm_phase(const P& p, int l, const u16* __restrict__ A, const u16* __restrict__ Bt, int mpx, char* lds) {
;     ...
;           } else if (tr == 4) {
;             float sr, cr, sc, cc;
;             sincos_rev((float)(s >> 6) * invf32, sr, cr);
;             sincos_rev((float)(s & 63) * invf32, sc, cc);
;             const float p0 = __shfl_xor(v0, 8), p1 = __shfl_xor(v1, 8), p2 = __shfl_xor(v2, 8), p3 = __shfl_xor(v3, 8);
;             v0 = lo8 ? (v0 * cr - p0 * sr) : (v0 * cr + p0 * sr);
;             v1 = lo8 ? (v1 * cc - p1 * sc) : (v1 * cc + p1 * sc);
;             v2 = lo8 ? (v2 * cr - p2 * sr) : (v2 * cr + p2 * sr);
;             v3 = lo8 ? (v3 * cc - p3 * sc) : (v3 * cc + p3 * sc);
;           }
;     ...
;       __builtin_amdgcn_fence(__ATOMIC_RELEASE, "wavefront");
;       u16* dh = (kind == 1) ? dst + hf * 64 : dst + (size_t)(hf * 64) * rstride;
; #pragma unroll
;       for (int i = 0; i < 8; ++i) {
;         const int c = lane + i * 64;
;         const int row = c >> 3, cc = c & 7;
;         uint4 v = *(const uint4*)&Tl[row * 72 + cc * 8];
;         *(uint4*)(dh + (size_t)row * rstride + cc * 8) = v;
;       }
	global_store_dwordx4 v172, v[158:161], s[62:63] offset:3072
	s_add_u32 s44, s44, 0x2000
	s_addc_u32 s45, s45, 0
	s_add_u32 s62, s62, 0x2000
	s_addc_u32 s63, s63, 0
	s_lshr_b32 s70, s69, 6
	s_add_i32 s70, s70, 1
	v_cvt_f32_i32_e32 v182, s70
	v_mul_f32_e32 v182, v174, v182
	v_mul_f32_e32 v183, 0.15915494, v182
	v_rndne_f32_e32 v183, v183
	v_fma_f32 v183, v182, 0.15915494, -v183
	v_sin_f32_e32 v175, v183
	v_cos_f32_e32 v176, v183
	s_nop 0
	v_cndmask_b32_e64 v177, v175, -v175, vcc
	v_mul_f32_dpp v182, v62, v177 row_ror:8 row_mask:0xf bank_mask:0xf
	v_mul_f32_dpp v183, v58, v212 row_ror:8 row_mask:0xf bank_mask:0xf
	v_mul_f32_dpp v184, v54, v177 row_ror:8 row_mask:0xf bank_mask:0xf
	v_mul_f32_dpp v185, v50, v212 row_ror:8 row_mask:0xf bank_mask:0xf
	v_fma_f32 v186, v62, v176, v182
	v_fma_f32 v187, v58, v238, v183
	v_fma_f32 v188, v54, v176, v184
	v_fma_f32 v189, v50, v238, v185
	v_cvt_pk_bf16_f32 v192, v186, v187
	v_cvt_pk_bf16_f32 v193, v188, v189
	ds_write_b16 v170, v192 offset:0
	ds_write_b16_d16_hi v170, v192 offset:32
	ds_write_b16 v170, v193 offset:64
	ds_write_b16_d16_hi v170, v193 offset:96
	v_mul_f32_dpp v182, v63, v177 row_ror:8 row_mask:0xf bank_mask:0xf
	v_mul_f32_dpp v183, v59, v213 row_ror:8 row_mask:0xf bank_mask:0xf
	v_mul_f32_dpp v184, v55, v177 row_ror:8 row_mask:0xf bank_mask:0xf
	v_mul_f32_dpp v185, v51, v213 row_ror:8 row_mask:0xf bank_mask:0xf
	v_fma_f32 v186, v63, v176, v182
	v_fma_f32 v187, v59, v239, v183
	v_fma_f32 v188, v55, v176, v184
	v_fma_f32 v189, v51, v239, v185
	v_cvt_pk_bf16_f32 v192, v186, v187
	v_cvt_pk_bf16_f32 v193, v188, v189
	ds_write_b16 v170, v192 offset:144
	ds_write_b16_d16_hi v170, v192 offset:176
	ds_write_b16 v170, v193 offset:208
	ds_write_b16_d16_hi v170, v193 offset:240
	v_mul_f32_dpp v182, v64, v177 row_ror:8 row_mask:0xf bank_mask:0xf
	v_mul_f32_dpp v183, v60, v214 row_ror:8 row_mask:0xf bank_mask:0xf
	v_mul_f32_dpp v184, v56, v177 row_ror:8 row_mask:0xf bank_mask:0xf
	v_mul_f32_dpp v185, v52, v214 row_ror:8 row_mask:0xf bank_mask:0xf
	v_fma_f32 v186, v64, v176, v182
	v_fma_f32 v187, v60, v240, v183
	v_fma_f32 v188, v56, v176, v184
	v_fma_f32 v189, v52, v240, v185
	v_cvt_pk_bf16_f32 v192, v186, v187
	v_cvt_pk_bf16_f32 v193, v188, v189
	ds_write_b16 v170, v192 offset:288
	ds_write_b16_d16_hi v170, v192 offset:320
	ds_write_b16 v170, v193 offset:352
	ds_write_b16_d16_hi v170, v193 offset:384
	v_mul_f32_dpp v182, v65, v177 row_ror:8 row_mask:0xf bank_mask:0xf
	v_mul_f32_dpp v183, v61, v215 row_ror:8 row_mask:0xf bank_mask:0xf
	v_mul_f32_dpp v184, v57, v177 row_ror:8 row_mask:0xf bank_mask:0xf
	v_mul_f32_dpp v185, v53, v215 row_ror:8 row_mask:0xf bank_mask:0xf
	v_fma_f32 v186, v65, v176, v182
	v_fma_f32 v187, v61, v241, v183
	v_fma_f32 v188, v57, v176, v184
	v_fma_f32 v189, v53, v241, v185
	v_cvt_pk_bf16_f32 v192, v186, v187
	v_cvt_pk_bf16_f32 v193, v188, v189
	ds_write_b16 v170, v192 offset:432
	ds_write_b16_d16_hi v170, v192 offset:464
	ds_write_b16 v170, v193 offset:496
	ds_write_b16_d16_hi v170, v193 offset:528
	v_mul_f32_dpp v182, v46, v177 row_ror:8 row_mask:0xf bank_mask:0xf
	v_mul_f32_dpp v183, v42, v216 row_ror:8 row_mask:0xf bank_mask:0xf
	v_mul_f32_dpp v184, v38, v177 row_ror:8 row_mask:0xf bank_mask:0xf
	v_mul_f32_dpp v185, v34, v216 row_ror:8 row_mask:0xf bank_mask:0xf
	v_fma_f32 v186, v46, v176, v182
	v_fma_f32 v187, v42, v242, v183
	v_fma_f32 v188, v38, v176, v184
	v_fma_f32 v189, v34, v242, v185
	v_cvt_pk_bf16_f32 v192, v186, v187
	v_cvt_pk_bf16_f32 v193, v188, v189
	ds_write_b16 v170, v192 offset:2304
	ds_write_b16_d16_hi v170, v192 offset:2336
	ds_write_b16 v170, v193 offset:2368
	ds_write_b16_d16_hi v170, v193 offset:2400
	v_mul_f32_dpp v182, v47, v177 row_ror:8 row_mask:0xf bank_mask:0xf
	v_mul_f32_dpp v183, v43, v217 row_ror:8 row_mask:0xf bank_mask:0xf
	v_mul_f32_dpp v184, v39, v177 row_ror:8 row_mask:0xf bank_mask:0xf
	v_mul_f32_dpp v185, v35, v217 row_ror:8 row_mask:0xf bank_mask:0xf
	v_fma_f32 v186, v47, v176, v182
	v_fma_f32 v187, v43, v243, v183
	v_fma_f32 v188, v39, v176, v184
	v_fma_f32 v189, v35, v243, v185
	v_cvt_pk_bf16_f32 v192, v186, v187
	v_cvt_pk_bf16_f32 v193, v188, v189
	ds_write_b16 v170, v192 offset:2448
	ds_write_b16_d16_hi v170, v192 offset:2480
	ds_write_b16 v170, v193 offset:2512
	ds_write_b16_d16_hi v170, v193 offset:2544
	v_mul_f32_dpp v182, v48, v177 row_ror:8 row_mask:0xf bank_mask:0xf
	v_mul_f32_dpp v183, v44, v218 row_ror:8 row_mask:0xf bank_mask:0xf
	v_mul_f32_dpp v184, v40, v177 row_ror:8 row_mask:0xf bank_mask:0xf
	v_mul_f32_dpp v185, v36, v218 row_ror:8 row_mask:0xf bank_mask:0xf
	v_fma_f32 v186, v48, v176, v182
	v_fma_f32 v187, v44, v244, v183
	v_fma_f32 v188, v40, v176, v184
	v_fma_f32 v189, v36, v244, v185
	v_cvt_pk_bf16_f32 v192, v186, v187
	v_cvt_pk_bf16_f32 v193, v188, v189
	ds_write_b16 v170, v192 offset:2592
	ds_write_b16_d16_hi v170, v192 offset:2624
	ds_write_b16 v170, v193 offset:2656
	ds_write_b16_d16_hi v170, v193 offset:2688
	v_mul_f32_dpp v182, v49, v177 row_ror:8 row_mask:0xf bank_mask:0xf
	v_mul_f32_dpp v183, v45, v219 row_ror:8 row_mask:0xf bank_mask:0xf
	v_mul_f32_dpp v184, v41, v177 row_ror:8 row_mask:0xf bank_mask:0xf
	v_mul_f32_dpp v185, v37, v219 row_ror:8 row_mask:0xf bank_mask:0xf
	v_fma_f32 v186, v49, v176, v182
	v_fma_f32 v187, v45, v245, v183
	v_fma_f32 v188, v41, v176, v184
	v_fma_f32 v189, v37, v245, v185
	v_cvt_pk_bf16_f32 v192, v186, v187
	v_cvt_pk_bf16_f32 v193, v188, v189
	ds_write_b16 v170, v192 offset:2736
	ds_write_b16_d16_hi v170, v192 offset:2768
	ds_write_b16 v170, v193 offset:2800
	ds_write_b16_d16_hi v170, v193 offset:2832
	v_mul_f32_dpp v182, v30, v177 row_ror:8 row_mask:0xf bank_mask:0xf
; template <int EPI>
; DI void gemm_phase(const P& p, int l, const u16* __restrict__ A, const u16* __restrict__ Bt, int mpx, char* lds) {
;     ...
;           } else if (tr == 4) {
;             float sr, cr, sc, cc;
;             sincos_rev((float)(s >> 6) * invf32, sr, cr);
;             sincos_rev((float)(s & 63) * invf32, sc, cc);
;             const float p0 = __shfl_xor(v0, 8), p1 = __shfl_xor(v1, 8), p2 = __shfl_xor(v2, 8), p3 = __shfl_xor(v3, 8);
;             v0 = lo8 ? (v0 * cr - p0 * sr) : (v0 * cr + p0 * sr);
;             v1 = lo8 ? (v1 * cc - p1 * sc) : (v1 * cc + p1 * sc);
;             v2 = lo8 ? (v2 * cr - p2 * sr) : (v2 * cr + p2 * sr);
;             v3 = lo8 ? (v3 * cc - p3 * sc) : (v3 * cc + p3 * sc);
;           }
;     ...
;       __builtin_amdgcn_fence(__ATOMIC_RELEASE, "wavefront");
;       u16* dh = (kind == 1) ? dst + hf * 64 : dst + (size_t)(hf * 64) * rstride;
; #pragma unroll
;       for (int i = 0; i < 8; ++i) {
;         const int c = lane + i * 64;
;         const int row = c >> 3, cc = c & 7;
;         uint4 v = *(const uint4*)&Tl[row * 72 + cc * 8];
;         *(uint4*)(dh + (size_t)row * rstride + cc * 8) = v;
;       }
	v_mul_f32_dpp v183, v26, v220 row_ror:8 row_mask:0xf bank_mask:0xf
	v_mul_f32_dpp v184, v22, v177 row_ror:8 row_mask:0xf bank_mask:0xf
	v_mul_f32_dpp v185, v18, v220 row_ror:8 row_mask:0xf bank_mask:0xf
	v_fma_f32 v186, v30, v176, v182
	v_fma_f32 v187, v26, v246, v183
	v_fma_f32 v188, v22, v176, v184
	v_fma_f32 v189, v18, v246, v185
	v_cvt_pk_bf16_f32 v192, v186, v187
	v_cvt_pk_bf16_f32 v193, v188, v189
	ds_write_b16 v170, v192 offset:4608
	ds_write_b16_d16_hi v170, v192 offset:4640
	ds_write_b16 v170, v193 offset:4672
	ds_write_b16_d16_hi v170, v193 offset:4704
	v_mul_f32_dpp v182, v31, v177 row_ror:8 row_mask:0xf bank_mask:0xf
	v_mul_f32_dpp v183, v27, v221 row_ror:8 row_mask:0xf bank_mask:0xf
	v_mul_f32_dpp v184, v23, v177 row_ror:8 row_mask:0xf bank_mask:0xf
	v_mul_f32_dpp v185, v19, v221 row_ror:8 row_mask:0xf bank_mask:0xf
	v_fma_f32 v186, v31, v176, v182
	v_fma_f32 v187, v27, v247, v183
	v_fma_f32 v188, v23, v176, v184
	v_fma_f32 v189, v19, v247, v185
	v_cvt_pk_bf16_f32 v192, v186, v187
	v_cvt_pk_bf16_f32 v193, v188, v189
	ds_write_b16 v170, v192 offset:4752
	ds_write_b16_d16_hi v170, v192 offset:4784
	ds_write_b16 v170, v193 offset:4816
	ds_write_b16_d16_hi v170, v193 offset:4848
	v_mul_f32_dpp v182, v32, v177 row_ror:8 row_mask:0xf bank_mask:0xf
	v_mul_f32_dpp v183, v28, v222 row_ror:8 row_mask:0xf bank_mask:0xf
	v_mul_f32_dpp v184, v24, v177 row_ror:8 row_mask:0xf bank_mask:0xf
	v_mul_f32_dpp v185, v20, v222 row_ror:8 row_mask:0xf bank_mask:0xf
	v_fma_f32 v186, v32, v176, v182
	v_fma_f32 v187, v28, v248, v183
	v_fma_f32 v188, v24, v176, v184
	v_fma_f32 v189, v20, v248, v185
	v_cvt_pk_bf16_f32 v192, v186, v187
	v_cvt_pk_bf16_f32 v193, v188, v189
	ds_write_b16 v170, v192 offset:4896
	ds_write_b16_d16_hi v170, v192 offset:4928
	ds_write_b16 v170, v193 offset:4960
	ds_write_b16_d16_hi v170, v193 offset:4992
	v_mul_f32_dpp v182, v33, v177 row_ror:8 row_mask:0xf bank_mask:0xf
	v_mul_f32_dpp v183, v29, v223 row_ror:8 row_mask:0xf bank_mask:0xf
	v_mul_f32_dpp v184, v25, v177 row_ror:8 row_mask:0xf bank_mask:0xf
	v_mul_f32_dpp v185, v21, v223 row_ror:8 row_mask:0xf bank_mask:0xf
	v_fma_f32 v186, v33, v176, v182
	v_fma_f32 v187, v29, v249, v183
	v_fma_f32 v188, v25, v176, v184
	v_fma_f32 v189, v21, v249, v185
	v_cvt_pk_bf16_f32 v192, v186, v187
	v_cvt_pk_bf16_f32 v193, v188, v189
	ds_write_b16 v170, v192 offset:5040
	ds_write_b16_d16_hi v170, v192 offset:5072
	ds_write_b16 v170, v193 offset:5104
	ds_write_b16_d16_hi v170, v193 offset:5136
	v_mul_f32_dpp v182, v166, v177 row_ror:8 row_mask:0xf bank_mask:0xf
	v_mul_f32_dpp v183, v162, v234 row_ror:8 row_mask:0xf bank_mask:0xf
	v_mul_f32_dpp v184, v2, v177 row_ror:8 row_mask:0xf bank_mask:0xf
	v_mul_f32_dpp v185, v6, v234 row_ror:8 row_mask:0xf bank_mask:0xf
	v_fma_f32 v186, v166, v176, v182
	v_fma_f32 v187, v162, v250, v183
	v_fma_f32 v188, v2, v176, v184
	v_fma_f32 v189, v6, v250, v185
	v_cvt_pk_bf16_f32 v192, v186, v187
	v_cvt_pk_bf16_f32 v193, v188, v189
	ds_write_b16 v170, v192 offset:6912
	ds_write_b16_d16_hi v170, v192 offset:6944
	ds_write_b16 v170, v193 offset:6976
	ds_write_b16_d16_hi v170, v193 offset:7008
	v_mul_f32_dpp v182, v167, v177 row_ror:8 row_mask:0xf bank_mask:0xf
	v_mul_f32_dpp v183, v163, v235 row_ror:8 row_mask:0xf bank_mask:0xf
	v_mul_f32_dpp v184, v3, v177 row_ror:8 row_mask:0xf bank_mask:0xf
	v_mul_f32_dpp v185, v7, v235 row_ror:8 row_mask:0xf bank_mask:0xf
	v_fma_f32 v186, v167, v176, v182
	v_fma_f32 v187, v163, v251, v183
	v_fma_f32 v188, v3, v176, v184
	v_fma_f32 v189, v7, v251, v185
	v_cvt_pk_bf16_f32 v192, v186, v187
	v_cvt_pk_bf16_f32 v193, v188, v189
	ds_write_b16 v170, v192 offset:7056
	ds_write_b16_d16_hi v170, v192 offset:7088
	ds_write_b16 v170, v193 offset:7120
	ds_write_b16_d16_hi v170, v193 offset:7152
	v_mul_f32_dpp v182, v168, v177 row_ror:8 row_mask:0xf bank_mask:0xf
	v_mul_f32_dpp v183, v164, v236 row_ror:8 row_mask:0xf bank_mask:0xf
	v_mul_f32_dpp v184, v4, v177 row_ror:8 row_mask:0xf bank_mask:0xf
	v_mul_f32_dpp v185, v8, v236 row_ror:8 row_mask:0xf bank_mask:0xf
	v_fma_f32 v186, v168, v176, v182
	v_fma_f32 v187, v164, v252, v183
	v_fma_f32 v188, v4, v176, v184
	v_fma_f32 v189, v8, v252, v185
	v_cvt_pk_bf16_f32 v192, v186, v187
	v_cvt_pk_bf16_f32 v193, v188, v189
	ds_write_b16 v170, v192 offset:7200
	ds_write_b16_d16_hi v170, v192 offset:7232
	ds_write_b16 v170, v193 offset:7264
	ds_write_b16_d16_hi v170, v193 offset:7296
	v_mul_f32_dpp v182, v169, v177 row_ror:8 row_mask:0xf bank_mask:0xf
	v_mul_f32_dpp v183, v165, v237 row_ror:8 row_mask:0xf bank_mask:0xf
	v_mul_f32_dpp v184, v5, v177 row_ror:8 row_mask:0xf bank_mask:0xf
	v_mul_f32_dpp v185, v9, v237 row_ror:8 row_mask:0xf bank_mask:0xf
	v_fma_f32 v186, v169, v176, v182
	v_fma_f32 v187, v165, v253, v183
	v_fma_f32 v188, v5, v176, v184
	v_fma_f32 v189, v9, v253, v185
	v_cvt_pk_bf16_f32 v192, v186, v187
	v_cvt_pk_bf16_f32 v193, v188, v189
	ds_write_b16 v170, v192 offset:7344
	ds_write_b16_d16_hi v170, v192 offset:7376
	ds_write_b16 v170, v193 offset:7408
	ds_write_b16_d16_hi v170, v193 offset:7440
	ds_read_b128 v[130:133], v171 offset:0
	ds_read_b128 v[134:137], v171 offset:1152
	ds_read_b128 v[138:141], v171 offset:2304
	ds_read_b128 v[142:145], v171 offset:3456
	ds_read_b128 v[146:149], v171 offset:4608
	ds_read_b128 v[150:153], v171 offset:5760
	ds_read_b128 v[154:157], v171 offset:6912
	ds_read_b128 v[158:161], v171 offset:8064
	s_waitcnt lgkmcnt(7)
	global_store_dwordx4 v172, v[130:133], s[44:45] offset:0
	s_waitcnt lgkmcnt(6)
	global_store_dwordx4 v172, v[134:137], s[44:45] offset:1024
	s_waitcnt lgkmcnt(5)
	global_store_dwordx4 v172, v[138:141], s[44:45] offset:2048
	s_waitcnt lgkmcnt(4)
	global_store_dwordx4 v172, v[142:145], s[44:45] offset:3072
	s_waitcnt lgkmcnt(3)
	global_store_dwordx4 v172, v[146:149], s[62:63] offset:0
	s_waitcnt lgkmcnt(2)
	global_store_dwordx4 v172, v[150:153], s[62:63] offset:1024
	s_waitcnt lgkmcnt(1)
	global_store_dwordx4 v172, v[154:157], s[62:63] offset:2048
	s_waitcnt lgkmcnt(0)
	global_store_dwordx4 v172, v[158:161], s[62:63] offset:3072
	s_branch .Lfe_done
; template <int EPI>
; DI void gemm_phase(const P& p, int l, const u16* __restrict__ A, const u16* __restrict__ Bt, int mpx, char* lds) {
;     ...
;     const float* gw = (cb < 1280 ? p.ga_qn : p.ga_kn) + l * 64;
;     float gv0 = 1.f, gv1 = 1.f, gv2 = 1.f, gv3 = 1.f;
;     if (donorm) { gv0 = gw[r]; gv1 = gw[16 + r]; gv2 = gw[32 + r]; gv3 = gw[48 + r]; }
;     const bool dorope = (tr == 3) && !isctx;
;     const float invf64 = exp2f(-13.287712379549449f * (float)r * (1.f / 16.f));
;     const float invf32 = exp2f(-13.287712379549449f * (float)(r & 7) * (1.f / 8.f));
;     ...
;             if (dorope) {
;               float sr, cr, sc, cc;
;               sincos_rev((float)(s >> 6) * invf64, sr, cr);
;               sincos_rev((float)(s & 63) * invf64, sc, cc);
.Lfe_k0_normrope:
	s_cmp_lt_u32 s43, 20
	s_movk_i32 s70, 0x68
	s_cselect_b32 s70, 0x60, s70
	s_add_u32 s70, s96, s70
	s_addc_u32 s71, s97, 0
	s_load_dwordx2 s[70:71], s[70:71], 0x0
	v_and_b32_e32 v0, 15, v226
	v_lshlrev_b32_e32 v0, 2, v0
	v_mov_b32_e32 v173, 0x358637bd
	s_waitcnt lgkmcnt(0)
	s_lshl_b32 s63, s52, 2
	s_add_u32 s70, s70, s63
	s_addc_u32 s71, s71, 0
	global_load_dword v178, v0, s[70:71] offset:0
	global_load_dword v179, v0, s[70:71] offset:64
	global_load_dword v180, v0, s[70:71] offset:128
	global_load_dword v181, v0, s[70:71] offset:192
	v_and_b32_e32 v0, 15, v226
	v_cvt_f32_ubyte0_e32 v0, v0
	v_mul_f32_e32 v0, 0xc1549a78, v0
	v_mul_f32_e32 v0, 0x3d800000, v0
	v_exp_f32_e32 v174, v0
	v_lshrrev_b32_e32 v0, 4, v226
	v_lshlrev_b32_e32 v0, 2, v0
	v_add_u32_e32 v182, 0, v0
	v_cvt_f32_i32_e32 v182, v182
	v_mul_f32_e32 v182, v174, v182
	v_mul_f32_e32 v183, 0.15915494, v182
	v_rndne_f32_e32 v183, v183
	v_fma_f32 v183, v182, 0.15915494, -v183
	v_sin_f32_e32 v212, v183
	v_cos_f32_e32 v238, v183
	v_add_u32_e32 v182, 1, v0
	v_cvt_f32_i32_e32 v182, v182
	v_mul_f32_e32 v182, v174, v182
	v_mul_f32_e32 v183, 0.15915494, v182
	v_rndne_f32_e32 v183, v183
	v_fma_f32 v183, v182, 0.15915494, -v183
	v_sin_f32_e32 v213, v183
	v_cos_f32_e32 v239, v183
	v_add_u32_e32 v182, 2, v0
	v_cvt_f32_i32_e32 v182, v182
	v_mul_f32_e32 v182, v174, v182
	v_mul_f32_e32 v183, 0.15915494, v182
	v_rndne_f32_e32 v183, v183
	v_fma_f32 v183, v182, 0.15915494, -v183
	v_sin_f32_e32 v214, v183
	v_cos_f32_e32 v240, v183
	v_add_u32_e32 v182, 3, v0
	v_cvt_f32_i32_e32 v182, v182
	v_mul_f32_e32 v182, v174, v182
	v_mul_f32_e32 v183, 0.15915494, v182
	v_rndne_f32_e32 v183, v183
	v_fma_f32 v183, v182, 0.15915494, -v183
	v_sin_f32_e32 v215, v183
	v_cos_f32_e32 v241, v183
	v_add_u32_e32 v182, 16, v0
	v_cvt_f32_i32_e32 v182, v182
	v_mul_f32_e32 v182, v174, v182
	v_mul_f32_e32 v183, 0.15915494, v182
	v_rndne_f32_e32 v183, v183
	v_fma_f32 v183, v182, 0.15915494, -v183
	v_sin_f32_e32 v216, v183
	v_cos_f32_e32 v242, v183
	v_add_u32_e32 v182, 17, v0
	v_cvt_f32_i32_e32 v182, v182
	v_mul_f32_e32 v182, v174, v182
	v_mul_f32_e32 v183, 0.15915494, v182
	v_rndne_f32_e32 v183, v183
	v_fma_f32 v183, v182, 0.15915494, -v183
	v_sin_f32_e32 v217, v183
	v_cos_f32_e32 v243, v183
	v_add_u32_e32 v182, 18, v0
	v_cvt_f32_i32_e32 v182, v182
	v_mul_f32_e32 v182, v174, v182
	v_mul_f32_e32 v183, 0.15915494, v182
	v_rndne_f32_e32 v183, v183
	v_fma_f32 v183, v182, 0.15915494, -v183
	v_sin_f32_e32 v218, v183
	v_cos_f32_e32 v244, v183
	v_add_u32_e32 v182, 19, v0
	v_cvt_f32_i32_e32 v182, v182
	v_mul_f32_e32 v182, v174, v182
	v_mul_f32_e32 v183, 0.15915494, v182
	v_rndne_f32_e32 v183, v183
	v_fma_f32 v183, v182, 0.15915494, -v183
	v_sin_f32_e32 v219, v183
	v_cos_f32_e32 v245, v183
	v_add_u32_e32 v182, 32, v0
	v_cvt_f32_i32_e32 v182, v182
	v_mul_f32_e32 v182, v174, v182
	v_mul_f32_e32 v183, 0.15915494, v182
	v_rndne_f32_e32 v183, v183
	v_fma_f32 v183, v182, 0.15915494, -v183
	v_sin_f32_e32 v220, v183
	v_cos_f32_e32 v246, v183
	v_add_u32_e32 v182, 33, v0
	v_cvt_f32_i32_e32 v182, v182
	v_mul_f32_e32 v182, v174, v182
	v_mul_f32_e32 v183, 0.15915494, v182
	v_rndne_f32_e32 v183, v183
	v_fma_f32 v183, v182, 0.15915494, -v183
	v_sin_f32_e32 v221, v183
	v_cos_f32_e32 v247, v183
	v_add_u32_e32 v182, 34, v0
	v_cvt_f32_i32_e32 v182, v182
	v_mul_f32_e32 v182, v174, v182
	v_mul_f32_e32 v183, 0.15915494, v182
	v_rndne_f32_e32 v183, v183
	v_fma_f32 v183, v182, 0.15915494, -v183
	v_sin_f32_e32 v222, v183
	v_cos_f32_e32 v248, v183
	v_add_u32_e32 v182, 35, v0
	v_cvt_f32_i32_e32 v182, v182
	v_mul_f32_e32 v182, v174, v182
	v_mul_f32_e32 v183, 0.15915494, v182
	v_rndne_f32_e32 v183, v183
	v_fma_f32 v183, v182, 0.15915494, -v183
	v_sin_f32_e32 v223, v183
	v_cos_f32_e32 v249, v183
	v_add_u32_e32 v182, 48, v0
	v_cvt_f32_i32_e32 v182, v182
	v_mul_f32_e32 v182, v174, v182
	v_mul_f32_e32 v183, 0.15915494, v182
	v_rndne_f32_e32 v183, v183
	v_fma_f32 v183, v182, 0.15915494, -v183
	v_sin_f32_e32 v234, v183
	v_cos_f32_e32 v250, v183
	v_add_u32_e32 v182, 49, v0
	v_cvt_f32_i32_e32 v182, v182
	v_mul_f32_e32 v182, v174, v182
	v_mul_f32_e32 v183, 0.15915494, v182
	v_rndne_f32_e32 v183, v183
	v_fma_f32 v183, v182, 0.15915494, -v183
	v_sin_f32_e32 v235, v183
	v_cos_f32_e32 v251, v183
	v_add_u32_e32 v182, 50, v0
	v_cvt_f32_i32_e32 v182, v182
	v_mul_f32_e32 v182, v174, v182
	v_mul_f32_e32 v183, 0.15915494, v182
	v_rndne_f32_e32 v183, v183
	v_fma_f32 v183, v182, 0.15915494, -v183
	v_sin_f32_e32 v236, v183
	v_cos_f32_e32 v252, v183
	v_add_u32_e32 v182, 51, v0
	v_cvt_f32_i32_e32 v182, v182
	v_mul_f32_e32 v182, v174, v182
	v_mul_f32_e32 v183, 0.15915494, v182
	v_rndne_f32_e32 v183, v183
	v_fma_f32 v183, v182, 0.15915494, -v183
	v_sin_f32_e32 v237, v183
	v_cos_f32_e32 v253, v183
	s_waitcnt vmcnt(0)
; template <int EPI>
; DI void gemm_phase(const P& p, int l, const u16* __restrict__ A, const u16* __restrict__ Bt, int mpx, char* lds) {
;     ...
;               float ss = v0 * v0 + v1 * v1 + v2 * v2 + v3 * v3;
;               ss += __shfl_xor(ss, 1);
;               ss += __shfl_xor(ss, 2);
;               ss += __shfl_xor(ss, 4);
;               ss += __shfl_xor(ss, 8);
;               const float inv = rsqrtf(ss * (1.f / 64.f) + 1e-6f);
;               v0 *= inv * gv0; v1 *= inv * gv1; v2 *= inv * gv2; v3 *= inv * gv3;
;             }
;             if (dorope) {
;               float sr, cr, sc, cc;
;               sincos_rev((float)(s >> 6) * invf64, sr, cr);
;               sincos_rev((float)(s & 63) * invf64, sc, cc);
;               const float a1 = v0, a2 = v1, b1 = v2, b2 = v3;
;               v0 = a1 * cr - a2 * sr;
;               v1 = a2 * cr + a1 * sr;
;               v2 = b1 * cc - b2 * sc;
;               v3 = b2 * cc + b1 * sc;
;             }
	s_add_u32 s62, s44, 0x1000
	s_addc_u32 s63, s45, 0
	s_lshr_b32 s70, s69, 6
	v_cvt_f32_i32_e32 v182, s70
	v_mul_f32_e32 v182, v174, v182
	v_mul_f32_e32 v183, 0.15915494, v182
	v_rndne_f32_e32 v183, v183
	v_fma_f32 v183, v182, 0.15915494, -v183
	v_sin_f32_e32 v175, v183
	v_cos_f32_e32 v176, v183
	v_mul_f32_e32 v182, v126, v126
	v_mul_f32_e32 v183, v122, v122
	v_mul_f32_e32 v184, v118, v118
	v_mul_f32_e32 v185, v114, v114
	v_add_f32_e32 v186, v182, v183
	v_add_f32_e32 v186, v186, v184
	v_add_f32_e32 v186, v186, v185
	s_nop 1
	v_add_f32_dpp v186, v186, v186 quad_perm:[1,0,3,2] row_mask:0xf bank_mask:0xf
	s_nop 1
	v_add_f32_dpp v186, v186, v186 quad_perm:[2,3,0,1] row_mask:0xf bank_mask:0xf
	s_nop 1
	v_add_f32_dpp v186, v186, v186 row_half_mirror row_mask:0xf bank_mask:0xf
	s_nop 1
	v_add_f32_dpp v186, v186, v186 row_mirror row_mask:0xf bank_mask:0xf
	v_fmamk_f32 v186, v186, 0x3c800000, v173
	v_rsq_f32_e32 v186, v186
	s_nop 0
	v_mul_f32_e32 v187, v178, v186
	v_mul_f32_e32 v188, v179, v186
	v_mul_f32_e32 v189, v180, v186
	v_mul_f32_e32 v190, v181, v186
	v_mul_f32_e32 v182, v126, v187
	v_mul_f32_e32 v183, v122, v188
	v_mul_f32_e32 v184, v118, v189
	v_mul_f32_e32 v185, v114, v190
	v_mul_f32_e32 v186, v175, v183
	v_mul_f32_e32 v187, v176, v183
	v_fma_f32 v188, v176, v182, -v186
	v_fma_f32 v189, v175, v182, v187
	v_mul_f32_e32 v186, v212, v185
	v_mul_f32_e32 v187, v238, v185
	v_fma_f32 v190, v238, v184, -v186
	v_fma_f32 v191, v212, v184, v187
	v_cvt_pk_bf16_f32 v192, v188, v189
	v_cvt_pk_bf16_f32 v193, v190, v191
	ds_write_b16 v170, v192 offset:0
	ds_write_b16_d16_hi v170, v192 offset:32
	ds_write_b16 v170, v193 offset:64
	ds_write_b16_d16_hi v170, v193 offset:96
	v_mul_f32_e32 v182, v127, v127
	v_mul_f32_e32 v183, v123, v123
	v_mul_f32_e32 v184, v119, v119
	v_mul_f32_e32 v185, v115, v115
	v_add_f32_e32 v186, v182, v183
	v_add_f32_e32 v186, v186, v184
	v_add_f32_e32 v186, v186, v185
	s_nop 1
	v_add_f32_dpp v186, v186, v186 quad_perm:[1,0,3,2] row_mask:0xf bank_mask:0xf
	s_nop 1
	v_add_f32_dpp v186, v186, v186 quad_perm:[2,3,0,1] row_mask:0xf bank_mask:0xf
	s_nop 1
	v_add_f32_dpp v186, v186, v186 row_half_mirror row_mask:0xf bank_mask:0xf
	s_nop 1
	v_add_f32_dpp v186, v186, v186 row_mirror row_mask:0xf bank_mask:0xf
	v_fmamk_f32 v186, v186, 0x3c800000, v173
	v_rsq_f32_e32 v186, v186
	s_nop 0
	v_mul_f32_e32 v187, v178, v186
	v_mul_f32_e32 v188, v179, v186
	v_mul_f32_e32 v189, v180, v186
	v_mul_f32_e32 v190, v181, v186
	v_mul_f32_e32 v182, v127, v187
	v_mul_f32_e32 v183, v123, v188
	v_mul_f32_e32 v184, v119, v189
	v_mul_f32_e32 v185, v115, v190
	v_mul_f32_e32 v186, v175, v183
	v_mul_f32_e32 v187, v176, v183
	v_fma_f32 v188, v176, v182, -v186
	v_fma_f32 v189, v175, v182, v187
	v_mul_f32_e32 v186, v213, v185
	v_mul_f32_e32 v187, v239, v185
	v_fma_f32 v190, v239, v184, -v186
	v_fma_f32 v191, v213, v184, v187
	v_cvt_pk_bf16_f32 v192, v188, v189
	v_cvt_pk_bf16_f32 v193, v190, v191
	ds_write_b16 v170, v192 offset:144
	ds_write_b16_d16_hi v170, v192 offset:176
	ds_write_b16 v170, v193 offset:208
	ds_write_b16_d16_hi v170, v193 offset:240
	v_mul_f32_e32 v182, v128, v128
	v_mul_f32_e32 v183, v124, v124
	v_mul_f32_e32 v184, v120, v120
	v_mul_f32_e32 v185, v116, v116
	v_add_f32_e32 v186, v182, v183
	v_add_f32_e32 v186, v186, v184
	v_add_f32_e32 v186, v186, v185
	s_nop 1
	v_add_f32_dpp v186, v186, v186 quad_perm:[1,0,3,2] row_mask:0xf bank_mask:0xf
	s_nop 1
	v_add_f32_dpp v186, v186, v186 quad_perm:[2,3,0,1] row_mask:0xf bank_mask:0xf
	s_nop 1
	v_add_f32_dpp v186, v186, v186 row_half_mirror row_mask:0xf bank_mask:0xf
	s_nop 1
	v_add_f32_dpp v186, v186, v186 row_mirror row_mask:0xf bank_mask:0xf
	v_fmamk_f32 v186, v186, 0x3c800000, v173
	v_rsq_f32_e32 v186, v186
	s_nop 0
	v_mul_f32_e32 v187, v178, v186
	v_mul_f32_e32 v188, v179, v186
	v_mul_f32_e32 v189, v180, v186
	v_mul_f32_e32 v190, v181, v186
	v_mul_f32_e32 v182, v128, v187
	v_mul_f32_e32 v183, v124, v188
	v_mul_f32_e32 v184, v120, v189
	v_mul_f32_e32 v185, v116, v190
	v_mul_f32_e32 v186, v175, v183
	v_mul_f32_e32 v187, v176, v183
	v_fma_f32 v188, v176, v182, -v186
	v_fma_f32 v189, v175, v182, v187
	v_mul_f32_e32 v186, v214, v185
	v_mul_f32_e32 v187, v240, v185
	v_fma_f32 v190, v240, v184, -v186
	v_fma_f32 v191, v214, v184, v187
	v_cvt_pk_bf16_f32 v192, v188, v189
	v_cvt_pk_bf16_f32 v193, v190, v191
	ds_write_b16 v170, v192 offset:288
	ds_write_b16_d16_hi v170, v192 offset:320
	ds_write_b16 v170, v193 offset:352
	ds_write_b16_d16_hi v170, v193 offset:384
	v_mul_f32_e32 v182, v129, v129
	v_mul_f32_e32 v183, v125, v125
	v_mul_f32_e32 v184, v121, v121
	v_mul_f32_e32 v185, v117, v117
	v_add_f32_e32 v186, v182, v183
	v_add_f32_e32 v186, v186, v184
	v_add_f32_e32 v186, v186, v185
	s_nop 1
	v_add_f32_dpp v186, v186, v186 quad_perm:[1,0,3,2] row_mask:0xf bank_mask:0xf
	s_nop 1
	v_add_f32_dpp v186, v186, v186 quad_perm:[2,3,0,1] row_mask:0xf bank_mask:0xf
	s_nop 1
	v_add_f32_dpp v186, v186, v186 row_half_mirror row_mask:0xf bank_mask:0xf
	s_nop 1
	v_add_f32_dpp v186, v186, v186 row_mirror row_mask:0xf bank_mask:0xf
	v_fmamk_f32 v186, v186, 0x3c800000, v173
	v_rsq_f32_e32 v186, v186
	s_nop 0
	v_mul_f32_e32 v187, v178, v186
	v_mul_f32_e32 v188, v179, v186
	v_mul_f32_e32 v189, v180, v186
	v_mul_f32_e32 v190, v181, v186
	v_mul_f32_e32 v182, v129, v187
	v_mul_f32_e32 v183, v125, v188
	v_mul_f32_e32 v184, v121, v189
	v_mul_f32_e32 v185, v117, v190
	v_mul_f32_e32 v186, v175, v183
	v_mul_f32_e32 v187, v176, v183
	v_fma_f32 v188, v176, v182, -v186
	v_fma_f32 v189, v175, v182, v187
	v_mul_f32_e32 v186, v215, v185
	v_mul_f32_e32 v187, v241, v185
	v_fma_f32 v190, v241, v184, -v186
	v_fma_f32 v191, v215, v184, v187
; template <int EPI>
; DI void gemm_phase(const P& p, int l, const u16* __restrict__ A, const u16* __restrict__ Bt, int mpx, char* lds) {
;     ...
;           } else if (tr == 3) {
;             if (donorm) {
;               float ss = v0 * v0 + v1 * v1 + v2 * v2 + v3 * v3;
;               ss += __shfl_xor(ss, 1);
;               ss += __shfl_xor(ss, 2);
;               ss += __shfl_xor(ss, 4);
;               ss += __shfl_xor(ss, 8);
;               const float inv = rsqrtf(ss * (1.f / 64.f) + 1e-6f);
;               v0 *= inv * gv0; v1 *= inv * gv1; v2 *= inv * gv2; v3 *= inv * gv3;
;             }
;             if (dorope) {
;               float sr, cr, sc, cc;
;               sincos_rev((float)(s >> 6) * invf64, sr, cr);
;               sincos_rev((float)(s & 63) * invf64, sc, cc);
;               const float a1 = v0, a2 = v1, b1 = v2, b2 = v3;
;               v0 = a1 * cr - a2 * sr;
;               v1 = a2 * cr + a1 * sr;
;               v2 = b1 * cc - b2 * sc;
;               v3 = b2 * cc + b1 * sc;
;             }
;     ...
;           } else {
;             Tl[rowl * 72 + 0 * 16 + r] = (u16)u01;
;             Tl[rowl * 72 + 1 * 16 + r] = (u16)(u01 >> 16);
;             Tl[rowl * 72 + 2 * 16 + r] = (u16)u23;
;             Tl[rowl * 72 + 3 * 16 + r] = (u16)(u23 >> 16);
	v_cvt_pk_bf16_f32 v192, v188, v189
	v_cvt_pk_bf16_f32 v193, v190, v191
	ds_write_b16 v170, v192 offset:432
	ds_write_b16_d16_hi v170, v192 offset:464
	ds_write_b16 v170, v193 offset:496
	ds_write_b16_d16_hi v170, v193 offset:528
	v_mul_f32_e32 v182, v110, v110
	v_mul_f32_e32 v183, v106, v106
	v_mul_f32_e32 v184, v102, v102
	v_mul_f32_e32 v185, v98, v98
	v_add_f32_e32 v186, v182, v183
	v_add_f32_e32 v186, v186, v184
	v_add_f32_e32 v186, v186, v185
	s_nop 1
	v_add_f32_dpp v186, v186, v186 quad_perm:[1,0,3,2] row_mask:0xf bank_mask:0xf
	s_nop 1
	v_add_f32_dpp v186, v186, v186 quad_perm:[2,3,0,1] row_mask:0xf bank_mask:0xf
	s_nop 1
	v_add_f32_dpp v186, v186, v186 row_half_mirror row_mask:0xf bank_mask:0xf
	s_nop 1
	v_add_f32_dpp v186, v186, v186 row_mirror row_mask:0xf bank_mask:0xf
	v_fmamk_f32 v186, v186, 0x3c800000, v173
	v_rsq_f32_e32 v186, v186
	s_nop 0
	v_mul_f32_e32 v187, v178, v186
	v_mul_f32_e32 v188, v179, v186
	v_mul_f32_e32 v189, v180, v186
	v_mul_f32_e32 v190, v181, v186
	v_mul_f32_e32 v182, v110, v187
	v_mul_f32_e32 v183, v106, v188
	v_mul_f32_e32 v184, v102, v189
	v_mul_f32_e32 v185, v98, v190
	v_mul_f32_e32 v186, v175, v183
	v_mul_f32_e32 v187, v176, v183
	v_fma_f32 v188, v176, v182, -v186
	v_fma_f32 v189, v175, v182, v187
	v_mul_f32_e32 v186, v216, v185
	v_mul_f32_e32 v187, v242, v185
	v_fma_f32 v190, v242, v184, -v186
	v_fma_f32 v191, v216, v184, v187
	v_cvt_pk_bf16_f32 v192, v188, v189
	v_cvt_pk_bf16_f32 v193, v190, v191
	ds_write_b16 v170, v192 offset:2304
	ds_write_b16_d16_hi v170, v192 offset:2336
	ds_write_b16 v170, v193 offset:2368
	ds_write_b16_d16_hi v170, v193 offset:2400
	v_mul_f32_e32 v182, v111, v111
	v_mul_f32_e32 v183, v107, v107
	v_mul_f32_e32 v184, v103, v103
	v_mul_f32_e32 v185, v99, v99
	v_add_f32_e32 v186, v182, v183
	v_add_f32_e32 v186, v186, v184
	v_add_f32_e32 v186, v186, v185
	s_nop 1
	v_add_f32_dpp v186, v186, v186 quad_perm:[1,0,3,2] row_mask:0xf bank_mask:0xf
	s_nop 1
	v_add_f32_dpp v186, v186, v186 quad_perm:[2,3,0,1] row_mask:0xf bank_mask:0xf
	s_nop 1
	v_add_f32_dpp v186, v186, v186 row_half_mirror row_mask:0xf bank_mask:0xf
	s_nop 1
	v_add_f32_dpp v186, v186, v186 row_mirror row_mask:0xf bank_mask:0xf
	v_fmamk_f32 v186, v186, 0x3c800000, v173
	v_rsq_f32_e32 v186, v186
	s_nop 0
	v_mul_f32_e32 v187, v178, v186
	v_mul_f32_e32 v188, v179, v186
	v_mul_f32_e32 v189, v180, v186
	v_mul_f32_e32 v190, v181, v186
	v_mul_f32_e32 v182, v111, v187
	v_mul_f32_e32 v183, v107, v188
	v_mul_f32_e32 v184, v103, v189
	v_mul_f32_e32 v185, v99, v190
	v_mul_f32_e32 v186, v175, v183
	v_mul_f32_e32 v187, v176, v183
	v_fma_f32 v188, v176, v182, -v186
	v_fma_f32 v189, v175, v182, v187
	v_mul_f32_e32 v186, v217, v185
	v_mul_f32_e32 v187, v243, v185
	v_fma_f32 v190, v243, v184, -v186
	v_fma_f32 v191, v217, v184, v187
	v_cvt_pk_bf16_f32 v192, v188, v189
	v_cvt_pk_bf16_f32 v193, v190, v191
	ds_write_b16 v170, v192 offset:2448
	ds_write_b16_d16_hi v170, v192 offset:2480
	ds_write_b16 v170, v193 offset:2512
	ds_write_b16_d16_hi v170, v193 offset:2544
	v_mul_f32_e32 v182, v112, v112
	v_mul_f32_e32 v183, v108, v108
	v_mul_f32_e32 v184, v104, v104
	v_mul_f32_e32 v185, v100, v100
	v_add_f32_e32 v186, v182, v183
	v_add_f32_e32 v186, v186, v184
	v_add_f32_e32 v186, v186, v185
	s_nop 1
	v_add_f32_dpp v186, v186, v186 quad_perm:[1,0,3,2] row_mask:0xf bank_mask:0xf
	s_nop 1
	v_add_f32_dpp v186, v186, v186 quad_perm:[2,3,0,1] row_mask:0xf bank_mask:0xf
	s_nop 1
	v_add_f32_dpp v186, v186, v186 row_half_mirror row_mask:0xf bank_mask:0xf
	s_nop 1
	v_add_f32_dpp v186, v186, v186 row_mirror row_mask:0xf bank_mask:0xf
	v_fmamk_f32 v186, v186, 0x3c800000, v173
	v_rsq_f32_e32 v186, v186
	s_nop 0
	v_mul_f32_e32 v187, v178, v186
	v_mul_f32_e32 v188, v179, v186
	v_mul_f32_e32 v189, v180, v186
	v_mul_f32_e32 v190, v181, v186
	v_mul_f32_e32 v182, v112, v187
	v_mul_f32_e32 v183, v108, v188
	v_mul_f32_e32 v184, v104, v189
	v_mul_f32_e32 v185, v100, v190
	v_mul_f32_e32 v186, v175, v183
	v_mul_f32_e32 v187, v176, v183
	v_fma_f32 v188, v176, v182, -v186
	v_fma_f32 v189, v175, v182, v187
	v_mul_f32_e32 v186, v218, v185
	v_mul_f32_e32 v187, v244, v185
	v_fma_f32 v190, v244, v184, -v186
	v_fma_f32 v191, v218, v184, v187
	v_cvt_pk_bf16_f32 v192, v188, v189
	v_cvt_pk_bf16_f32 v193, v190, v191
	ds_write_b16 v170, v192 offset:2592
	ds_write_b16_d16_hi v170, v192 offset:2624
	ds_write_b16 v170, v193 offset:2656
	ds_write_b16_d16_hi v170, v193 offset:2688
	v_mul_f32_e32 v182, v113, v113
	v_mul_f32_e32 v183, v109, v109
	v_mul_f32_e32 v184, v105, v105
	v_mul_f32_e32 v185, v101, v101
	v_add_f32_e32 v186, v182, v183
	v_add_f32_e32 v186, v186, v184
	v_add_f32_e32 v186, v186, v185
	s_nop 1
	v_add_f32_dpp v186, v186, v186 quad_perm:[1,0,3,2] row_mask:0xf bank_mask:0xf
	s_nop 1
	v_add_f32_dpp v186, v186, v186 quad_perm:[2,3,0,1] row_mask:0xf bank_mask:0xf
	s_nop 1
	v_add_f32_dpp v186, v186, v186 row_half_mirror row_mask:0xf bank_mask:0xf
	s_nop 1
	v_add_f32_dpp v186, v186, v186 row_mirror row_mask:0xf bank_mask:0xf
	v_fmamk_f32 v186, v186, 0x3c800000, v173
	v_rsq_f32_e32 v186, v186
	s_nop 0
	v_mul_f32_e32 v187, v178, v186
	v_mul_f32_e32 v188, v179, v186
	v_mul_f32_e32 v189, v180, v186
	v_mul_f32_e32 v190, v181, v186
	v_mul_f32_e32 v182, v113, v187
	v_mul_f32_e32 v183, v109, v188
	v_mul_f32_e32 v184, v105, v189
	v_mul_f32_e32 v185, v101, v190
	v_mul_f32_e32 v186, v175, v183
	v_mul_f32_e32 v187, v176, v183
	v_fma_f32 v188, v176, v182, -v186
	v_fma_f32 v189, v175, v182, v187
	v_mul_f32_e32 v186, v219, v185
	v_mul_f32_e32 v187, v245, v185
	v_fma_f32 v190, v245, v184, -v186
	v_fma_f32 v191, v219, v184, v187
	v_cvt_pk_bf16_f32 v192, v188, v189
	v_cvt_pk_bf16_f32 v193, v190, v191
; template <int EPI>
; DI void gemm_phase(const P& p, int l, const u16* __restrict__ A, const u16* __restrict__ Bt, int mpx, char* lds) {
;     ...
;           } else if (tr == 3) {
;             if (donorm) {
;               float ss = v0 * v0 + v1 * v1 + v2 * v2 + v3 * v3;
;               ss += __shfl_xor(ss, 1);
;               ss += __shfl_xor(ss, 2);
;               ss += __shfl_xor(ss, 4);
;               ss += __shfl_xor(ss, 8);
;               const float inv = rsqrtf(ss * (1.f / 64.f) + 1e-6f);
;               v0 *= inv * gv0; v1 *= inv * gv1; v2 *= inv * gv2; v3 *= inv * gv3;
;             }
;             if (dorope) {
;               float sr, cr, sc, cc;
;               sincos_rev((float)(s >> 6) * invf64, sr, cr);
;               sincos_rev((float)(s & 63) * invf64, sc, cc);
;               const float a1 = v0, a2 = v1, b1 = v2, b2 = v3;
;               v0 = a1 * cr - a2 * sr;
;               v1 = a2 * cr + a1 * sr;
;               v2 = b1 * cc - b2 * sc;
;               v3 = b2 * cc + b1 * sc;
;             }
;     ...
;           } else {
;             Tl[rowl * 72 + 0 * 16 + r] = (u16)u01;
;             Tl[rowl * 72 + 1 * 16 + r] = (u16)(u01 >> 16);
;             Tl[rowl * 72 + 2 * 16 + r] = (u16)u23;
;             Tl[rowl * 72 + 3 * 16 + r] = (u16)(u23 >> 16);
	ds_write_b16 v170, v192 offset:2736
	ds_write_b16_d16_hi v170, v192 offset:2768
	ds_write_b16 v170, v193 offset:2800
	ds_write_b16_d16_hi v170, v193 offset:2832
	v_mul_f32_e32 v182, v94, v94
	v_mul_f32_e32 v183, v90, v90
	v_mul_f32_e32 v184, v86, v86
	v_mul_f32_e32 v185, v82, v82
	v_add_f32_e32 v186, v182, v183
	v_add_f32_e32 v186, v186, v184
	v_add_f32_e32 v186, v186, v185
	s_nop 1
	v_add_f32_dpp v186, v186, v186 quad_perm:[1,0,3,2] row_mask:0xf bank_mask:0xf
	s_nop 1
	v_add_f32_dpp v186, v186, v186 quad_perm:[2,3,0,1] row_mask:0xf bank_mask:0xf
	s_nop 1
	v_add_f32_dpp v186, v186, v186 row_half_mirror row_mask:0xf bank_mask:0xf
	s_nop 1
	v_add_f32_dpp v186, v186, v186 row_mirror row_mask:0xf bank_mask:0xf
	v_fmamk_f32 v186, v186, 0x3c800000, v173
	v_rsq_f32_e32 v186, v186
	s_nop 0
	v_mul_f32_e32 v187, v178, v186
	v_mul_f32_e32 v188, v179, v186
	v_mul_f32_e32 v189, v180, v186
	v_mul_f32_e32 v190, v181, v186
	v_mul_f32_e32 v182, v94, v187
	v_mul_f32_e32 v183, v90, v188
	v_mul_f32_e32 v184, v86, v189
	v_mul_f32_e32 v185, v82, v190
	v_mul_f32_e32 v186, v175, v183
	v_mul_f32_e32 v187, v176, v183
	v_fma_f32 v188, v176, v182, -v186
	v_fma_f32 v189, v175, v182, v187
	v_mul_f32_e32 v186, v220, v185
	v_mul_f32_e32 v187, v246, v185
	v_fma_f32 v190, v246, v184, -v186
	v_fma_f32 v191, v220, v184, v187
	v_cvt_pk_bf16_f32 v192, v188, v189
	v_cvt_pk_bf16_f32 v193, v190, v191
	ds_write_b16 v170, v192 offset:4608
	ds_write_b16_d16_hi v170, v192 offset:4640
	ds_write_b16 v170, v193 offset:4672
	ds_write_b16_d16_hi v170, v193 offset:4704
	v_mul_f32_e32 v182, v95, v95
	v_mul_f32_e32 v183, v91, v91
	v_mul_f32_e32 v184, v87, v87
	v_mul_f32_e32 v185, v83, v83
	v_add_f32_e32 v186, v182, v183
	v_add_f32_e32 v186, v186, v184
	v_add_f32_e32 v186, v186, v185
	s_nop 1
	v_add_f32_dpp v186, v186, v186 quad_perm:[1,0,3,2] row_mask:0xf bank_mask:0xf
	s_nop 1
	v_add_f32_dpp v186, v186, v186 quad_perm:[2,3,0,1] row_mask:0xf bank_mask:0xf
	s_nop 1
	v_add_f32_dpp v186, v186, v186 row_half_mirror row_mask:0xf bank_mask:0xf
	s_nop 1
	v_add_f32_dpp v186, v186, v186 row_mirror row_mask:0xf bank_mask:0xf
	v_fmamk_f32 v186, v186, 0x3c800000, v173
	v_rsq_f32_e32 v186, v186
	s_nop 0
	v_mul_f32_e32 v187, v178, v186
	v_mul_f32_e32 v188, v179, v186
	v_mul_f32_e32 v189, v180, v186
	v_mul_f32_e32 v190, v181, v186
	v_mul_f32_e32 v182, v95, v187
	v_mul_f32_e32 v183, v91, v188
	v_mul_f32_e32 v184, v87, v189
	v_mul_f32_e32 v185, v83, v190
	v_mul_f32_e32 v186, v175, v183
	v_mul_f32_e32 v187, v176, v183
	v_fma_f32 v188, v176, v182, -v186
	v_fma_f32 v189, v175, v182, v187
	v_mul_f32_e32 v186, v221, v185
	v_mul_f32_e32 v187, v247, v185
	v_fma_f32 v190, v247, v184, -v186
	v_fma_f32 v191, v221, v184, v187
	v_cvt_pk_bf16_f32 v192, v188, v189
	v_cvt_pk_bf16_f32 v193, v190, v191
	ds_write_b16 v170, v192 offset:4752
	ds_write_b16_d16_hi v170, v192 offset:4784
	ds_write_b16 v170, v193 offset:4816
	ds_write_b16_d16_hi v170, v193 offset:4848
	v_mul_f32_e32 v182, v96, v96
	v_mul_f32_e32 v183, v92, v92
	v_mul_f32_e32 v184, v88, v88
	v_mul_f32_e32 v185, v84, v84
	v_add_f32_e32 v186, v182, v183
	v_add_f32_e32 v186, v186, v184
	v_add_f32_e32 v186, v186, v185
	s_nop 1
	v_add_f32_dpp v186, v186, v186 quad_perm:[1,0,3,2] row_mask:0xf bank_mask:0xf
	s_nop 1
	v_add_f32_dpp v186, v186, v186 quad_perm:[2,3,0,1] row_mask:0xf bank_mask:0xf
	s_nop 1
	v_add_f32_dpp v186, v186, v186 row_half_mirror row_mask:0xf bank_mask:0xf
	s_nop 1
	v_add_f32_dpp v186, v186, v186 row_mirror row_mask:0xf bank_mask:0xf
	v_fmamk_f32 v186, v186, 0x3c800000, v173
	v_rsq_f32_e32 v186, v186
	s_nop 0
	v_mul_f32_e32 v187, v178, v186
	v_mul_f32_e32 v188, v179, v186
	v_mul_f32_e32 v189, v180, v186
	v_mul_f32_e32 v190, v181, v186
	v_mul_f32_e32 v182, v96, v187
	v_mul_f32_e32 v183, v92, v188
	v_mul_f32_e32 v184, v88, v189
	v_mul_f32_e32 v185, v84, v190
	v_mul_f32_e32 v186, v175, v183
	v_mul_f32_e32 v187, v176, v183
	v_fma_f32 v188, v176, v182, -v186
	v_fma_f32 v189, v175, v182, v187
	v_mul_f32_e32 v186, v222, v185
	v_mul_f32_e32 v187, v248, v185
	v_fma_f32 v190, v248, v184, -v186
	v_fma_f32 v191, v222, v184, v187
	v_cvt_pk_bf16_f32 v192, v188, v189
	v_cvt_pk_bf16_f32 v193, v190, v191
	ds_write_b16 v170, v192 offset:4896
	ds_write_b16_d16_hi v170, v192 offset:4928
	ds_write_b16 v170, v193 offset:4960
	ds_write_b16_d16_hi v170, v193 offset:4992
	v_mul_f32_e32 v182, v97, v97
	v_mul_f32_e32 v183, v93, v93
	v_mul_f32_e32 v184, v89, v89
	v_mul_f32_e32 v185, v85, v85
	v_add_f32_e32 v186, v182, v183
	v_add_f32_e32 v186, v186, v184
	v_add_f32_e32 v186, v186, v185
	s_nop 1
	v_add_f32_dpp v186, v186, v186 quad_perm:[1,0,3,2] row_mask:0xf bank_mask:0xf
	s_nop 1
	v_add_f32_dpp v186, v186, v186 quad_perm:[2,3,0,1] row_mask:0xf bank_mask:0xf
	s_nop 1
	v_add_f32_dpp v186, v186, v186 row_half_mirror row_mask:0xf bank_mask:0xf
	s_nop 1
	v_add_f32_dpp v186, v186, v186 row_mirror row_mask:0xf bank_mask:0xf
	v_fmamk_f32 v186, v186, 0x3c800000, v173
	v_rsq_f32_e32 v186, v186
	s_nop 0
	v_mul_f32_e32 v187, v178, v186
	v_mul_f32_e32 v188, v179, v186
	v_mul_f32_e32 v189, v180, v186
	v_mul_f32_e32 v190, v181, v186
	v_mul_f32_e32 v182, v97, v187
	v_mul_f32_e32 v183, v93, v188
	v_mul_f32_e32 v184, v89, v189
	v_mul_f32_e32 v185, v85, v190
	v_mul_f32_e32 v186, v175, v183
	v_mul_f32_e32 v187, v176, v183
	v_fma_f32 v188, v176, v182, -v186
	v_fma_f32 v189, v175, v182, v187
	v_mul_f32_e32 v186, v223, v185
	v_mul_f32_e32 v187, v249, v185
	v_fma_f32 v190, v249, v184, -v186
	v_fma_f32 v191, v223, v184, v187
	v_cvt_pk_bf16_f32 v192, v188, v189
	v_cvt_pk_bf16_f32 v193, v190, v191
	ds_write_b16 v170, v192 offset:5040
	ds_write_b16_d16_hi v170, v192 offset:5072
	ds_write_b16 v170, v193 offset:5104
; template <int EPI>
; DI void gemm_phase(const P& p, int l, const u16* __restrict__ A, const u16* __restrict__ Bt, int mpx, char* lds) {
;     ...
;           } else if (tr == 3) {
;             if (donorm) {
;               float ss = v0 * v0 + v1 * v1 + v2 * v2 + v3 * v3;
;               ss += __shfl_xor(ss, 1);
;               ss += __shfl_xor(ss, 2);
;               ss += __shfl_xor(ss, 4);
;               ss += __shfl_xor(ss, 8);
;               const float inv = rsqrtf(ss * (1.f / 64.f) + 1e-6f);
;               v0 *= inv * gv0; v1 *= inv * gv1; v2 *= inv * gv2; v3 *= inv * gv3;
;             }
;             if (dorope) {
;               float sr, cr, sc, cc;
;               sincos_rev((float)(s >> 6) * invf64, sr, cr);
;               sincos_rev((float)(s & 63) * invf64, sc, cc);
;               const float a1 = v0, a2 = v1, b1 = v2, b2 = v3;
;               v0 = a1 * cr - a2 * sr;
;               v1 = a2 * cr + a1 * sr;
;               v2 = b1 * cc - b2 * sc;
;               v3 = b2 * cc + b1 * sc;
;             }
;     ...
;       u16* dh = (kind == 1) ? dst + hf * 64 : dst + (size_t)(hf * 64) * rstride;
; #pragma unroll
;       for (int i = 0; i < 8; ++i) {
;         const int c = lane + i * 64;
;         const int row = c >> 3, cc = c & 7;
;         uint4 v = *(const uint4*)&Tl[row * 72 + cc * 8];
;         *(uint4*)(dh + (size_t)row * rstride + cc * 8) = v;
;       }
	ds_write_b16_d16_hi v170, v193 offset:5136
	v_mul_f32_e32 v182, v78, v78
	v_mul_f32_e32 v183, v74, v74
	v_mul_f32_e32 v184, v70, v70
	v_mul_f32_e32 v185, v66, v66
	v_add_f32_e32 v186, v182, v183
	v_add_f32_e32 v186, v186, v184
	v_add_f32_e32 v186, v186, v185
	s_nop 1
	v_add_f32_dpp v186, v186, v186 quad_perm:[1,0,3,2] row_mask:0xf bank_mask:0xf
	s_nop 1
	v_add_f32_dpp v186, v186, v186 quad_perm:[2,3,0,1] row_mask:0xf bank_mask:0xf
	s_nop 1
	v_add_f32_dpp v186, v186, v186 row_half_mirror row_mask:0xf bank_mask:0xf
	s_nop 1
	v_add_f32_dpp v186, v186, v186 row_mirror row_mask:0xf bank_mask:0xf
	v_fmamk_f32 v186, v186, 0x3c800000, v173
	v_rsq_f32_e32 v186, v186
	s_nop 0
	v_mul_f32_e32 v187, v178, v186
	v_mul_f32_e32 v188, v179, v186
	v_mul_f32_e32 v189, v180, v186
	v_mul_f32_e32 v190, v181, v186
	v_mul_f32_e32 v182, v78, v187
	v_mul_f32_e32 v183, v74, v188
	v_mul_f32_e32 v184, v70, v189
	v_mul_f32_e32 v185, v66, v190
	v_mul_f32_e32 v186, v175, v183
	v_mul_f32_e32 v187, v176, v183
	v_fma_f32 v188, v176, v182, -v186
	v_fma_f32 v189, v175, v182, v187
	v_mul_f32_e32 v186, v234, v185
	v_mul_f32_e32 v187, v250, v185
	v_fma_f32 v190, v250, v184, -v186
	v_fma_f32 v191, v234, v184, v187
	v_cvt_pk_bf16_f32 v192, v188, v189
	v_cvt_pk_bf16_f32 v193, v190, v191
	ds_write_b16 v170, v192 offset:6912
	ds_write_b16_d16_hi v170, v192 offset:6944
	ds_write_b16 v170, v193 offset:6976
	ds_write_b16_d16_hi v170, v193 offset:7008
	v_mul_f32_e32 v182, v79, v79
	v_mul_f32_e32 v183, v75, v75
	v_mul_f32_e32 v184, v71, v71
	v_mul_f32_e32 v185, v67, v67
	v_add_f32_e32 v186, v182, v183
	v_add_f32_e32 v186, v186, v184
	v_add_f32_e32 v186, v186, v185
	s_nop 1
	v_add_f32_dpp v186, v186, v186 quad_perm:[1,0,3,2] row_mask:0xf bank_mask:0xf
	s_nop 1
	v_add_f32_dpp v186, v186, v186 quad_perm:[2,3,0,1] row_mask:0xf bank_mask:0xf
	s_nop 1
	v_add_f32_dpp v186, v186, v186 row_half_mirror row_mask:0xf bank_mask:0xf
	s_nop 1
	v_add_f32_dpp v186, v186, v186 row_mirror row_mask:0xf bank_mask:0xf
	v_fmamk_f32 v186, v186, 0x3c800000, v173
	v_rsq_f32_e32 v186, v186
	s_nop 0
	v_mul_f32_e32 v187, v178, v186
	v_mul_f32_e32 v188, v179, v186
	v_mul_f32_e32 v189, v180, v186
	v_mul_f32_e32 v190, v181, v186
	v_mul_f32_e32 v182, v79, v187
	v_mul_f32_e32 v183, v75, v188
	v_mul_f32_e32 v184, v71, v189
	v_mul_f32_e32 v185, v67, v190
	v_mul_f32_e32 v186, v175, v183
	v_mul_f32_e32 v187, v176, v183
	v_fma_f32 v188, v176, v182, -v186
	v_fma_f32 v189, v175, v182, v187
	v_mul_f32_e32 v186, v235, v185
	v_mul_f32_e32 v187, v251, v185
	v_fma_f32 v190, v251, v184, -v186
	v_fma_f32 v191, v235, v184, v187
	v_cvt_pk_bf16_f32 v192, v188, v189
	v_cvt_pk_bf16_f32 v193, v190, v191
	ds_write_b16 v170, v192 offset:7056
	ds_write_b16_d16_hi v170, v192 offset:7088
	ds_write_b16 v170, v193 offset:7120
	ds_write_b16_d16_hi v170, v193 offset:7152
	v_mul_f32_e32 v182, v80, v80
	v_mul_f32_e32 v183, v76, v76
	v_mul_f32_e32 v184, v72, v72
	v_mul_f32_e32 v185, v68, v68
	v_add_f32_e32 v186, v182, v183
	v_add_f32_e32 v186, v186, v184
	v_add_f32_e32 v186, v186, v185
	s_nop 1
	v_add_f32_dpp v186, v186, v186 quad_perm:[1,0,3,2] row_mask:0xf bank_mask:0xf
	s_nop 1
	v_add_f32_dpp v186, v186, v186 quad_perm:[2,3,0,1] row_mask:0xf bank_mask:0xf
	s_nop 1
	v_add_f32_dpp v186, v186, v186 row_half_mirror row_mask:0xf bank_mask:0xf
	s_nop 1
	v_add_f32_dpp v186, v186, v186 row_mirror row_mask:0xf bank_mask:0xf
	v_fmamk_f32 v186, v186, 0x3c800000, v173
	v_rsq_f32_e32 v186, v186
	s_nop 0
	v_mul_f32_e32 v187, v178, v186
	v_mul_f32_e32 v188, v179, v186
	v_mul_f32_e32 v189, v180, v186
	v_mul_f32_e32 v190, v181, v186
	v_mul_f32_e32 v182, v80, v187
	v_mul_f32_e32 v183, v76, v188
	v_mul_f32_e32 v184, v72, v189
	v_mul_f32_e32 v185, v68, v190
	v_mul_f32_e32 v186, v175, v183
	v_mul_f32_e32 v187, v176, v183
	v_fma_f32 v188, v176, v182, -v186
	v_fma_f32 v189, v175, v182, v187
	v_mul_f32_e32 v186, v236, v185
	v_mul_f32_e32 v187, v252, v185
	v_fma_f32 v190, v252, v184, -v186
	v_fma_f32 v191, v236, v184, v187
	v_cvt_pk_bf16_f32 v192, v188, v189
	v_cvt_pk_bf16_f32 v193, v190, v191
	ds_write_b16 v170, v192 offset:7200
	ds_write_b16_d16_hi v170, v192 offset:7232
	ds_write_b16 v170, v193 offset:7264
	ds_write_b16_d16_hi v170, v193 offset:7296
	v_mul_f32_e32 v182, v81, v81
	v_mul_f32_e32 v183, v77, v77
	v_mul_f32_e32 v184, v73, v73
	v_mul_f32_e32 v185, v69, v69
	v_add_f32_e32 v186, v182, v183
	v_add_f32_e32 v186, v186, v184
	v_add_f32_e32 v186, v186, v185
	s_nop 1
	v_add_f32_dpp v186, v186, v186 quad_perm:[1,0,3,2] row_mask:0xf bank_mask:0xf
	s_nop 1
	v_add_f32_dpp v186, v186, v186 quad_perm:[2,3,0,1] row_mask:0xf bank_mask:0xf
	s_nop 1
	v_add_f32_dpp v186, v186, v186 row_half_mirror row_mask:0xf bank_mask:0xf
	s_nop 1
	v_add_f32_dpp v186, v186, v186 row_mirror row_mask:0xf bank_mask:0xf
	v_fmamk_f32 v186, v186, 0x3c800000, v173
	v_rsq_f32_e32 v186, v186
	s_nop 0
	v_mul_f32_e32 v187, v178, v186
	v_mul_f32_e32 v188, v179, v186
	v_mul_f32_e32 v189, v180, v186
	v_mul_f32_e32 v190, v181, v186
	v_mul_f32_e32 v182, v81, v187
	v_mul_f32_e32 v183, v77, v188
	v_mul_f32_e32 v184, v73, v189
	v_mul_f32_e32 v185, v69, v190
	v_mul_f32_e32 v186, v175, v183
	v_mul_f32_e32 v187, v176, v183
	v_fma_f32 v188, v176, v182, -v186
	v_fma_f32 v189, v175, v182, v187
	v_mul_f32_e32 v186, v237, v185
	v_mul_f32_e32 v187, v253, v185
	v_fma_f32 v190, v253, v184, -v186
	v_fma_f32 v191, v237, v184, v187
	v_cvt_pk_bf16_f32 v192, v188, v189
	v_cvt_pk_bf16_f32 v193, v190, v191
	ds_write_b16 v170, v192 offset:7344
	ds_write_b16_d16_hi v170, v192 offset:7376
	ds_write_b16 v170, v193 offset:7408
	ds_write_b16_d16_hi v170, v193 offset:7440
	ds_read_b128 v[130:133], v171 offset:0
	ds_read_b128 v[134:137], v171 offset:1152
	ds_read_b128 v[138:141], v171 offset:2304
	ds_read_b128 v[142:145], v171 offset:3456
	ds_read_b128 v[146:149], v171 offset:4608
	ds_read_b128 v[150:153], v171 offset:5760
	ds_read_b128 v[154:157], v171 offset:6912
	ds_read_b128 v[158:161], v171 offset:8064
	s_waitcnt lgkmcnt(7)
; template <int EPI>
; DI void gemm_phase(const P& p, int l, const u16* __restrict__ A, const u16* __restrict__ Bt, int mpx, char* lds) {
;     ...
;             if (dorope) {
;               float sr, cr, sc, cc;
;               sincos_rev((float)(s >> 6) * invf64, sr, cr);
;               sincos_rev((float)(s & 63) * invf64, sc, cc);
;     ...
;       u16* dh = (kind == 1) ? dst + hf * 64 : dst + (size_t)(hf * 64) * rstride;
; #pragma unroll
;       for (int i = 0; i < 8; ++i) {
;         const int c = lane + i * 64;
;         const int row = c >> 3, cc = c & 7;
;         uint4 v = *(const uint4*)&Tl[row * 72 + cc * 8];
;         *(uint4*)(dh + (size_t)row * rstride + cc * 8) = v;
;       }
	global_store_dwordx4 v172, v[130:133], s[44:45] offset:0
	s_waitcnt lgkmcnt(6)
	global_store_dwordx4 v172, v[134:137], s[44:45] offset:1024
	s_waitcnt lgkmcnt(5)
	global_store_dwordx4 v172, v[138:141], s[44:45] offset:2048
	s_waitcnt lgkmcnt(4)
	global_store_dwordx4 v172, v[142:145], s[44:45] offset:3072
	s_waitcnt lgkmcnt(3)
	global_store_dwordx4 v172, v[146:149], s[62:63] offset:0
	s_waitcnt lgkmcnt(2)
	global_store_dwordx4 v172, v[150:153], s[62:63] offset:1024
	s_waitcnt lgkmcnt(1)
	global_store_dwordx4 v172, v[154:157], s[62:63] offset:2048
	s_waitcnt lgkmcnt(0)
	global_store_dwordx4 v172, v[158:161], s[62:63] offset:3072
	s_add_u32 s44, s44, 0x2000
	s_addc_u32 s45, s45, 0
	s_add_u32 s62, s62, 0x2000
	s_addc_u32 s63, s63, 0
	s_lshr_b32 s70, s69, 6
	s_add_i32 s70, s70, 1
	v_cvt_f32_i32_e32 v182, s70
	v_mul_f32_e32 v182, v174, v182
	v_mul_f32_e32 v183, 0.15915494, v182
	v_rndne_f32_e32 v183, v183
	v_fma_f32 v183, v182, 0.15915494, -v183
	v_sin_f32_e32 v175, v183
	v_cos_f32_e32 v176, v183
	v_mul_f32_e32 v182, v62, v62
	v_mul_f32_e32 v183, v58, v58
	v_mul_f32_e32 v184, v54, v54
	v_mul_f32_e32 v185, v50, v50
	v_add_f32_e32 v186, v182, v183
	v_add_f32_e32 v186, v186, v184
	v_add_f32_e32 v186, v186, v185
	s_nop 1
	v_add_f32_dpp v186, v186, v186 quad_perm:[1,0,3,2] row_mask:0xf bank_mask:0xf
	s_nop 1
	v_add_f32_dpp v186, v186, v186 quad_perm:[2,3,0,1] row_mask:0xf bank_mask:0xf
	s_nop 1
	v_add_f32_dpp v186, v186, v186 row_half_mirror row_mask:0xf bank_mask:0xf
	s_nop 1
	v_add_f32_dpp v186, v186, v186 row_mirror row_mask:0xf bank_mask:0xf
	v_fmamk_f32 v186, v186, 0x3c800000, v173
	v_rsq_f32_e32 v186, v186
	s_nop 0
	v_mul_f32_e32 v187, v178, v186
	v_mul_f32_e32 v188, v179, v186
	v_mul_f32_e32 v189, v180, v186
	v_mul_f32_e32 v190, v181, v186
	v_mul_f32_e32 v182, v62, v187
	v_mul_f32_e32 v183, v58, v188
	v_mul_f32_e32 v184, v54, v189
	v_mul_f32_e32 v185, v50, v190
	v_mul_f32_e32 v186, v175, v183
	v_mul_f32_e32 v187, v176, v183
	v_fma_f32 v188, v176, v182, -v186
	v_fma_f32 v189, v175, v182, v187
	v_mul_f32_e32 v186, v212, v185
	v_mul_f32_e32 v187, v238, v185
	v_fma_f32 v190, v238, v184, -v186
	v_fma_f32 v191, v212, v184, v187
	v_cvt_pk_bf16_f32 v192, v188, v189
	v_cvt_pk_bf16_f32 v193, v190, v191
	ds_write_b16 v170, v192 offset:0
	ds_write_b16_d16_hi v170, v192 offset:32
	ds_write_b16 v170, v193 offset:64
	ds_write_b16_d16_hi v170, v193 offset:96
	v_mul_f32_e32 v182, v63, v63
	v_mul_f32_e32 v183, v59, v59
	v_mul_f32_e32 v184, v55, v55
	v_mul_f32_e32 v185, v51, v51
	v_add_f32_e32 v186, v182, v183
	v_add_f32_e32 v186, v186, v184
	v_add_f32_e32 v186, v186, v185
	s_nop 1
	v_add_f32_dpp v186, v186, v186 quad_perm:[1,0,3,2] row_mask:0xf bank_mask:0xf
	s_nop 1
	v_add_f32_dpp v186, v186, v186 quad_perm:[2,3,0,1] row_mask:0xf bank_mask:0xf
	s_nop 1
	v_add_f32_dpp v186, v186, v186 row_half_mirror row_mask:0xf bank_mask:0xf
	s_nop 1
	v_add_f32_dpp v186, v186, v186 row_mirror row_mask:0xf bank_mask:0xf
	v_fmamk_f32 v186, v186, 0x3c800000, v173
	v_rsq_f32_e32 v186, v186
	s_nop 0
	v_mul_f32_e32 v187, v178, v186
	v_mul_f32_e32 v188, v179, v186
	v_mul_f32_e32 v189, v180, v186
	v_mul_f32_e32 v190, v181, v186
	v_mul_f32_e32 v182, v63, v187
	v_mul_f32_e32 v183, v59, v188
	v_mul_f32_e32 v184, v55, v189
	v_mul_f32_e32 v185, v51, v190
	v_mul_f32_e32 v186, v175, v183
	v_mul_f32_e32 v187, v176, v183
	v_fma_f32 v188, v176, v182, -v186
	v_fma_f32 v189, v175, v182, v187
	v_mul_f32_e32 v186, v213, v185
	v_mul_f32_e32 v187, v239, v185
	v_fma_f32 v190, v239, v184, -v186
	v_fma_f32 v191, v213, v184, v187
	v_cvt_pk_bf16_f32 v192, v188, v189
	v_cvt_pk_bf16_f32 v193, v190, v191
	ds_write_b16 v170, v192 offset:144
	ds_write_b16_d16_hi v170, v192 offset:176
	ds_write_b16 v170, v193 offset:208
	ds_write_b16_d16_hi v170, v193 offset:240
	v_mul_f32_e32 v182, v64, v64
	v_mul_f32_e32 v183, v60, v60
	v_mul_f32_e32 v184, v56, v56
	v_mul_f32_e32 v185, v52, v52
	v_add_f32_e32 v186, v182, v183
	v_add_f32_e32 v186, v186, v184
	v_add_f32_e32 v186, v186, v185
	s_nop 1
	v_add_f32_dpp v186, v186, v186 quad_perm:[1,0,3,2] row_mask:0xf bank_mask:0xf
	s_nop 1
	v_add_f32_dpp v186, v186, v186 quad_perm:[2,3,0,1] row_mask:0xf bank_mask:0xf
	s_nop 1
	v_add_f32_dpp v186, v186, v186 row_half_mirror row_mask:0xf bank_mask:0xf
	s_nop 1
	v_add_f32_dpp v186, v186, v186 row_mirror row_mask:0xf bank_mask:0xf
	v_fmamk_f32 v186, v186, 0x3c800000, v173
	v_rsq_f32_e32 v186, v186
	s_nop 0
	v_mul_f32_e32 v187, v178, v186
	v_mul_f32_e32 v188, v179, v186
	v_mul_f32_e32 v189, v180, v186
	v_mul_f32_e32 v190, v181, v186
	v_mul_f32_e32 v182, v64, v187
	v_mul_f32_e32 v183, v60, v188
	v_mul_f32_e32 v184, v56, v189
	v_mul_f32_e32 v185, v52, v190
	v_mul_f32_e32 v186, v175, v183
	v_mul_f32_e32 v187, v176, v183
	v_fma_f32 v188, v176, v182, -v186
	v_fma_f32 v189, v175, v182, v187
	v_mul_f32_e32 v186, v214, v185
	v_mul_f32_e32 v187, v240, v185
	v_fma_f32 v190, v240, v184, -v186
	v_fma_f32 v191, v214, v184, v187
	v_cvt_pk_bf16_f32 v192, v188, v189
	v_cvt_pk_bf16_f32 v193, v190, v191
	ds_write_b16 v170, v192 offset:288
	ds_write_b16_d16_hi v170, v192 offset:320
	ds_write_b16 v170, v193 offset:352
	ds_write_b16_d16_hi v170, v193 offset:384
	v_mul_f32_e32 v182, v65, v65
	v_mul_f32_e32 v183, v61, v61
	v_mul_f32_e32 v184, v57, v57
	v_mul_f32_e32 v185, v53, v53
	v_add_f32_e32 v186, v182, v183
	v_add_f32_e32 v186, v186, v184
	v_add_f32_e32 v186, v186, v185
	s_nop 1
	v_add_f32_dpp v186, v186, v186 quad_perm:[1,0,3,2] row_mask:0xf bank_mask:0xf
	s_nop 1
	v_add_f32_dpp v186, v186, v186 quad_perm:[2,3,0,1] row_mask:0xf bank_mask:0xf
	s_nop 1
	v_add_f32_dpp v186, v186, v186 row_half_mirror row_mask:0xf bank_mask:0xf
	s_nop 1
; template <int EPI>
; DI void gemm_phase(const P& p, int l, const u16* __restrict__ A, const u16* __restrict__ Bt, int mpx, char* lds) {
;     ...
;           } else if (tr == 3) {
;             if (donorm) {
;               float ss = v0 * v0 + v1 * v1 + v2 * v2 + v3 * v3;
;               ss += __shfl_xor(ss, 1);
;               ss += __shfl_xor(ss, 2);
;               ss += __shfl_xor(ss, 4);
;               ss += __shfl_xor(ss, 8);
;               const float inv = rsqrtf(ss * (1.f / 64.f) + 1e-6f);
;               v0 *= inv * gv0; v1 *= inv * gv1; v2 *= inv * gv2; v3 *= inv * gv3;
;             }
;             if (dorope) {
;               float sr, cr, sc, cc;
;               sincos_rev((float)(s >> 6) * invf64, sr, cr);
;               sincos_rev((float)(s & 63) * invf64, sc, cc);
;               const float a1 = v0, a2 = v1, b1 = v2, b2 = v3;
;               v0 = a1 * cr - a2 * sr;
;               v1 = a2 * cr + a1 * sr;
;               v2 = b1 * cc - b2 * sc;
;               v3 = b2 * cc + b1 * sc;
;             }
;     ...
;           } else {
;             Tl[rowl * 72 + 0 * 16 + r] = (u16)u01;
;             Tl[rowl * 72 + 1 * 16 + r] = (u16)(u01 >> 16);
;             Tl[rowl * 72 + 2 * 16 + r] = (u16)u23;
;             Tl[rowl * 72 + 3 * 16 + r] = (u16)(u23 >> 16);
	v_add_f32_dpp v186, v186, v186 row_mirror row_mask:0xf bank_mask:0xf
	v_fmamk_f32 v186, v186, 0x3c800000, v173
	v_rsq_f32_e32 v186, v186
	s_nop 0
	v_mul_f32_e32 v187, v178, v186
	v_mul_f32_e32 v188, v179, v186
	v_mul_f32_e32 v189, v180, v186
	v_mul_f32_e32 v190, v181, v186
	v_mul_f32_e32 v182, v65, v187
	v_mul_f32_e32 v183, v61, v188
	v_mul_f32_e32 v184, v57, v189
	v_mul_f32_e32 v185, v53, v190
	v_mul_f32_e32 v186, v175, v183
	v_mul_f32_e32 v187, v176, v183
	v_fma_f32 v188, v176, v182, -v186
	v_fma_f32 v189, v175, v182, v187
	v_mul_f32_e32 v186, v215, v185
	v_mul_f32_e32 v187, v241, v185
	v_fma_f32 v190, v241, v184, -v186
	v_fma_f32 v191, v215, v184, v187
	v_cvt_pk_bf16_f32 v192, v188, v189
	v_cvt_pk_bf16_f32 v193, v190, v191
	ds_write_b16 v170, v192 offset:432
	ds_write_b16_d16_hi v170, v192 offset:464
	ds_write_b16 v170, v193 offset:496
	ds_write_b16_d16_hi v170, v193 offset:528
	v_mul_f32_e32 v182, v46, v46
	v_mul_f32_e32 v183, v42, v42
	v_mul_f32_e32 v184, v38, v38
	v_mul_f32_e32 v185, v34, v34
	v_add_f32_e32 v186, v182, v183
	v_add_f32_e32 v186, v186, v184
	v_add_f32_e32 v186, v186, v185
	s_nop 1
	v_add_f32_dpp v186, v186, v186 quad_perm:[1,0,3,2] row_mask:0xf bank_mask:0xf
	s_nop 1
	v_add_f32_dpp v186, v186, v186 quad_perm:[2,3,0,1] row_mask:0xf bank_mask:0xf
	s_nop 1
	v_add_f32_dpp v186, v186, v186 row_half_mirror row_mask:0xf bank_mask:0xf
	s_nop 1
	v_add_f32_dpp v186, v186, v186 row_mirror row_mask:0xf bank_mask:0xf
	v_fmamk_f32 v186, v186, 0x3c800000, v173
	v_rsq_f32_e32 v186, v186
	s_nop 0
	v_mul_f32_e32 v187, v178, v186
	v_mul_f32_e32 v188, v179, v186
	v_mul_f32_e32 v189, v180, v186
	v_mul_f32_e32 v190, v181, v186
	v_mul_f32_e32 v182, v46, v187
	v_mul_f32_e32 v183, v42, v188
	v_mul_f32_e32 v184, v38, v189
	v_mul_f32_e32 v185, v34, v190
	v_mul_f32_e32 v186, v175, v183
	v_mul_f32_e32 v187, v176, v183
	v_fma_f32 v188, v176, v182, -v186
	v_fma_f32 v189, v175, v182, v187
	v_mul_f32_e32 v186, v216, v185
	v_mul_f32_e32 v187, v242, v185
	v_fma_f32 v190, v242, v184, -v186
	v_fma_f32 v191, v216, v184, v187
	v_cvt_pk_bf16_f32 v192, v188, v189
	v_cvt_pk_bf16_f32 v193, v190, v191
	ds_write_b16 v170, v192 offset:2304
	ds_write_b16_d16_hi v170, v192 offset:2336
	ds_write_b16 v170, v193 offset:2368
	ds_write_b16_d16_hi v170, v193 offset:2400
	v_mul_f32_e32 v182, v47, v47
	v_mul_f32_e32 v183, v43, v43
	v_mul_f32_e32 v184, v39, v39
	v_mul_f32_e32 v185, v35, v35
	v_add_f32_e32 v186, v182, v183
	v_add_f32_e32 v186, v186, v184
	v_add_f32_e32 v186, v186, v185
	s_nop 1
	v_add_f32_dpp v186, v186, v186 quad_perm:[1,0,3,2] row_mask:0xf bank_mask:0xf
	s_nop 1
	v_add_f32_dpp v186, v186, v186 quad_perm:[2,3,0,1] row_mask:0xf bank_mask:0xf
	s_nop 1
	v_add_f32_dpp v186, v186, v186 row_half_mirror row_mask:0xf bank_mask:0xf
	s_nop 1
	v_add_f32_dpp v186, v186, v186 row_mirror row_mask:0xf bank_mask:0xf
	v_fmamk_f32 v186, v186, 0x3c800000, v173
	v_rsq_f32_e32 v186, v186
	s_nop 0
	v_mul_f32_e32 v187, v178, v186
	v_mul_f32_e32 v188, v179, v186
	v_mul_f32_e32 v189, v180, v186
	v_mul_f32_e32 v190, v181, v186
	v_mul_f32_e32 v182, v47, v187
	v_mul_f32_e32 v183, v43, v188
	v_mul_f32_e32 v184, v39, v189
	v_mul_f32_e32 v185, v35, v190
	v_mul_f32_e32 v186, v175, v183
	v_mul_f32_e32 v187, v176, v183
	v_fma_f32 v188, v176, v182, -v186
	v_fma_f32 v189, v175, v182, v187
	v_mul_f32_e32 v186, v217, v185
	v_mul_f32_e32 v187, v243, v185
	v_fma_f32 v190, v243, v184, -v186
	v_fma_f32 v191, v217, v184, v187
	v_cvt_pk_bf16_f32 v192, v188, v189
	v_cvt_pk_bf16_f32 v193, v190, v191
	ds_write_b16 v170, v192 offset:2448
	ds_write_b16_d16_hi v170, v192 offset:2480
	ds_write_b16 v170, v193 offset:2512
	ds_write_b16_d16_hi v170, v193 offset:2544
	v_mul_f32_e32 v182, v48, v48
	v_mul_f32_e32 v183, v44, v44
	v_mul_f32_e32 v184, v40, v40
	v_mul_f32_e32 v185, v36, v36
	v_add_f32_e32 v186, v182, v183
	v_add_f32_e32 v186, v186, v184
	v_add_f32_e32 v186, v186, v185
	s_nop 1
	v_add_f32_dpp v186, v186, v186 quad_perm:[1,0,3,2] row_mask:0xf bank_mask:0xf
	s_nop 1
	v_add_f32_dpp v186, v186, v186 quad_perm:[2,3,0,1] row_mask:0xf bank_mask:0xf
	s_nop 1
	v_add_f32_dpp v186, v186, v186 row_half_mirror row_mask:0xf bank_mask:0xf
	s_nop 1
	v_add_f32_dpp v186, v186, v186 row_mirror row_mask:0xf bank_mask:0xf
	v_fmamk_f32 v186, v186, 0x3c800000, v173
	v_rsq_f32_e32 v186, v186
	s_nop 0
	v_mul_f32_e32 v187, v178, v186
	v_mul_f32_e32 v188, v179, v186
	v_mul_f32_e32 v189, v180, v186
	v_mul_f32_e32 v190, v181, v186
	v_mul_f32_e32 v182, v48, v187
	v_mul_f32_e32 v183, v44, v188
	v_mul_f32_e32 v184, v40, v189
	v_mul_f32_e32 v185, v36, v190
	v_mul_f32_e32 v186, v175, v183
	v_mul_f32_e32 v187, v176, v183
	v_fma_f32 v188, v176, v182, -v186
	v_fma_f32 v189, v175, v182, v187
	v_mul_f32_e32 v186, v218, v185
	v_mul_f32_e32 v187, v244, v185
	v_fma_f32 v190, v244, v184, -v186
	v_fma_f32 v191, v218, v184, v187
	v_cvt_pk_bf16_f32 v192, v188, v189
	v_cvt_pk_bf16_f32 v193, v190, v191
	ds_write_b16 v170, v192 offset:2592
	ds_write_b16_d16_hi v170, v192 offset:2624
	ds_write_b16 v170, v193 offset:2656
	ds_write_b16_d16_hi v170, v193 offset:2688
	v_mul_f32_e32 v182, v49, v49
	v_mul_f32_e32 v183, v45, v45
	v_mul_f32_e32 v184, v41, v41
	v_mul_f32_e32 v185, v37, v37
	v_add_f32_e32 v186, v182, v183
	v_add_f32_e32 v186, v186, v184
	v_add_f32_e32 v186, v186, v185
	s_nop 1
	v_add_f32_dpp v186, v186, v186 quad_perm:[1,0,3,2] row_mask:0xf bank_mask:0xf
	s_nop 1
	v_add_f32_dpp v186, v186, v186 quad_perm:[2,3,0,1] row_mask:0xf bank_mask:0xf
	s_nop 1
	v_add_f32_dpp v186, v186, v186 row_half_mirror row_mask:0xf bank_mask:0xf
	s_nop 1
	v_add_f32_dpp v186, v186, v186 row_mirror row_mask:0xf bank_mask:0xf
	v_fmamk_f32 v186, v186, 0x3c800000, v173
; template <int EPI>
; DI void gemm_phase(const P& p, int l, const u16* __restrict__ A, const u16* __restrict__ Bt, int mpx, char* lds) {
;     ...
;           } else if (tr == 3) {
;             if (donorm) {
;               float ss = v0 * v0 + v1 * v1 + v2 * v2 + v3 * v3;
;               ss += __shfl_xor(ss, 1);
;               ss += __shfl_xor(ss, 2);
;               ss += __shfl_xor(ss, 4);
;               ss += __shfl_xor(ss, 8);
;               const float inv = rsqrtf(ss * (1.f / 64.f) + 1e-6f);
;               v0 *= inv * gv0; v1 *= inv * gv1; v2 *= inv * gv2; v3 *= inv * gv3;
;             }
;             if (dorope) {
;               float sr, cr, sc, cc;
;               sincos_rev((float)(s >> 6) * invf64, sr, cr);
;               sincos_rev((float)(s & 63) * invf64, sc, cc);
;               const float a1 = v0, a2 = v1, b1 = v2, b2 = v3;
;               v0 = a1 * cr - a2 * sr;
;               v1 = a2 * cr + a1 * sr;
;               v2 = b1 * cc - b2 * sc;
;               v3 = b2 * cc + b1 * sc;
;             }
;     ...
;           } else {
;             Tl[rowl * 72 + 0 * 16 + r] = (u16)u01;
;             Tl[rowl * 72 + 1 * 16 + r] = (u16)(u01 >> 16);
;             Tl[rowl * 72 + 2 * 16 + r] = (u16)u23;
;             Tl[rowl * 72 + 3 * 16 + r] = (u16)(u23 >> 16);
	v_rsq_f32_e32 v186, v186
	s_nop 0
	v_mul_f32_e32 v187, v178, v186
	v_mul_f32_e32 v188, v179, v186
	v_mul_f32_e32 v189, v180, v186
	v_mul_f32_e32 v190, v181, v186
	v_mul_f32_e32 v182, v49, v187
	v_mul_f32_e32 v183, v45, v188
	v_mul_f32_e32 v184, v41, v189
	v_mul_f32_e32 v185, v37, v190
	v_mul_f32_e32 v186, v175, v183
	v_mul_f32_e32 v187, v176, v183
	v_fma_f32 v188, v176, v182, -v186
	v_fma_f32 v189, v175, v182, v187
	v_mul_f32_e32 v186, v219, v185
	v_mul_f32_e32 v187, v245, v185
	v_fma_f32 v190, v245, v184, -v186
	v_fma_f32 v191, v219, v184, v187
	v_cvt_pk_bf16_f32 v192, v188, v189
	v_cvt_pk_bf16_f32 v193, v190, v191
	ds_write_b16 v170, v192 offset:2736
	ds_write_b16_d16_hi v170, v192 offset:2768
	ds_write_b16 v170, v193 offset:2800
	ds_write_b16_d16_hi v170, v193 offset:2832
	v_mul_f32_e32 v182, v30, v30
	v_mul_f32_e32 v183, v26, v26
	v_mul_f32_e32 v184, v22, v22
	v_mul_f32_e32 v185, v18, v18
	v_add_f32_e32 v186, v182, v183
	v_add_f32_e32 v186, v186, v184
	v_add_f32_e32 v186, v186, v185
	s_nop 1
	v_add_f32_dpp v186, v186, v186 quad_perm:[1,0,3,2] row_mask:0xf bank_mask:0xf
	s_nop 1
	v_add_f32_dpp v186, v186, v186 quad_perm:[2,3,0,1] row_mask:0xf bank_mask:0xf
	s_nop 1
	v_add_f32_dpp v186, v186, v186 row_half_mirror row_mask:0xf bank_mask:0xf
	s_nop 1
	v_add_f32_dpp v186, v186, v186 row_mirror row_mask:0xf bank_mask:0xf
	v_fmamk_f32 v186, v186, 0x3c800000, v173
	v_rsq_f32_e32 v186, v186
	s_nop 0
	v_mul_f32_e32 v187, v178, v186
	v_mul_f32_e32 v188, v179, v186
	v_mul_f32_e32 v189, v180, v186
	v_mul_f32_e32 v190, v181, v186
	v_mul_f32_e32 v182, v30, v187
	v_mul_f32_e32 v183, v26, v188
	v_mul_f32_e32 v184, v22, v189
	v_mul_f32_e32 v185, v18, v190
	v_mul_f32_e32 v186, v175, v183
	v_mul_f32_e32 v187, v176, v183
	v_fma_f32 v188, v176, v182, -v186
	v_fma_f32 v189, v175, v182, v187
	v_mul_f32_e32 v186, v220, v185
	v_mul_f32_e32 v187, v246, v185
	v_fma_f32 v190, v246, v184, -v186
	v_fma_f32 v191, v220, v184, v187
	v_cvt_pk_bf16_f32 v192, v188, v189
	v_cvt_pk_bf16_f32 v193, v190, v191
	ds_write_b16 v170, v192 offset:4608
	ds_write_b16_d16_hi v170, v192 offset:4640
	ds_write_b16 v170, v193 offset:4672
	ds_write_b16_d16_hi v170, v193 offset:4704
	v_mul_f32_e32 v182, v31, v31
	v_mul_f32_e32 v183, v27, v27
	v_mul_f32_e32 v184, v23, v23
	v_mul_f32_e32 v185, v19, v19
	v_add_f32_e32 v186, v182, v183
	v_add_f32_e32 v186, v186, v184
	v_add_f32_e32 v186, v186, v185
	s_nop 1
	v_add_f32_dpp v186, v186, v186 quad_perm:[1,0,3,2] row_mask:0xf bank_mask:0xf
	s_nop 1
	v_add_f32_dpp v186, v186, v186 quad_perm:[2,3,0,1] row_mask:0xf bank_mask:0xf
	s_nop 1
	v_add_f32_dpp v186, v186, v186 row_half_mirror row_mask:0xf bank_mask:0xf
	s_nop 1
	v_add_f32_dpp v186, v186, v186 row_mirror row_mask:0xf bank_mask:0xf
	v_fmamk_f32 v186, v186, 0x3c800000, v173
	v_rsq_f32_e32 v186, v186
	s_nop 0
	v_mul_f32_e32 v187, v178, v186
	v_mul_f32_e32 v188, v179, v186
	v_mul_f32_e32 v189, v180, v186
	v_mul_f32_e32 v190, v181, v186
	v_mul_f32_e32 v182, v31, v187
	v_mul_f32_e32 v183, v27, v188
	v_mul_f32_e32 v184, v23, v189
	v_mul_f32_e32 v185, v19, v190
	v_mul_f32_e32 v186, v175, v183
	v_mul_f32_e32 v187, v176, v183
	v_fma_f32 v188, v176, v182, -v186
	v_fma_f32 v189, v175, v182, v187
	v_mul_f32_e32 v186, v221, v185
	v_mul_f32_e32 v187, v247, v185
	v_fma_f32 v190, v247, v184, -v186
	v_fma_f32 v191, v221, v184, v187
	v_cvt_pk_bf16_f32 v192, v188, v189
	v_cvt_pk_bf16_f32 v193, v190, v191
	ds_write_b16 v170, v192 offset:4752
	ds_write_b16_d16_hi v170, v192 offset:4784
	ds_write_b16 v170, v193 offset:4816
	ds_write_b16_d16_hi v170, v193 offset:4848
	v_mul_f32_e32 v182, v32, v32
	v_mul_f32_e32 v183, v28, v28
	v_mul_f32_e32 v184, v24, v24
	v_mul_f32_e32 v185, v20, v20
	v_add_f32_e32 v186, v182, v183
	v_add_f32_e32 v186, v186, v184
	v_add_f32_e32 v186, v186, v185
	s_nop 1
	v_add_f32_dpp v186, v186, v186 quad_perm:[1,0,3,2] row_mask:0xf bank_mask:0xf
	s_nop 1
	v_add_f32_dpp v186, v186, v186 quad_perm:[2,3,0,1] row_mask:0xf bank_mask:0xf
	s_nop 1
	v_add_f32_dpp v186, v186, v186 row_half_mirror row_mask:0xf bank_mask:0xf
	s_nop 1
	v_add_f32_dpp v186, v186, v186 row_mirror row_mask:0xf bank_mask:0xf
	v_fmamk_f32 v186, v186, 0x3c800000, v173
	v_rsq_f32_e32 v186, v186
	s_nop 0
	v_mul_f32_e32 v187, v178, v186
	v_mul_f32_e32 v188, v179, v186
	v_mul_f32_e32 v189, v180, v186
	v_mul_f32_e32 v190, v181, v186
	v_mul_f32_e32 v182, v32, v187
	v_mul_f32_e32 v183, v28, v188
	v_mul_f32_e32 v184, v24, v189
	v_mul_f32_e32 v185, v20, v190
	v_mul_f32_e32 v186, v175, v183
	v_mul_f32_e32 v187, v176, v183
	v_fma_f32 v188, v176, v182, -v186
	v_fma_f32 v189, v175, v182, v187
	v_mul_f32_e32 v186, v222, v185
	v_mul_f32_e32 v187, v248, v185
	v_fma_f32 v190, v248, v184, -v186
	v_fma_f32 v191, v222, v184, v187
	v_cvt_pk_bf16_f32 v192, v188, v189
	v_cvt_pk_bf16_f32 v193, v190, v191
	ds_write_b16 v170, v192 offset:4896
	ds_write_b16_d16_hi v170, v192 offset:4928
	ds_write_b16 v170, v193 offset:4960
	ds_write_b16_d16_hi v170, v193 offset:4992
	v_mul_f32_e32 v182, v33, v33
	v_mul_f32_e32 v183, v29, v29
	v_mul_f32_e32 v184, v25, v25
	v_mul_f32_e32 v185, v21, v21
	v_add_f32_e32 v186, v182, v183
	v_add_f32_e32 v186, v186, v184
	v_add_f32_e32 v186, v186, v185
	s_nop 1
	v_add_f32_dpp v186, v186, v186 quad_perm:[1,0,3,2] row_mask:0xf bank_mask:0xf
	s_nop 1
	v_add_f32_dpp v186, v186, v186 quad_perm:[2,3,0,1] row_mask:0xf bank_mask:0xf
	s_nop 1
	v_add_f32_dpp v186, v186, v186 row_half_mirror row_mask:0xf bank_mask:0xf
	s_nop 1
	v_add_f32_dpp v186, v186, v186 row_mirror row_mask:0xf bank_mask:0xf
	v_fmamk_f32 v186, v186, 0x3c800000, v173
	v_rsq_f32_e32 v186, v186
	s_nop 0
	v_mul_f32_e32 v187, v178, v186
	v_mul_f32_e32 v188, v179, v186
; template <int EPI>
; DI void gemm_phase(const P& p, int l, const u16* __restrict__ A, const u16* __restrict__ Bt, int mpx, char* lds) {
;     ...
;           } else if (tr == 3) {
;             if (donorm) {
;               float ss = v0 * v0 + v1 * v1 + v2 * v2 + v3 * v3;
;               ss += __shfl_xor(ss, 1);
;               ss += __shfl_xor(ss, 2);
;               ss += __shfl_xor(ss, 4);
;               ss += __shfl_xor(ss, 8);
;               const float inv = rsqrtf(ss * (1.f / 64.f) + 1e-6f);
;               v0 *= inv * gv0; v1 *= inv * gv1; v2 *= inv * gv2; v3 *= inv * gv3;
;             }
;             if (dorope) {
;               float sr, cr, sc, cc;
;               sincos_rev((float)(s >> 6) * invf64, sr, cr);
;               sincos_rev((float)(s & 63) * invf64, sc, cc);
;               const float a1 = v0, a2 = v1, b1 = v2, b2 = v3;
;               v0 = a1 * cr - a2 * sr;
;               v1 = a2 * cr + a1 * sr;
;               v2 = b1 * cc - b2 * sc;
;               v3 = b2 * cc + b1 * sc;
;             }
;     ...
;       u16* dh = (kind == 1) ? dst + hf * 64 : dst + (size_t)(hf * 64) * rstride;
; #pragma unroll
;       for (int i = 0; i < 8; ++i) {
;         const int c = lane + i * 64;
;         const int row = c >> 3, cc = c & 7;
;         uint4 v = *(const uint4*)&Tl[row * 72 + cc * 8];
;         *(uint4*)(dh + (size_t)row * rstride + cc * 8) = v;
;       }
	v_mul_f32_e32 v189, v180, v186
	v_mul_f32_e32 v190, v181, v186
	v_mul_f32_e32 v182, v33, v187
	v_mul_f32_e32 v183, v29, v188
	v_mul_f32_e32 v184, v25, v189
	v_mul_f32_e32 v185, v21, v190
	v_mul_f32_e32 v186, v175, v183
	v_mul_f32_e32 v187, v176, v183
	v_fma_f32 v188, v176, v182, -v186
	v_fma_f32 v189, v175, v182, v187
	v_mul_f32_e32 v186, v223, v185
	v_mul_f32_e32 v187, v249, v185
	v_fma_f32 v190, v249, v184, -v186
	v_fma_f32 v191, v223, v184, v187
	v_cvt_pk_bf16_f32 v192, v188, v189
	v_cvt_pk_bf16_f32 v193, v190, v191
	ds_write_b16 v170, v192 offset:5040
	ds_write_b16_d16_hi v170, v192 offset:5072
	ds_write_b16 v170, v193 offset:5104
	ds_write_b16_d16_hi v170, v193 offset:5136
	v_mul_f32_e32 v182, v166, v166
	v_mul_f32_e32 v183, v162, v162
	v_mul_f32_e32 v184, v2, v2
	v_mul_f32_e32 v185, v6, v6
	v_add_f32_e32 v186, v182, v183
	v_add_f32_e32 v186, v186, v184
	v_add_f32_e32 v186, v186, v185
	s_nop 1
	v_add_f32_dpp v186, v186, v186 quad_perm:[1,0,3,2] row_mask:0xf bank_mask:0xf
	s_nop 1
	v_add_f32_dpp v186, v186, v186 quad_perm:[2,3,0,1] row_mask:0xf bank_mask:0xf
	s_nop 1
	v_add_f32_dpp v186, v186, v186 row_half_mirror row_mask:0xf bank_mask:0xf
	s_nop 1
	v_add_f32_dpp v186, v186, v186 row_mirror row_mask:0xf bank_mask:0xf
	v_fmamk_f32 v186, v186, 0x3c800000, v173
	v_rsq_f32_e32 v186, v186
	s_nop 0
	v_mul_f32_e32 v187, v178, v186
	v_mul_f32_e32 v188, v179, v186
	v_mul_f32_e32 v189, v180, v186
	v_mul_f32_e32 v190, v181, v186
	v_mul_f32_e32 v182, v166, v187
	v_mul_f32_e32 v183, v162, v188
	v_mul_f32_e32 v184, v2, v189
	v_mul_f32_e32 v185, v6, v190
	v_mul_f32_e32 v186, v175, v183
	v_mul_f32_e32 v187, v176, v183
	v_fma_f32 v188, v176, v182, -v186
	v_fma_f32 v189, v175, v182, v187
	v_mul_f32_e32 v186, v234, v185
	v_mul_f32_e32 v187, v250, v185
	v_fma_f32 v190, v250, v184, -v186
	v_fma_f32 v191, v234, v184, v187
	v_cvt_pk_bf16_f32 v192, v188, v189
	v_cvt_pk_bf16_f32 v193, v190, v191
	ds_write_b16 v170, v192 offset:6912
	ds_write_b16_d16_hi v170, v192 offset:6944
	ds_write_b16 v170, v193 offset:6976
	ds_write_b16_d16_hi v170, v193 offset:7008
	v_mul_f32_e32 v182, v167, v167
	v_mul_f32_e32 v183, v163, v163
	v_mul_f32_e32 v184, v3, v3
	v_mul_f32_e32 v185, v7, v7
	v_add_f32_e32 v186, v182, v183
	v_add_f32_e32 v186, v186, v184
	v_add_f32_e32 v186, v186, v185
	s_nop 1
	v_add_f32_dpp v186, v186, v186 quad_perm:[1,0,3,2] row_mask:0xf bank_mask:0xf
	s_nop 1
	v_add_f32_dpp v186, v186, v186 quad_perm:[2,3,0,1] row_mask:0xf bank_mask:0xf
	s_nop 1
	v_add_f32_dpp v186, v186, v186 row_half_mirror row_mask:0xf bank_mask:0xf
	s_nop 1
	v_add_f32_dpp v186, v186, v186 row_mirror row_mask:0xf bank_mask:0xf
	v_fmamk_f32 v186, v186, 0x3c800000, v173
	v_rsq_f32_e32 v186, v186
	s_nop 0
	v_mul_f32_e32 v187, v178, v186
	v_mul_f32_e32 v188, v179, v186
	v_mul_f32_e32 v189, v180, v186
	v_mul_f32_e32 v190, v181, v186
	v_mul_f32_e32 v182, v167, v187
	v_mul_f32_e32 v183, v163, v188
	v_mul_f32_e32 v184, v3, v189
	v_mul_f32_e32 v185, v7, v190
	v_mul_f32_e32 v186, v175, v183
	v_mul_f32_e32 v187, v176, v183
	v_fma_f32 v188, v176, v182, -v186
	v_fma_f32 v189, v175, v182, v187
	v_mul_f32_e32 v186, v235, v185
	v_mul_f32_e32 v187, v251, v185
	v_fma_f32 v190, v251, v184, -v186
	v_fma_f32 v191, v235, v184, v187
	v_cvt_pk_bf16_f32 v192, v188, v189
	v_cvt_pk_bf16_f32 v193, v190, v191
	ds_write_b16 v170, v192 offset:7056
	ds_write_b16_d16_hi v170, v192 offset:7088
	ds_write_b16 v170, v193 offset:7120
	ds_write_b16_d16_hi v170, v193 offset:7152
	v_mul_f32_e32 v182, v168, v168
	v_mul_f32_e32 v183, v164, v164
	v_mul_f32_e32 v184, v4, v4
	v_mul_f32_e32 v185, v8, v8
	v_add_f32_e32 v186, v182, v183
	v_add_f32_e32 v186, v186, v184
	v_add_f32_e32 v186, v186, v185
	s_nop 1
	v_add_f32_dpp v186, v186, v186 quad_perm:[1,0,3,2] row_mask:0xf bank_mask:0xf
	s_nop 1
	v_add_f32_dpp v186, v186, v186 quad_perm:[2,3,0,1] row_mask:0xf bank_mask:0xf
	s_nop 1
	v_add_f32_dpp v186, v186, v186 row_half_mirror row_mask:0xf bank_mask:0xf
	s_nop 1
	v_add_f32_dpp v186, v186, v186 row_mirror row_mask:0xf bank_mask:0xf
	v_fmamk_f32 v186, v186, 0x3c800000, v173
	v_rsq_f32_e32 v186, v186
	s_nop 0
	v_mul_f32_e32 v187, v178, v186
	v_mul_f32_e32 v188, v179, v186
	v_mul_f32_e32 v189, v180, v186
	v_mul_f32_e32 v190, v181, v186
	v_mul_f32_e32 v182, v168, v187
	v_mul_f32_e32 v183, v164, v188
	v_mul_f32_e32 v184, v4, v189
	v_mul_f32_e32 v185, v8, v190
	v_mul_f32_e32 v186, v175, v183
	v_mul_f32_e32 v187, v176, v183
	v_fma_f32 v188, v176, v182, -v186
	v_fma_f32 v189, v175, v182, v187
	v_mul_f32_e32 v186, v236, v185
	v_mul_f32_e32 v187, v252, v185
	v_fma_f32 v190, v252, v184, -v186
	v_fma_f32 v191, v236, v184, v187
	v_cvt_pk_bf16_f32 v192, v188, v189
	v_cvt_pk_bf16_f32 v193, v190, v191
	ds_write_b16 v170, v192 offset:7200
	ds_write_b16_d16_hi v170, v192 offset:7232
	ds_write_b16 v170, v193 offset:7264
	ds_write_b16_d16_hi v170, v193 offset:7296
	v_mul_f32_e32 v182, v169, v169
	v_mul_f32_e32 v183, v165, v165
	v_mul_f32_e32 v184, v5, v5
	v_mul_f32_e32 v185, v9, v9
	v_add_f32_e32 v186, v182, v183
	v_add_f32_e32 v186, v186, v184
	v_add_f32_e32 v186, v186, v185
	s_nop 1
	v_add_f32_dpp v186, v186, v186 quad_perm:[1,0,3,2] row_mask:0xf bank_mask:0xf
	s_nop 1
	v_add_f32_dpp v186, v186, v186 quad_perm:[2,3,0,1] row_mask:0xf bank_mask:0xf
	s_nop 1
	v_add_f32_dpp v186, v186, v186 row_half_mirror row_mask:0xf bank_mask:0xf
	s_nop 1
	v_add_f32_dpp v186, v186, v186 row_mirror row_mask:0xf bank_mask:0xf
	v_fmamk_f32 v186, v186, 0x3c800000, v173
	v_rsq_f32_e32 v186, v186
	s_nop 0
	v_mul_f32_e32 v187, v178, v186
	v_mul_f32_e32 v188, v179, v186
	v_mul_f32_e32 v189, v180, v186
	v_mul_f32_e32 v190, v181, v186
	v_mul_f32_e32 v182, v169, v187
	v_mul_f32_e32 v183, v165, v188
	v_mul_f32_e32 v184, v5, v189
	v_mul_f32_e32 v185, v9, v190
	v_mul_f32_e32 v186, v175, v183
	v_mul_f32_e32 v187, v176, v183
	v_fma_f32 v188, v176, v182, -v186
	v_fma_f32 v189, v175, v182, v187
	v_mul_f32_e32 v186, v237, v185
	v_mul_f32_e32 v187, v253, v185
	v_fma_f32 v190, v253, v184, -v186
	v_fma_f32 v191, v237, v184, v187
	v_cvt_pk_bf16_f32 v192, v188, v189
	v_cvt_pk_bf16_f32 v193, v190, v191
	ds_write_b16 v170, v192 offset:7344
	ds_write_b16_d16_hi v170, v192 offset:7376
	ds_write_b16 v170, v193 offset:7408
	ds_write_b16_d16_hi v170, v193 offset:7440
	ds_read_b128 v[130:133], v171 offset:0
	ds_read_b128 v[134:137], v171 offset:1152
	ds_read_b128 v[138:141], v171 offset:2304
	ds_read_b128 v[142:145], v171 offset:3456
	ds_read_b128 v[146:149], v171 offset:4608
	ds_read_b128 v[150:153], v171 offset:5760
	ds_read_b128 v[154:157], v171 offset:6912
	ds_read_b128 v[158:161], v171 offset:8064
	s_waitcnt lgkmcnt(7)
; template <int EPI>
; DI void gemm_phase(const P& p, int l, const u16* __restrict__ A, const u16* __restrict__ Bt, int mpx, char* lds) {
;     ...
;     const float* gw = (cb < 1280 ? p.ga_qn : p.ga_kn) + l * 64;
;     float gv0 = 1.f, gv1 = 1.f, gv2 = 1.f, gv3 = 1.f;
;     if (donorm) { gv0 = gw[r]; gv1 = gw[16 + r]; gv2 = gw[32 + r]; gv3 = gw[48 + r]; }
;     ...
;             if (donorm) {
;               float ss = v0 * v0 + v1 * v1 + v2 * v2 + v3 * v3;
;               ss += __shfl_xor(ss, 1);
;               ss += __shfl_xor(ss, 2);
;               ss += __shfl_xor(ss, 4);
;               ss += __shfl_xor(ss, 8);
;               const float inv = rsqrtf(ss * (1.f / 64.f) + 1e-6f);
;               v0 *= inv * gv0; v1 *= inv * gv1; v2 *= inv * gv2; v3 *= inv * gv3;
;             }
	global_store_dwordx4 v172, v[130:133], s[44:45] offset:0
	s_waitcnt lgkmcnt(6)
	global_store_dwordx4 v172, v[134:137], s[44:45] offset:1024
	s_waitcnt lgkmcnt(5)
	global_store_dwordx4 v172, v[138:141], s[44:45] offset:2048
	s_waitcnt lgkmcnt(4)
	global_store_dwordx4 v172, v[142:145], s[44:45] offset:3072
	s_waitcnt lgkmcnt(3)
	global_store_dwordx4 v172, v[146:149], s[62:63] offset:0
	s_waitcnt lgkmcnt(2)
	global_store_dwordx4 v172, v[150:153], s[62:63] offset:1024
	s_waitcnt lgkmcnt(1)
	global_store_dwordx4 v172, v[154:157], s[62:63] offset:2048
	s_waitcnt lgkmcnt(0)
	global_store_dwordx4 v172, v[158:161], s[62:63] offset:3072
	s_branch .Lfe_done
.Lfe_k0_norm:
	s_cmp_lt_u32 s43, 20
	s_movk_i32 s70, 0x68
	s_cselect_b32 s70, 0x60, s70
	s_add_u32 s70, s96, s70
	s_addc_u32 s71, s97, 0
	s_load_dwordx2 s[70:71], s[70:71], 0x0
	v_and_b32_e32 v0, 15, v226
	v_lshlrev_b32_e32 v0, 2, v0
	v_mov_b32_e32 v173, 0x358637bd
	s_waitcnt lgkmcnt(0)
	s_lshl_b32 s63, s52, 2
	s_add_u32 s70, s70, s63
	s_addc_u32 s71, s71, 0
	global_load_dword v178, v0, s[70:71] offset:0
	global_load_dword v179, v0, s[70:71] offset:64
	global_load_dword v180, v0, s[70:71] offset:128
	global_load_dword v181, v0, s[70:71] offset:192
	s_waitcnt vmcnt(0)
	s_add_u32 s62, s44, 0x1000
	s_addc_u32 s63, s45, 0
	v_mul_f32_e32 v182, v126, v126
	v_mul_f32_e32 v183, v122, v122
	v_mul_f32_e32 v184, v118, v118
	v_mul_f32_e32 v185, v114, v114
	v_add_f32_e32 v186, v182, v183
	v_add_f32_e32 v186, v186, v184
	v_add_f32_e32 v186, v186, v185
	s_nop 1
	v_add_f32_dpp v186, v186, v186 quad_perm:[1,0,3,2] row_mask:0xf bank_mask:0xf
	s_nop 1
	v_add_f32_dpp v186, v186, v186 quad_perm:[2,3,0,1] row_mask:0xf bank_mask:0xf
	s_nop 1
	v_add_f32_dpp v186, v186, v186 row_half_mirror row_mask:0xf bank_mask:0xf
	s_nop 1
	v_add_f32_dpp v186, v186, v186 row_mirror row_mask:0xf bank_mask:0xf
	v_fmamk_f32 v186, v186, 0x3c800000, v173
	v_rsq_f32_e32 v186, v186
	s_nop 0
	v_mul_f32_e32 v187, v178, v186
	v_mul_f32_e32 v188, v179, v186
	v_mul_f32_e32 v189, v180, v186
	v_mul_f32_e32 v190, v181, v186
	v_mul_f32_e32 v182, v126, v187
	v_mul_f32_e32 v183, v122, v188
	v_mul_f32_e32 v184, v118, v189
	v_mul_f32_e32 v185, v114, v190
	v_cvt_pk_bf16_f32 v192, v182, v183
	v_cvt_pk_bf16_f32 v193, v184, v185
	ds_write_b16 v170, v192 offset:0
	ds_write_b16_d16_hi v170, v192 offset:32
	ds_write_b16 v170, v193 offset:64
	ds_write_b16_d16_hi v170, v193 offset:96
	v_mul_f32_e32 v182, v127, v127
	v_mul_f32_e32 v183, v123, v123
	v_mul_f32_e32 v184, v119, v119
	v_mul_f32_e32 v185, v115, v115
	v_add_f32_e32 v186, v182, v183
	v_add_f32_e32 v186, v186, v184
	v_add_f32_e32 v186, v186, v185
	s_nop 1
	v_add_f32_dpp v186, v186, v186 quad_perm:[1,0,3,2] row_mask:0xf bank_mask:0xf
	s_nop 1
	v_add_f32_dpp v186, v186, v186 quad_perm:[2,3,0,1] row_mask:0xf bank_mask:0xf
	s_nop 1
	v_add_f32_dpp v186, v186, v186 row_half_mirror row_mask:0xf bank_mask:0xf
	s_nop 1
	v_add_f32_dpp v186, v186, v186 row_mirror row_mask:0xf bank_mask:0xf
	v_fmamk_f32 v186, v186, 0x3c800000, v173
	v_rsq_f32_e32 v186, v186
	s_nop 0
	v_mul_f32_e32 v187, v178, v186
	v_mul_f32_e32 v188, v179, v186
	v_mul_f32_e32 v189, v180, v186
	v_mul_f32_e32 v190, v181, v186
	v_mul_f32_e32 v182, v127, v187
	v_mul_f32_e32 v183, v123, v188
	v_mul_f32_e32 v184, v119, v189
	v_mul_f32_e32 v185, v115, v190
	v_cvt_pk_bf16_f32 v192, v182, v183
	v_cvt_pk_bf16_f32 v193, v184, v185
	ds_write_b16 v170, v192 offset:144
	ds_write_b16_d16_hi v170, v192 offset:176
	ds_write_b16 v170, v193 offset:208
	ds_write_b16_d16_hi v170, v193 offset:240
	v_mul_f32_e32 v182, v128, v128
	v_mul_f32_e32 v183, v124, v124
	v_mul_f32_e32 v184, v120, v120
	v_mul_f32_e32 v185, v116, v116
	v_add_f32_e32 v186, v182, v183
	v_add_f32_e32 v186, v186, v184
	v_add_f32_e32 v186, v186, v185
	s_nop 1
	v_add_f32_dpp v186, v186, v186 quad_perm:[1,0,3,2] row_mask:0xf bank_mask:0xf
	s_nop 1
	v_add_f32_dpp v186, v186, v186 quad_perm:[2,3,0,1] row_mask:0xf bank_mask:0xf
	s_nop 1
	v_add_f32_dpp v186, v186, v186 row_half_mirror row_mask:0xf bank_mask:0xf
	s_nop 1
	v_add_f32_dpp v186, v186, v186 row_mirror row_mask:0xf bank_mask:0xf
	v_fmamk_f32 v186, v186, 0x3c800000, v173
	v_rsq_f32_e32 v186, v186
	s_nop 0
	v_mul_f32_e32 v187, v178, v186
	v_mul_f32_e32 v188, v179, v186
	v_mul_f32_e32 v189, v180, v186
	v_mul_f32_e32 v190, v181, v186
	v_mul_f32_e32 v182, v128, v187
	v_mul_f32_e32 v183, v124, v188
	v_mul_f32_e32 v184, v120, v189
	v_mul_f32_e32 v185, v116, v190
	v_cvt_pk_bf16_f32 v192, v182, v183
	v_cvt_pk_bf16_f32 v193, v184, v185
	ds_write_b16 v170, v192 offset:288
	ds_write_b16_d16_hi v170, v192 offset:320
	ds_write_b16 v170, v193 offset:352
	ds_write_b16_d16_hi v170, v193 offset:384
	v_mul_f32_e32 v182, v129, v129
	v_mul_f32_e32 v183, v125, v125
	v_mul_f32_e32 v184, v121, v121
	v_mul_f32_e32 v185, v117, v117
	v_add_f32_e32 v186, v182, v183
	v_add_f32_e32 v186, v186, v184
	v_add_f32_e32 v186, v186, v185
	s_nop 1
	v_add_f32_dpp v186, v186, v186 quad_perm:[1,0,3,2] row_mask:0xf bank_mask:0xf
	s_nop 1
	v_add_f32_dpp v186, v186, v186 quad_perm:[2,3,0,1] row_mask:0xf bank_mask:0xf
	s_nop 1
	v_add_f32_dpp v186, v186, v186 row_half_mirror row_mask:0xf bank_mask:0xf
	s_nop 1
	v_add_f32_dpp v186, v186, v186 row_mirror row_mask:0xf bank_mask:0xf
	v_fmamk_f32 v186, v186, 0x3c800000, v173
	v_rsq_f32_e32 v186, v186
	s_nop 0
	v_mul_f32_e32 v187, v178, v186
	v_mul_f32_e32 v188, v179, v186
	v_mul_f32_e32 v189, v180, v186
	v_mul_f32_e32 v190, v181, v186
	v_mul_f32_e32 v182, v129, v187
	v_mul_f32_e32 v183, v125, v188
	v_mul_f32_e32 v184, v121, v189
	v_mul_f32_e32 v185, v117, v190
	v_cvt_pk_bf16_f32 v192, v182, v183
	v_cvt_pk_bf16_f32 v193, v184, v185
; template <int EPI>
; DI void gemm_phase(const P& p, int l, const u16* __restrict__ A, const u16* __restrict__ Bt, int mpx, char* lds) {
;     ...
;             if (donorm) {
;               float ss = v0 * v0 + v1 * v1 + v2 * v2 + v3 * v3;
;               ss += __shfl_xor(ss, 1);
;               ss += __shfl_xor(ss, 2);
;               ss += __shfl_xor(ss, 4);
;               ss += __shfl_xor(ss, 8);
;               const float inv = rsqrtf(ss * (1.f / 64.f) + 1e-6f);
;               v0 *= inv * gv0; v1 *= inv * gv1; v2 *= inv * gv2; v3 *= inv * gv3;
;             }
;     ...
;           } else {
;             Tl[rowl * 72 + 0 * 16 + r] = (u16)u01;
;             Tl[rowl * 72 + 1 * 16 + r] = (u16)(u01 >> 16);
;             Tl[rowl * 72 + 2 * 16 + r] = (u16)u23;
;             Tl[rowl * 72 + 3 * 16 + r] = (u16)(u23 >> 16);
	ds_write_b16 v170, v192 offset:432
	ds_write_b16_d16_hi v170, v192 offset:464
	ds_write_b16 v170, v193 offset:496
	ds_write_b16_d16_hi v170, v193 offset:528
	v_mul_f32_e32 v182, v110, v110
	v_mul_f32_e32 v183, v106, v106
	v_mul_f32_e32 v184, v102, v102
	v_mul_f32_e32 v185, v98, v98
	v_add_f32_e32 v186, v182, v183
	v_add_f32_e32 v186, v186, v184
	v_add_f32_e32 v186, v186, v185
	s_nop 1
	v_add_f32_dpp v186, v186, v186 quad_perm:[1,0,3,2] row_mask:0xf bank_mask:0xf
	s_nop 1
	v_add_f32_dpp v186, v186, v186 quad_perm:[2,3,0,1] row_mask:0xf bank_mask:0xf
	s_nop 1
	v_add_f32_dpp v186, v186, v186 row_half_mirror row_mask:0xf bank_mask:0xf
	s_nop 1
	v_add_f32_dpp v186, v186, v186 row_mirror row_mask:0xf bank_mask:0xf
	v_fmamk_f32 v186, v186, 0x3c800000, v173
	v_rsq_f32_e32 v186, v186
	s_nop 0
	v_mul_f32_e32 v187, v178, v186
	v_mul_f32_e32 v188, v179, v186
	v_mul_f32_e32 v189, v180, v186
	v_mul_f32_e32 v190, v181, v186
	v_mul_f32_e32 v182, v110, v187
	v_mul_f32_e32 v183, v106, v188
	v_mul_f32_e32 v184, v102, v189
	v_mul_f32_e32 v185, v98, v190
	v_cvt_pk_bf16_f32 v192, v182, v183
	v_cvt_pk_bf16_f32 v193, v184, v185
	ds_write_b16 v170, v192 offset:2304
	ds_write_b16_d16_hi v170, v192 offset:2336
	ds_write_b16 v170, v193 offset:2368
	ds_write_b16_d16_hi v170, v193 offset:2400
	v_mul_f32_e32 v182, v111, v111
	v_mul_f32_e32 v183, v107, v107
	v_mul_f32_e32 v184, v103, v103
	v_mul_f32_e32 v185, v99, v99
	v_add_f32_e32 v186, v182, v183
	v_add_f32_e32 v186, v186, v184
	v_add_f32_e32 v186, v186, v185
	s_nop 1
	v_add_f32_dpp v186, v186, v186 quad_perm:[1,0,3,2] row_mask:0xf bank_mask:0xf
	s_nop 1
	v_add_f32_dpp v186, v186, v186 quad_perm:[2,3,0,1] row_mask:0xf bank_mask:0xf
	s_nop 1
	v_add_f32_dpp v186, v186, v186 row_half_mirror row_mask:0xf bank_mask:0xf
	s_nop 1
	v_add_f32_dpp v186, v186, v186 row_mirror row_mask:0xf bank_mask:0xf
	v_fmamk_f32 v186, v186, 0x3c800000, v173
	v_rsq_f32_e32 v186, v186
	s_nop 0
	v_mul_f32_e32 v187, v178, v186
	v_mul_f32_e32 v188, v179, v186
	v_mul_f32_e32 v189, v180, v186
	v_mul_f32_e32 v190, v181, v186
	v_mul_f32_e32 v182, v111, v187
	v_mul_f32_e32 v183, v107, v188
	v_mul_f32_e32 v184, v103, v189
	v_mul_f32_e32 v185, v99, v190
	v_cvt_pk_bf16_f32 v192, v182, v183
	v_cvt_pk_bf16_f32 v193, v184, v185
	ds_write_b16 v170, v192 offset:2448
	ds_write_b16_d16_hi v170, v192 offset:2480
	ds_write_b16 v170, v193 offset:2512
	ds_write_b16_d16_hi v170, v193 offset:2544
	v_mul_f32_e32 v182, v112, v112
	v_mul_f32_e32 v183, v108, v108
	v_mul_f32_e32 v184, v104, v104
	v_mul_f32_e32 v185, v100, v100
	v_add_f32_e32 v186, v182, v183
	v_add_f32_e32 v186, v186, v184
	v_add_f32_e32 v186, v186, v185
	s_nop 1
	v_add_f32_dpp v186, v186, v186 quad_perm:[1,0,3,2] row_mask:0xf bank_mask:0xf
	s_nop 1
	v_add_f32_dpp v186, v186, v186 quad_perm:[2,3,0,1] row_mask:0xf bank_mask:0xf
	s_nop 1
	v_add_f32_dpp v186, v186, v186 row_half_mirror row_mask:0xf bank_mask:0xf
	s_nop 1
	v_add_f32_dpp v186, v186, v186 row_mirror row_mask:0xf bank_mask:0xf
	v_fmamk_f32 v186, v186, 0x3c800000, v173
	v_rsq_f32_e32 v186, v186
	s_nop 0
	v_mul_f32_e32 v187, v178, v186
	v_mul_f32_e32 v188, v179, v186
	v_mul_f32_e32 v189, v180, v186
	v_mul_f32_e32 v190, v181, v186
	v_mul_f32_e32 v182, v112, v187
	v_mul_f32_e32 v183, v108, v188
	v_mul_f32_e32 v184, v104, v189
	v_mul_f32_e32 v185, v100, v190
	v_cvt_pk_bf16_f32 v192, v182, v183
	v_cvt_pk_bf16_f32 v193, v184, v185
	ds_write_b16 v170, v192 offset:2592
	ds_write_b16_d16_hi v170, v192 offset:2624
	ds_write_b16 v170, v193 offset:2656
	ds_write_b16_d16_hi v170, v193 offset:2688
	v_mul_f32_e32 v182, v113, v113
	v_mul_f32_e32 v183, v109, v109
	v_mul_f32_e32 v184, v105, v105
	v_mul_f32_e32 v185, v101, v101
	v_add_f32_e32 v186, v182, v183
	v_add_f32_e32 v186, v186, v184
	v_add_f32_e32 v186, v186, v185
	s_nop 1
	v_add_f32_dpp v186, v186, v186 quad_perm:[1,0,3,2] row_mask:0xf bank_mask:0xf
	s_nop 1
	v_add_f32_dpp v186, v186, v186 quad_perm:[2,3,0,1] row_mask:0xf bank_mask:0xf
	s_nop 1
	v_add_f32_dpp v186, v186, v186 row_half_mirror row_mask:0xf bank_mask:0xf
	s_nop 1
	v_add_f32_dpp v186, v186, v186 row_mirror row_mask:0xf bank_mask:0xf
	v_fmamk_f32 v186, v186, 0x3c800000, v173
	v_rsq_f32_e32 v186, v186
	s_nop 0
	v_mul_f32_e32 v187, v178, v186
	v_mul_f32_e32 v188, v179, v186
	v_mul_f32_e32 v189, v180, v186
	v_mul_f32_e32 v190, v181, v186
	v_mul_f32_e32 v182, v113, v187
	v_mul_f32_e32 v183, v109, v188
	v_mul_f32_e32 v184, v105, v189
	v_mul_f32_e32 v185, v101, v190
	v_cvt_pk_bf16_f32 v192, v182, v183
	v_cvt_pk_bf16_f32 v193, v184, v185
	ds_write_b16 v170, v192 offset:2736
	ds_write_b16_d16_hi v170, v192 offset:2768
	ds_write_b16 v170, v193 offset:2800
	ds_write_b16_d16_hi v170, v193 offset:2832
	v_mul_f32_e32 v182, v94, v94
	v_mul_f32_e32 v183, v90, v90
	v_mul_f32_e32 v184, v86, v86
	v_mul_f32_e32 v185, v82, v82
	v_add_f32_e32 v186, v182, v183
	v_add_f32_e32 v186, v186, v184
	v_add_f32_e32 v186, v186, v185
	s_nop 1
	v_add_f32_dpp v186, v186, v186 quad_perm:[1,0,3,2] row_mask:0xf bank_mask:0xf
	s_nop 1
	v_add_f32_dpp v186, v186, v186 quad_perm:[2,3,0,1] row_mask:0xf bank_mask:0xf
	s_nop 1
	v_add_f32_dpp v186, v186, v186 row_half_mirror row_mask:0xf bank_mask:0xf
	s_nop 1
	v_add_f32_dpp v186, v186, v186 row_mirror row_mask:0xf bank_mask:0xf
	v_fmamk_f32 v186, v186, 0x3c800000, v173
	v_rsq_f32_e32 v186, v186
	s_nop 0
	v_mul_f32_e32 v187, v178, v186
	v_mul_f32_e32 v188, v179, v186
	v_mul_f32_e32 v189, v180, v186
	v_mul_f32_e32 v190, v181, v186
	v_mul_f32_e32 v182, v94, v187
	v_mul_f32_e32 v183, v90, v188
	v_mul_f32_e32 v184, v86, v189
	v_mul_f32_e32 v185, v82, v190
	v_cvt_pk_bf16_f32 v192, v182, v183
	v_cvt_pk_bf16_f32 v193, v184, v185
; template <int EPI>
; DI void gemm_phase(const P& p, int l, const u16* __restrict__ A, const u16* __restrict__ Bt, int mpx, char* lds) {
;     ...
;             if (donorm) {
;               float ss = v0 * v0 + v1 * v1 + v2 * v2 + v3 * v3;
;               ss += __shfl_xor(ss, 1);
;               ss += __shfl_xor(ss, 2);
;               ss += __shfl_xor(ss, 4);
;               ss += __shfl_xor(ss, 8);
;               const float inv = rsqrtf(ss * (1.f / 64.f) + 1e-6f);
;               v0 *= inv * gv0; v1 *= inv * gv1; v2 *= inv * gv2; v3 *= inv * gv3;
;             }
;     ...
;           } else {
;             Tl[rowl * 72 + 0 * 16 + r] = (u16)u01;
;             Tl[rowl * 72 + 1 * 16 + r] = (u16)(u01 >> 16);
;             Tl[rowl * 72 + 2 * 16 + r] = (u16)u23;
;             Tl[rowl * 72 + 3 * 16 + r] = (u16)(u23 >> 16);
	ds_write_b16 v170, v192 offset:4608
	ds_write_b16_d16_hi v170, v192 offset:4640
	ds_write_b16 v170, v193 offset:4672
	ds_write_b16_d16_hi v170, v193 offset:4704
	v_mul_f32_e32 v182, v95, v95
	v_mul_f32_e32 v183, v91, v91
	v_mul_f32_e32 v184, v87, v87
	v_mul_f32_e32 v185, v83, v83
	v_add_f32_e32 v186, v182, v183
	v_add_f32_e32 v186, v186, v184
	v_add_f32_e32 v186, v186, v185
	s_nop 1
	v_add_f32_dpp v186, v186, v186 quad_perm:[1,0,3,2] row_mask:0xf bank_mask:0xf
	s_nop 1
	v_add_f32_dpp v186, v186, v186 quad_perm:[2,3,0,1] row_mask:0xf bank_mask:0xf
	s_nop 1
	v_add_f32_dpp v186, v186, v186 row_half_mirror row_mask:0xf bank_mask:0xf
	s_nop 1
	v_add_f32_dpp v186, v186, v186 row_mirror row_mask:0xf bank_mask:0xf
	v_fmamk_f32 v186, v186, 0x3c800000, v173
	v_rsq_f32_e32 v186, v186
	s_nop 0
	v_mul_f32_e32 v187, v178, v186
	v_mul_f32_e32 v188, v179, v186
	v_mul_f32_e32 v189, v180, v186
	v_mul_f32_e32 v190, v181, v186
	v_mul_f32_e32 v182, v95, v187
	v_mul_f32_e32 v183, v91, v188
	v_mul_f32_e32 v184, v87, v189
	v_mul_f32_e32 v185, v83, v190
	v_cvt_pk_bf16_f32 v192, v182, v183
	v_cvt_pk_bf16_f32 v193, v184, v185
	ds_write_b16 v170, v192 offset:4752
	ds_write_b16_d16_hi v170, v192 offset:4784
	ds_write_b16 v170, v193 offset:4816
	ds_write_b16_d16_hi v170, v193 offset:4848
	v_mul_f32_e32 v182, v96, v96
	v_mul_f32_e32 v183, v92, v92
	v_mul_f32_e32 v184, v88, v88
	v_mul_f32_e32 v185, v84, v84
	v_add_f32_e32 v186, v182, v183
	v_add_f32_e32 v186, v186, v184
	v_add_f32_e32 v186, v186, v185
	s_nop 1
	v_add_f32_dpp v186, v186, v186 quad_perm:[1,0,3,2] row_mask:0xf bank_mask:0xf
	s_nop 1
	v_add_f32_dpp v186, v186, v186 quad_perm:[2,3,0,1] row_mask:0xf bank_mask:0xf
	s_nop 1
	v_add_f32_dpp v186, v186, v186 row_half_mirror row_mask:0xf bank_mask:0xf
	s_nop 1
	v_add_f32_dpp v186, v186, v186 row_mirror row_mask:0xf bank_mask:0xf
	v_fmamk_f32 v186, v186, 0x3c800000, v173
	v_rsq_f32_e32 v186, v186
	s_nop 0
	v_mul_f32_e32 v187, v178, v186
	v_mul_f32_e32 v188, v179, v186
	v_mul_f32_e32 v189, v180, v186
	v_mul_f32_e32 v190, v181, v186
	v_mul_f32_e32 v182, v96, v187
	v_mul_f32_e32 v183, v92, v188
	v_mul_f32_e32 v184, v88, v189
	v_mul_f32_e32 v185, v84, v190
	v_cvt_pk_bf16_f32 v192, v182, v183
	v_cvt_pk_bf16_f32 v193, v184, v185
	ds_write_b16 v170, v192 offset:4896
	ds_write_b16_d16_hi v170, v192 offset:4928
	ds_write_b16 v170, v193 offset:4960
	ds_write_b16_d16_hi v170, v193 offset:4992
	v_mul_f32_e32 v182, v97, v97
	v_mul_f32_e32 v183, v93, v93
	v_mul_f32_e32 v184, v89, v89
	v_mul_f32_e32 v185, v85, v85
	v_add_f32_e32 v186, v182, v183
	v_add_f32_e32 v186, v186, v184
	v_add_f32_e32 v186, v186, v185
	s_nop 1
	v_add_f32_dpp v186, v186, v186 quad_perm:[1,0,3,2] row_mask:0xf bank_mask:0xf
	s_nop 1
	v_add_f32_dpp v186, v186, v186 quad_perm:[2,3,0,1] row_mask:0xf bank_mask:0xf
	s_nop 1
	v_add_f32_dpp v186, v186, v186 row_half_mirror row_mask:0xf bank_mask:0xf
	s_nop 1
	v_add_f32_dpp v186, v186, v186 row_mirror row_mask:0xf bank_mask:0xf
	v_fmamk_f32 v186, v186, 0x3c800000, v173
	v_rsq_f32_e32 v186, v186
	s_nop 0
	v_mul_f32_e32 v187, v178, v186
	v_mul_f32_e32 v188, v179, v186
	v_mul_f32_e32 v189, v180, v186
	v_mul_f32_e32 v190, v181, v186
	v_mul_f32_e32 v182, v97, v187
	v_mul_f32_e32 v183, v93, v188
	v_mul_f32_e32 v184, v89, v189
	v_mul_f32_e32 v185, v85, v190
	v_cvt_pk_bf16_f32 v192, v182, v183
	v_cvt_pk_bf16_f32 v193, v184, v185
	ds_write_b16 v170, v192 offset:5040
	ds_write_b16_d16_hi v170, v192 offset:5072
	ds_write_b16 v170, v193 offset:5104
	ds_write_b16_d16_hi v170, v193 offset:5136
	v_mul_f32_e32 v182, v78, v78
	v_mul_f32_e32 v183, v74, v74
	v_mul_f32_e32 v184, v70, v70
	v_mul_f32_e32 v185, v66, v66
	v_add_f32_e32 v186, v182, v183
	v_add_f32_e32 v186, v186, v184
	v_add_f32_e32 v186, v186, v185
	s_nop 1
	v_add_f32_dpp v186, v186, v186 quad_perm:[1,0,3,2] row_mask:0xf bank_mask:0xf
	s_nop 1
	v_add_f32_dpp v186, v186, v186 quad_perm:[2,3,0,1] row_mask:0xf bank_mask:0xf
	s_nop 1
	v_add_f32_dpp v186, v186, v186 row_half_mirror row_mask:0xf bank_mask:0xf
	s_nop 1
	v_add_f32_dpp v186, v186, v186 row_mirror row_mask:0xf bank_mask:0xf
	v_fmamk_f32 v186, v186, 0x3c800000, v173
	v_rsq_f32_e32 v186, v186
	s_nop 0
	v_mul_f32_e32 v187, v178, v186
	v_mul_f32_e32 v188, v179, v186
	v_mul_f32_e32 v189, v180, v186
	v_mul_f32_e32 v190, v181, v186
	v_mul_f32_e32 v182, v78, v187
	v_mul_f32_e32 v183, v74, v188
	v_mul_f32_e32 v184, v70, v189
	v_mul_f32_e32 v185, v66, v190
	v_cvt_pk_bf16_f32 v192, v182, v183
	v_cvt_pk_bf16_f32 v193, v184, v185
	ds_write_b16 v170, v192 offset:6912
	ds_write_b16_d16_hi v170, v192 offset:6944
	ds_write_b16 v170, v193 offset:6976
	ds_write_b16_d16_hi v170, v193 offset:7008
	v_mul_f32_e32 v182, v79, v79
	v_mul_f32_e32 v183, v75, v75
	v_mul_f32_e32 v184, v71, v71
	v_mul_f32_e32 v185, v67, v67
	v_add_f32_e32 v186, v182, v183
	v_add_f32_e32 v186, v186, v184
	v_add_f32_e32 v186, v186, v185
	s_nop 1
	v_add_f32_dpp v186, v186, v186 quad_perm:[1,0,3,2] row_mask:0xf bank_mask:0xf
	s_nop 1
	v_add_f32_dpp v186, v186, v186 quad_perm:[2,3,0,1] row_mask:0xf bank_mask:0xf
	s_nop 1
	v_add_f32_dpp v186, v186, v186 row_half_mirror row_mask:0xf bank_mask:0xf
	s_nop 1
	v_add_f32_dpp v186, v186, v186 row_mirror row_mask:0xf bank_mask:0xf
	v_fmamk_f32 v186, v186, 0x3c800000, v173
	v_rsq_f32_e32 v186, v186
	s_nop 0
	v_mul_f32_e32 v187, v178, v186
	v_mul_f32_e32 v188, v179, v186
	v_mul_f32_e32 v189, v180, v186
	v_mul_f32_e32 v190, v181, v186
	v_mul_f32_e32 v182, v79, v187
	v_mul_f32_e32 v183, v75, v188
	v_mul_f32_e32 v184, v71, v189
	v_mul_f32_e32 v185, v67, v190
	v_cvt_pk_bf16_f32 v192, v182, v183
	v_cvt_pk_bf16_f32 v193, v184, v185
	ds_write_b16 v170, v192 offset:7056
; template <int EPI>
; DI void gemm_phase(const P& p, int l, const u16* __restrict__ A, const u16* __restrict__ Bt, int mpx, char* lds) {
;     ...
;             if (donorm) {
;               float ss = v0 * v0 + v1 * v1 + v2 * v2 + v3 * v3;
;               ss += __shfl_xor(ss, 1);
;               ss += __shfl_xor(ss, 2);
;               ss += __shfl_xor(ss, 4);
;               ss += __shfl_xor(ss, 8);
;               const float inv = rsqrtf(ss * (1.f / 64.f) + 1e-6f);
;               v0 *= inv * gv0; v1 *= inv * gv1; v2 *= inv * gv2; v3 *= inv * gv3;
;             }
;     ...
;       u16* dh = (kind == 1) ? dst + hf * 64 : dst + (size_t)(hf * 64) * rstride;
; #pragma unroll
;       for (int i = 0; i < 8; ++i) {
;         const int c = lane + i * 64;
;         const int row = c >> 3, cc = c & 7;
;         uint4 v = *(const uint4*)&Tl[row * 72 + cc * 8];
;         *(uint4*)(dh + (size_t)row * rstride + cc * 8) = v;
;       }
	ds_write_b16_d16_hi v170, v192 offset:7088
	ds_write_b16 v170, v193 offset:7120
	ds_write_b16_d16_hi v170, v193 offset:7152
	v_mul_f32_e32 v182, v80, v80
	v_mul_f32_e32 v183, v76, v76
	v_mul_f32_e32 v184, v72, v72
	v_mul_f32_e32 v185, v68, v68
	v_add_f32_e32 v186, v182, v183
	v_add_f32_e32 v186, v186, v184
	v_add_f32_e32 v186, v186, v185
	s_nop 1
	v_add_f32_dpp v186, v186, v186 quad_perm:[1,0,3,2] row_mask:0xf bank_mask:0xf
	s_nop 1
	v_add_f32_dpp v186, v186, v186 quad_perm:[2,3,0,1] row_mask:0xf bank_mask:0xf
	s_nop 1
	v_add_f32_dpp v186, v186, v186 row_half_mirror row_mask:0xf bank_mask:0xf
	s_nop 1
	v_add_f32_dpp v186, v186, v186 row_mirror row_mask:0xf bank_mask:0xf
	v_fmamk_f32 v186, v186, 0x3c800000, v173
	v_rsq_f32_e32 v186, v186
	s_nop 0
	v_mul_f32_e32 v187, v178, v186
	v_mul_f32_e32 v188, v179, v186
	v_mul_f32_e32 v189, v180, v186
	v_mul_f32_e32 v190, v181, v186
	v_mul_f32_e32 v182, v80, v187
	v_mul_f32_e32 v183, v76, v188
	v_mul_f32_e32 v184, v72, v189
	v_mul_f32_e32 v185, v68, v190
	v_cvt_pk_bf16_f32 v192, v182, v183
	v_cvt_pk_bf16_f32 v193, v184, v185
	ds_write_b16 v170, v192 offset:7200
	ds_write_b16_d16_hi v170, v192 offset:7232
	ds_write_b16 v170, v193 offset:7264
	ds_write_b16_d16_hi v170, v193 offset:7296
	v_mul_f32_e32 v182, v81, v81
	v_mul_f32_e32 v183, v77, v77
	v_mul_f32_e32 v184, v73, v73
	v_mul_f32_e32 v185, v69, v69
	v_add_f32_e32 v186, v182, v183
	v_add_f32_e32 v186, v186, v184
	v_add_f32_e32 v186, v186, v185
	s_nop 1
	v_add_f32_dpp v186, v186, v186 quad_perm:[1,0,3,2] row_mask:0xf bank_mask:0xf
	s_nop 1
	v_add_f32_dpp v186, v186, v186 quad_perm:[2,3,0,1] row_mask:0xf bank_mask:0xf
	s_nop 1
	v_add_f32_dpp v186, v186, v186 row_half_mirror row_mask:0xf bank_mask:0xf
	s_nop 1
	v_add_f32_dpp v186, v186, v186 row_mirror row_mask:0xf bank_mask:0xf
	v_fmamk_f32 v186, v186, 0x3c800000, v173
	v_rsq_f32_e32 v186, v186
	s_nop 0
	v_mul_f32_e32 v187, v178, v186
	v_mul_f32_e32 v188, v179, v186
	v_mul_f32_e32 v189, v180, v186
	v_mul_f32_e32 v190, v181, v186
	v_mul_f32_e32 v182, v81, v187
	v_mul_f32_e32 v183, v77, v188
	v_mul_f32_e32 v184, v73, v189
	v_mul_f32_e32 v185, v69, v190
	v_cvt_pk_bf16_f32 v192, v182, v183
	v_cvt_pk_bf16_f32 v193, v184, v185
	ds_write_b16 v170, v192 offset:7344
	ds_write_b16_d16_hi v170, v192 offset:7376
	ds_write_b16 v170, v193 offset:7408
	ds_write_b16_d16_hi v170, v193 offset:7440
	ds_read_b128 v[130:133], v171 offset:0
	ds_read_b128 v[134:137], v171 offset:1152
	ds_read_b128 v[138:141], v171 offset:2304
	ds_read_b128 v[142:145], v171 offset:3456
	ds_read_b128 v[146:149], v171 offset:4608
	ds_read_b128 v[150:153], v171 offset:5760
	ds_read_b128 v[154:157], v171 offset:6912
	ds_read_b128 v[158:161], v171 offset:8064
	s_waitcnt lgkmcnt(7)
	global_store_dwordx4 v172, v[130:133], s[44:45] offset:0
	s_waitcnt lgkmcnt(6)
	global_store_dwordx4 v172, v[134:137], s[44:45] offset:1024
	s_waitcnt lgkmcnt(5)
	global_store_dwordx4 v172, v[138:141], s[44:45] offset:2048
	s_waitcnt lgkmcnt(4)
	global_store_dwordx4 v172, v[142:145], s[44:45] offset:3072
	s_waitcnt lgkmcnt(3)
	global_store_dwordx4 v172, v[146:149], s[62:63] offset:0
	s_waitcnt lgkmcnt(2)
	global_store_dwordx4 v172, v[150:153], s[62:63] offset:1024
	s_waitcnt lgkmcnt(1)
	global_store_dwordx4 v172, v[154:157], s[62:63] offset:2048
	s_waitcnt lgkmcnt(0)
	global_store_dwordx4 v172, v[158:161], s[62:63] offset:3072
	s_add_u32 s44, s44, 0x2000
	s_addc_u32 s45, s45, 0
	s_add_u32 s62, s62, 0x2000
	s_addc_u32 s63, s63, 0
	v_mul_f32_e32 v182, v62, v62
	v_mul_f32_e32 v183, v58, v58
	v_mul_f32_e32 v184, v54, v54
	v_mul_f32_e32 v185, v50, v50
	v_add_f32_e32 v186, v182, v183
	v_add_f32_e32 v186, v186, v184
	v_add_f32_e32 v186, v186, v185
	s_nop 1
	v_add_f32_dpp v186, v186, v186 quad_perm:[1,0,3,2] row_mask:0xf bank_mask:0xf
	s_nop 1
	v_add_f32_dpp v186, v186, v186 quad_perm:[2,3,0,1] row_mask:0xf bank_mask:0xf
	s_nop 1
	v_add_f32_dpp v186, v186, v186 row_half_mirror row_mask:0xf bank_mask:0xf
	s_nop 1
	v_add_f32_dpp v186, v186, v186 row_mirror row_mask:0xf bank_mask:0xf
	v_fmamk_f32 v186, v186, 0x3c800000, v173
	v_rsq_f32_e32 v186, v186
	s_nop 0
	v_mul_f32_e32 v187, v178, v186
	v_mul_f32_e32 v188, v179, v186
	v_mul_f32_e32 v189, v180, v186
	v_mul_f32_e32 v190, v181, v186
	v_mul_f32_e32 v182, v62, v187
	v_mul_f32_e32 v183, v58, v188
	v_mul_f32_e32 v184, v54, v189
	v_mul_f32_e32 v185, v50, v190
	v_cvt_pk_bf16_f32 v192, v182, v183
	v_cvt_pk_bf16_f32 v193, v184, v185
	ds_write_b16 v170, v192 offset:0
	ds_write_b16_d16_hi v170, v192 offset:32
	ds_write_b16 v170, v193 offset:64
	ds_write_b16_d16_hi v170, v193 offset:96
	v_mul_f32_e32 v182, v63, v63
	v_mul_f32_e32 v183, v59, v59
	v_mul_f32_e32 v184, v55, v55
	v_mul_f32_e32 v185, v51, v51
	v_add_f32_e32 v186, v182, v183
	v_add_f32_e32 v186, v186, v184
	v_add_f32_e32 v186, v186, v185
	s_nop 1
	v_add_f32_dpp v186, v186, v186 quad_perm:[1,0,3,2] row_mask:0xf bank_mask:0xf
	s_nop 1
	v_add_f32_dpp v186, v186, v186 quad_perm:[2,3,0,1] row_mask:0xf bank_mask:0xf
	s_nop 1
	v_add_f32_dpp v186, v186, v186 row_half_mirror row_mask:0xf bank_mask:0xf
	s_nop 1
	v_add_f32_dpp v186, v186, v186 row_mirror row_mask:0xf bank_mask:0xf
	v_fmamk_f32 v186, v186, 0x3c800000, v173
	v_rsq_f32_e32 v186, v186
	s_nop 0
	v_mul_f32_e32 v187, v178, v186
	v_mul_f32_e32 v188, v179, v186
	v_mul_f32_e32 v189, v180, v186
	v_mul_f32_e32 v190, v181, v186
	v_mul_f32_e32 v182, v63, v187
	v_mul_f32_e32 v183, v59, v188
	v_mul_f32_e32 v184, v55, v189
	v_mul_f32_e32 v185, v51, v190
	v_cvt_pk_bf16_f32 v192, v182, v183
	v_cvt_pk_bf16_f32 v193, v184, v185
	ds_write_b16 v170, v192 offset:144
	ds_write_b16_d16_hi v170, v192 offset:176
	ds_write_b16 v170, v193 offset:208
; template <int EPI>
; DI void gemm_phase(const P& p, int l, const u16* __restrict__ A, const u16* __restrict__ Bt, int mpx, char* lds) {
;     ...
;             if (donorm) {
;               float ss = v0 * v0 + v1 * v1 + v2 * v2 + v3 * v3;
;               ss += __shfl_xor(ss, 1);
;               ss += __shfl_xor(ss, 2);
;               ss += __shfl_xor(ss, 4);
;               ss += __shfl_xor(ss, 8);
;               const float inv = rsqrtf(ss * (1.f / 64.f) + 1e-6f);
;               v0 *= inv * gv0; v1 *= inv * gv1; v2 *= inv * gv2; v3 *= inv * gv3;
;             }
;     ...
;           } else {
;             Tl[rowl * 72 + 0 * 16 + r] = (u16)u01;
;             Tl[rowl * 72 + 1 * 16 + r] = (u16)(u01 >> 16);
;             Tl[rowl * 72 + 2 * 16 + r] = (u16)u23;
;             Tl[rowl * 72 + 3 * 16 + r] = (u16)(u23 >> 16);
	ds_write_b16_d16_hi v170, v193 offset:240
	v_mul_f32_e32 v182, v64, v64
	v_mul_f32_e32 v183, v60, v60
	v_mul_f32_e32 v184, v56, v56
	v_mul_f32_e32 v185, v52, v52
	v_add_f32_e32 v186, v182, v183
	v_add_f32_e32 v186, v186, v184
	v_add_f32_e32 v186, v186, v185
	s_nop 1
	v_add_f32_dpp v186, v186, v186 quad_perm:[1,0,3,2] row_mask:0xf bank_mask:0xf
	s_nop 1
	v_add_f32_dpp v186, v186, v186 quad_perm:[2,3,0,1] row_mask:0xf bank_mask:0xf
	s_nop 1
	v_add_f32_dpp v186, v186, v186 row_half_mirror row_mask:0xf bank_mask:0xf
	s_nop 1
	v_add_f32_dpp v186, v186, v186 row_mirror row_mask:0xf bank_mask:0xf
	v_fmamk_f32 v186, v186, 0x3c800000, v173
	v_rsq_f32_e32 v186, v186
	s_nop 0
	v_mul_f32_e32 v187, v178, v186
	v_mul_f32_e32 v188, v179, v186
	v_mul_f32_e32 v189, v180, v186
	v_mul_f32_e32 v190, v181, v186
	v_mul_f32_e32 v182, v64, v187
	v_mul_f32_e32 v183, v60, v188
	v_mul_f32_e32 v184, v56, v189
	v_mul_f32_e32 v185, v52, v190
	v_cvt_pk_bf16_f32 v192, v182, v183
	v_cvt_pk_bf16_f32 v193, v184, v185
	ds_write_b16 v170, v192 offset:288
	ds_write_b16_d16_hi v170, v192 offset:320
	ds_write_b16 v170, v193 offset:352
	ds_write_b16_d16_hi v170, v193 offset:384
	v_mul_f32_e32 v182, v65, v65
	v_mul_f32_e32 v183, v61, v61
	v_mul_f32_e32 v184, v57, v57
	v_mul_f32_e32 v185, v53, v53
	v_add_f32_e32 v186, v182, v183
	v_add_f32_e32 v186, v186, v184
	v_add_f32_e32 v186, v186, v185
	s_nop 1
	v_add_f32_dpp v186, v186, v186 quad_perm:[1,0,3,2] row_mask:0xf bank_mask:0xf
	s_nop 1
	v_add_f32_dpp v186, v186, v186 quad_perm:[2,3,0,1] row_mask:0xf bank_mask:0xf
	s_nop 1
	v_add_f32_dpp v186, v186, v186 row_half_mirror row_mask:0xf bank_mask:0xf
	s_nop 1
	v_add_f32_dpp v186, v186, v186 row_mirror row_mask:0xf bank_mask:0xf
	v_fmamk_f32 v186, v186, 0x3c800000, v173
	v_rsq_f32_e32 v186, v186
	s_nop 0
	v_mul_f32_e32 v187, v178, v186
	v_mul_f32_e32 v188, v179, v186
	v_mul_f32_e32 v189, v180, v186
	v_mul_f32_e32 v190, v181, v186
	v_mul_f32_e32 v182, v65, v187
	v_mul_f32_e32 v183, v61, v188
	v_mul_f32_e32 v184, v57, v189
	v_mul_f32_e32 v185, v53, v190
	v_cvt_pk_bf16_f32 v192, v182, v183
	v_cvt_pk_bf16_f32 v193, v184, v185
	ds_write_b16 v170, v192 offset:432
	ds_write_b16_d16_hi v170, v192 offset:464
	ds_write_b16 v170, v193 offset:496
	ds_write_b16_d16_hi v170, v193 offset:528
	v_mul_f32_e32 v182, v46, v46
	v_mul_f32_e32 v183, v42, v42
	v_mul_f32_e32 v184, v38, v38
	v_mul_f32_e32 v185, v34, v34
	v_add_f32_e32 v186, v182, v183
	v_add_f32_e32 v186, v186, v184
	v_add_f32_e32 v186, v186, v185
	s_nop 1
	v_add_f32_dpp v186, v186, v186 quad_perm:[1,0,3,2] row_mask:0xf bank_mask:0xf
	s_nop 1
	v_add_f32_dpp v186, v186, v186 quad_perm:[2,3,0,1] row_mask:0xf bank_mask:0xf
	s_nop 1
	v_add_f32_dpp v186, v186, v186 row_half_mirror row_mask:0xf bank_mask:0xf
	s_nop 1
	v_add_f32_dpp v186, v186, v186 row_mirror row_mask:0xf bank_mask:0xf
	v_fmamk_f32 v186, v186, 0x3c800000, v173
	v_rsq_f32_e32 v186, v186
	s_nop 0
	v_mul_f32_e32 v187, v178, v186
	v_mul_f32_e32 v188, v179, v186
	v_mul_f32_e32 v189, v180, v186
	v_mul_f32_e32 v190, v181, v186
	v_mul_f32_e32 v182, v46, v187
	v_mul_f32_e32 v183, v42, v188
	v_mul_f32_e32 v184, v38, v189
	v_mul_f32_e32 v185, v34, v190
	v_cvt_pk_bf16_f32 v192, v182, v183
	v_cvt_pk_bf16_f32 v193, v184, v185
	ds_write_b16 v170, v192 offset:2304
	ds_write_b16_d16_hi v170, v192 offset:2336
	ds_write_b16 v170, v193 offset:2368
	ds_write_b16_d16_hi v170, v193 offset:2400
	v_mul_f32_e32 v182, v47, v47
	v_mul_f32_e32 v183, v43, v43
	v_mul_f32_e32 v184, v39, v39
	v_mul_f32_e32 v185, v35, v35
	v_add_f32_e32 v186, v182, v183
	v_add_f32_e32 v186, v186, v184
	v_add_f32_e32 v186, v186, v185
	s_nop 1
	v_add_f32_dpp v186, v186, v186 quad_perm:[1,0,3,2] row_mask:0xf bank_mask:0xf
	s_nop 1
	v_add_f32_dpp v186, v186, v186 quad_perm:[2,3,0,1] row_mask:0xf bank_mask:0xf
	s_nop 1
	v_add_f32_dpp v186, v186, v186 row_half_mirror row_mask:0xf bank_mask:0xf
	s_nop 1
	v_add_f32_dpp v186, v186, v186 row_mirror row_mask:0xf bank_mask:0xf
	v_fmamk_f32 v186, v186, 0x3c800000, v173
	v_rsq_f32_e32 v186, v186
	s_nop 0
	v_mul_f32_e32 v187, v178, v186
	v_mul_f32_e32 v188, v179, v186
	v_mul_f32_e32 v189, v180, v186
	v_mul_f32_e32 v190, v181, v186
	v_mul_f32_e32 v182, v47, v187
	v_mul_f32_e32 v183, v43, v188
	v_mul_f32_e32 v184, v39, v189
	v_mul_f32_e32 v185, v35, v190
	v_cvt_pk_bf16_f32 v192, v182, v183
	v_cvt_pk_bf16_f32 v193, v184, v185
	ds_write_b16 v170, v192 offset:2448
	ds_write_b16_d16_hi v170, v192 offset:2480
	ds_write_b16 v170, v193 offset:2512
	ds_write_b16_d16_hi v170, v193 offset:2544
	v_mul_f32_e32 v182, v48, v48
	v_mul_f32_e32 v183, v44, v44
	v_mul_f32_e32 v184, v40, v40
	v_mul_f32_e32 v185, v36, v36
	v_add_f32_e32 v186, v182, v183
	v_add_f32_e32 v186, v186, v184
	v_add_f32_e32 v186, v186, v185
	s_nop 1
	v_add_f32_dpp v186, v186, v186 quad_perm:[1,0,3,2] row_mask:0xf bank_mask:0xf
	s_nop 1
	v_add_f32_dpp v186, v186, v186 quad_perm:[2,3,0,1] row_mask:0xf bank_mask:0xf
	s_nop 1
	v_add_f32_dpp v186, v186, v186 row_half_mirror row_mask:0xf bank_mask:0xf
	s_nop 1
	v_add_f32_dpp v186, v186, v186 row_mirror row_mask:0xf bank_mask:0xf
	v_fmamk_f32 v186, v186, 0x3c800000, v173
	v_rsq_f32_e32 v186, v186
	s_nop 0
	v_mul_f32_e32 v187, v178, v186
	v_mul_f32_e32 v188, v179, v186
	v_mul_f32_e32 v189, v180, v186
	v_mul_f32_e32 v190, v181, v186
	v_mul_f32_e32 v182, v48, v187
	v_mul_f32_e32 v183, v44, v188
	v_mul_f32_e32 v184, v40, v189
	v_mul_f32_e32 v185, v36, v190
	v_cvt_pk_bf16_f32 v192, v182, v183
	v_cvt_pk_bf16_f32 v193, v184, v185
	ds_write_b16 v170, v192 offset:2592
	ds_write_b16_d16_hi v170, v192 offset:2624
	ds_write_b16 v170, v193 offset:2656
	ds_write_b16_d16_hi v170, v193 offset:2688
; template <int EPI>
; DI void gemm_phase(const P& p, int l, const u16* __restrict__ A, const u16* __restrict__ Bt, int mpx, char* lds) {
;     ...
;             if (donorm) {
;               float ss = v0 * v0 + v1 * v1 + v2 * v2 + v3 * v3;
;               ss += __shfl_xor(ss, 1);
;               ss += __shfl_xor(ss, 2);
;               ss += __shfl_xor(ss, 4);
;               ss += __shfl_xor(ss, 8);
;               const float inv = rsqrtf(ss * (1.f / 64.f) + 1e-6f);
;               v0 *= inv * gv0; v1 *= inv * gv1; v2 *= inv * gv2; v3 *= inv * gv3;
;             }
;     ...
;           } else {
;             Tl[rowl * 72 + 0 * 16 + r] = (u16)u01;
;             Tl[rowl * 72 + 1 * 16 + r] = (u16)(u01 >> 16);
;             Tl[rowl * 72 + 2 * 16 + r] = (u16)u23;
;             Tl[rowl * 72 + 3 * 16 + r] = (u16)(u23 >> 16);
	v_mul_f32_e32 v182, v49, v49
	v_mul_f32_e32 v183, v45, v45
	v_mul_f32_e32 v184, v41, v41
	v_mul_f32_e32 v185, v37, v37
	v_add_f32_e32 v186, v182, v183
	v_add_f32_e32 v186, v186, v184
	v_add_f32_e32 v186, v186, v185
	s_nop 1
	v_add_f32_dpp v186, v186, v186 quad_perm:[1,0,3,2] row_mask:0xf bank_mask:0xf
	s_nop 1
	v_add_f32_dpp v186, v186, v186 quad_perm:[2,3,0,1] row_mask:0xf bank_mask:0xf
	s_nop 1
	v_add_f32_dpp v186, v186, v186 row_half_mirror row_mask:0xf bank_mask:0xf
	s_nop 1
	v_add_f32_dpp v186, v186, v186 row_mirror row_mask:0xf bank_mask:0xf
	v_fmamk_f32 v186, v186, 0x3c800000, v173
	v_rsq_f32_e32 v186, v186
	s_nop 0
	v_mul_f32_e32 v187, v178, v186
	v_mul_f32_e32 v188, v179, v186
	v_mul_f32_e32 v189, v180, v186
	v_mul_f32_e32 v190, v181, v186
	v_mul_f32_e32 v182, v49, v187
	v_mul_f32_e32 v183, v45, v188
	v_mul_f32_e32 v184, v41, v189
	v_mul_f32_e32 v185, v37, v190
	v_cvt_pk_bf16_f32 v192, v182, v183
	v_cvt_pk_bf16_f32 v193, v184, v185
	ds_write_b16 v170, v192 offset:2736
	ds_write_b16_d16_hi v170, v192 offset:2768
	ds_write_b16 v170, v193 offset:2800
	ds_write_b16_d16_hi v170, v193 offset:2832
	v_mul_f32_e32 v182, v30, v30
	v_mul_f32_e32 v183, v26, v26
	v_mul_f32_e32 v184, v22, v22
	v_mul_f32_e32 v185, v18, v18
	v_add_f32_e32 v186, v182, v183
	v_add_f32_e32 v186, v186, v184
	v_add_f32_e32 v186, v186, v185
	s_nop 1
	v_add_f32_dpp v186, v186, v186 quad_perm:[1,0,3,2] row_mask:0xf bank_mask:0xf
	s_nop 1
	v_add_f32_dpp v186, v186, v186 quad_perm:[2,3,0,1] row_mask:0xf bank_mask:0xf
	s_nop 1
	v_add_f32_dpp v186, v186, v186 row_half_mirror row_mask:0xf bank_mask:0xf
	s_nop 1
	v_add_f32_dpp v186, v186, v186 row_mirror row_mask:0xf bank_mask:0xf
	v_fmamk_f32 v186, v186, 0x3c800000, v173
	v_rsq_f32_e32 v186, v186
	s_nop 0
	v_mul_f32_e32 v187, v178, v186
	v_mul_f32_e32 v188, v179, v186
	v_mul_f32_e32 v189, v180, v186
	v_mul_f32_e32 v190, v181, v186
	v_mul_f32_e32 v182, v30, v187
	v_mul_f32_e32 v183, v26, v188
	v_mul_f32_e32 v184, v22, v189
	v_mul_f32_e32 v185, v18, v190
	v_cvt_pk_bf16_f32 v192, v182, v183
	v_cvt_pk_bf16_f32 v193, v184, v185
	ds_write_b16 v170, v192 offset:4608
	ds_write_b16_d16_hi v170, v192 offset:4640
	ds_write_b16 v170, v193 offset:4672
	ds_write_b16_d16_hi v170, v193 offset:4704
	v_mul_f32_e32 v182, v31, v31
	v_mul_f32_e32 v183, v27, v27
	v_mul_f32_e32 v184, v23, v23
	v_mul_f32_e32 v185, v19, v19
	v_add_f32_e32 v186, v182, v183
	v_add_f32_e32 v186, v186, v184
	v_add_f32_e32 v186, v186, v185
	s_nop 1
	v_add_f32_dpp v186, v186, v186 quad_perm:[1,0,3,2] row_mask:0xf bank_mask:0xf
	s_nop 1
	v_add_f32_dpp v186, v186, v186 quad_perm:[2,3,0,1] row_mask:0xf bank_mask:0xf
	s_nop 1
	v_add_f32_dpp v186, v186, v186 row_half_mirror row_mask:0xf bank_mask:0xf
	s_nop 1
	v_add_f32_dpp v186, v186, v186 row_mirror row_mask:0xf bank_mask:0xf
	v_fmamk_f32 v186, v186, 0x3c800000, v173
	v_rsq_f32_e32 v186, v186
	s_nop 0
	v_mul_f32_e32 v187, v178, v186
	v_mul_f32_e32 v188, v179, v186
	v_mul_f32_e32 v189, v180, v186
	v_mul_f32_e32 v190, v181, v186
	v_mul_f32_e32 v182, v31, v187
	v_mul_f32_e32 v183, v27, v188
	v_mul_f32_e32 v184, v23, v189
	v_mul_f32_e32 v185, v19, v190
	v_cvt_pk_bf16_f32 v192, v182, v183
	v_cvt_pk_bf16_f32 v193, v184, v185
	ds_write_b16 v170, v192 offset:4752
	ds_write_b16_d16_hi v170, v192 offset:4784
	ds_write_b16 v170, v193 offset:4816
	ds_write_b16_d16_hi v170, v193 offset:4848
	v_mul_f32_e32 v182, v32, v32
	v_mul_f32_e32 v183, v28, v28
	v_mul_f32_e32 v184, v24, v24
	v_mul_f32_e32 v185, v20, v20
	v_add_f32_e32 v186, v182, v183
	v_add_f32_e32 v186, v186, v184
	v_add_f32_e32 v186, v186, v185
	s_nop 1
	v_add_f32_dpp v186, v186, v186 quad_perm:[1,0,3,2] row_mask:0xf bank_mask:0xf
	s_nop 1
	v_add_f32_dpp v186, v186, v186 quad_perm:[2,3,0,1] row_mask:0xf bank_mask:0xf
	s_nop 1
	v_add_f32_dpp v186, v186, v186 row_half_mirror row_mask:0xf bank_mask:0xf
	s_nop 1
	v_add_f32_dpp v186, v186, v186 row_mirror row_mask:0xf bank_mask:0xf
	v_fmamk_f32 v186, v186, 0x3c800000, v173
	v_rsq_f32_e32 v186, v186
	s_nop 0
	v_mul_f32_e32 v187, v178, v186
	v_mul_f32_e32 v188, v179, v186
	v_mul_f32_e32 v189, v180, v186
	v_mul_f32_e32 v190, v181, v186
	v_mul_f32_e32 v182, v32, v187
	v_mul_f32_e32 v183, v28, v188
	v_mul_f32_e32 v184, v24, v189
	v_mul_f32_e32 v185, v20, v190
	v_cvt_pk_bf16_f32 v192, v182, v183
	v_cvt_pk_bf16_f32 v193, v184, v185
	ds_write_b16 v170, v192 offset:4896
	ds_write_b16_d16_hi v170, v192 offset:4928
	ds_write_b16 v170, v193 offset:4960
	ds_write_b16_d16_hi v170, v193 offset:4992
	v_mul_f32_e32 v182, v33, v33
	v_mul_f32_e32 v183, v29, v29
	v_mul_f32_e32 v184, v25, v25
	v_mul_f32_e32 v185, v21, v21
	v_add_f32_e32 v186, v182, v183
	v_add_f32_e32 v186, v186, v184
	v_add_f32_e32 v186, v186, v185
	s_nop 1
	v_add_f32_dpp v186, v186, v186 quad_perm:[1,0,3,2] row_mask:0xf bank_mask:0xf
	s_nop 1
	v_add_f32_dpp v186, v186, v186 quad_perm:[2,3,0,1] row_mask:0xf bank_mask:0xf
	s_nop 1
	v_add_f32_dpp v186, v186, v186 row_half_mirror row_mask:0xf bank_mask:0xf
	s_nop 1
	v_add_f32_dpp v186, v186, v186 row_mirror row_mask:0xf bank_mask:0xf
	v_fmamk_f32 v186, v186, 0x3c800000, v173
	v_rsq_f32_e32 v186, v186
	s_nop 0
	v_mul_f32_e32 v187, v178, v186
	v_mul_f32_e32 v188, v179, v186
	v_mul_f32_e32 v189, v180, v186
	v_mul_f32_e32 v190, v181, v186
	v_mul_f32_e32 v182, v33, v187
	v_mul_f32_e32 v183, v29, v188
	v_mul_f32_e32 v184, v25, v189
	v_mul_f32_e32 v185, v21, v190
	v_cvt_pk_bf16_f32 v192, v182, v183
	v_cvt_pk_bf16_f32 v193, v184, v185
	ds_write_b16 v170, v192 offset:5040
	ds_write_b16_d16_hi v170, v192 offset:5072
	ds_write_b16 v170, v193 offset:5104
; template <int EPI>
; DI void gemm_phase(const P& p, int l, const u16* __restrict__ A, const u16* __restrict__ Bt, int mpx, char* lds) {
;     ...
;             if (donorm) {
;               float ss = v0 * v0 + v1 * v1 + v2 * v2 + v3 * v3;
;               ss += __shfl_xor(ss, 1);
;               ss += __shfl_xor(ss, 2);
;               ss += __shfl_xor(ss, 4);
;               ss += __shfl_xor(ss, 8);
;               const float inv = rsqrtf(ss * (1.f / 64.f) + 1e-6f);
;               v0 *= inv * gv0; v1 *= inv * gv1; v2 *= inv * gv2; v3 *= inv * gv3;
;             }
;     ...
;       u16* dh = (kind == 1) ? dst + hf * 64 : dst + (size_t)(hf * 64) * rstride;
; #pragma unroll
;       for (int i = 0; i < 8; ++i) {
;         const int c = lane + i * 64;
;         const int row = c >> 3, cc = c & 7;
;         uint4 v = *(const uint4*)&Tl[row * 72 + cc * 8];
;         *(uint4*)(dh + (size_t)row * rstride + cc * 8) = v;
;       }
	ds_write_b16_d16_hi v170, v193 offset:5136
	v_mul_f32_e32 v182, v166, v166
	v_mul_f32_e32 v183, v162, v162
	v_mul_f32_e32 v184, v2, v2
	v_mul_f32_e32 v185, v6, v6
	v_add_f32_e32 v186, v182, v183
	v_add_f32_e32 v186, v186, v184
	v_add_f32_e32 v186, v186, v185
	s_nop 1
	v_add_f32_dpp v186, v186, v186 quad_perm:[1,0,3,2] row_mask:0xf bank_mask:0xf
	s_nop 1
	v_add_f32_dpp v186, v186, v186 quad_perm:[2,3,0,1] row_mask:0xf bank_mask:0xf
	s_nop 1
	v_add_f32_dpp v186, v186, v186 row_half_mirror row_mask:0xf bank_mask:0xf
	s_nop 1
	v_add_f32_dpp v186, v186, v186 row_mirror row_mask:0xf bank_mask:0xf
	v_fmamk_f32 v186, v186, 0x3c800000, v173
	v_rsq_f32_e32 v186, v186
	s_nop 0
	v_mul_f32_e32 v187, v178, v186
	v_mul_f32_e32 v188, v179, v186
	v_mul_f32_e32 v189, v180, v186
	v_mul_f32_e32 v190, v181, v186
	v_mul_f32_e32 v182, v166, v187
	v_mul_f32_e32 v183, v162, v188
	v_mul_f32_e32 v184, v2, v189
	v_mul_f32_e32 v185, v6, v190
	v_cvt_pk_bf16_f32 v192, v182, v183
	v_cvt_pk_bf16_f32 v193, v184, v185
	ds_write_b16 v170, v192 offset:6912
	ds_write_b16_d16_hi v170, v192 offset:6944
	ds_write_b16 v170, v193 offset:6976
	ds_write_b16_d16_hi v170, v193 offset:7008
	v_mul_f32_e32 v182, v167, v167
	v_mul_f32_e32 v183, v163, v163
	v_mul_f32_e32 v184, v3, v3
	v_mul_f32_e32 v185, v7, v7
	v_add_f32_e32 v186, v182, v183
	v_add_f32_e32 v186, v186, v184
	v_add_f32_e32 v186, v186, v185
	s_nop 1
	v_add_f32_dpp v186, v186, v186 quad_perm:[1,0,3,2] row_mask:0xf bank_mask:0xf
	s_nop 1
	v_add_f32_dpp v186, v186, v186 quad_perm:[2,3,0,1] row_mask:0xf bank_mask:0xf
	s_nop 1
	v_add_f32_dpp v186, v186, v186 row_half_mirror row_mask:0xf bank_mask:0xf
	s_nop 1
	v_add_f32_dpp v186, v186, v186 row_mirror row_mask:0xf bank_mask:0xf
	v_fmamk_f32 v186, v186, 0x3c800000, v173
	v_rsq_f32_e32 v186, v186
	s_nop 0
	v_mul_f32_e32 v187, v178, v186
	v_mul_f32_e32 v188, v179, v186
	v_mul_f32_e32 v189, v180, v186
	v_mul_f32_e32 v190, v181, v186
	v_mul_f32_e32 v182, v167, v187
	v_mul_f32_e32 v183, v163, v188
	v_mul_f32_e32 v184, v3, v189
	v_mul_f32_e32 v185, v7, v190
	v_cvt_pk_bf16_f32 v192, v182, v183
	v_cvt_pk_bf16_f32 v193, v184, v185
	ds_write_b16 v170, v192 offset:7056
	ds_write_b16_d16_hi v170, v192 offset:7088
	ds_write_b16 v170, v193 offset:7120
	ds_write_b16_d16_hi v170, v193 offset:7152
	v_mul_f32_e32 v182, v168, v168
	v_mul_f32_e32 v183, v164, v164
	v_mul_f32_e32 v184, v4, v4
	v_mul_f32_e32 v185, v8, v8
	v_add_f32_e32 v186, v182, v183
	v_add_f32_e32 v186, v186, v184
	v_add_f32_e32 v186, v186, v185
	s_nop 1
	v_add_f32_dpp v186, v186, v186 quad_perm:[1,0,3,2] row_mask:0xf bank_mask:0xf
	s_nop 1
	v_add_f32_dpp v186, v186, v186 quad_perm:[2,3,0,1] row_mask:0xf bank_mask:0xf
	s_nop 1
	v_add_f32_dpp v186, v186, v186 row_half_mirror row_mask:0xf bank_mask:0xf
	s_nop 1
	v_add_f32_dpp v186, v186, v186 row_mirror row_mask:0xf bank_mask:0xf
	v_fmamk_f32 v186, v186, 0x3c800000, v173
	v_rsq_f32_e32 v186, v186
	s_nop 0
	v_mul_f32_e32 v187, v178, v186
	v_mul_f32_e32 v188, v179, v186
	v_mul_f32_e32 v189, v180, v186
	v_mul_f32_e32 v190, v181, v186
	v_mul_f32_e32 v182, v168, v187
	v_mul_f32_e32 v183, v164, v188
	v_mul_f32_e32 v184, v4, v189
	v_mul_f32_e32 v185, v8, v190
	v_cvt_pk_bf16_f32 v192, v182, v183
	v_cvt_pk_bf16_f32 v193, v184, v185
	ds_write_b16 v170, v192 offset:7200
	ds_write_b16_d16_hi v170, v192 offset:7232
	ds_write_b16 v170, v193 offset:7264
	ds_write_b16_d16_hi v170, v193 offset:7296
	v_mul_f32_e32 v182, v169, v169
	v_mul_f32_e32 v183, v165, v165
	v_mul_f32_e32 v184, v5, v5
	v_mul_f32_e32 v185, v9, v9
	v_add_f32_e32 v186, v182, v183
	v_add_f32_e32 v186, v186, v184
	v_add_f32_e32 v186, v186, v185
	s_nop 1
	v_add_f32_dpp v186, v186, v186 quad_perm:[1,0,3,2] row_mask:0xf bank_mask:0xf
	s_nop 1
	v_add_f32_dpp v186, v186, v186 quad_perm:[2,3,0,1] row_mask:0xf bank_mask:0xf
	s_nop 1
	v_add_f32_dpp v186, v186, v186 row_half_mirror row_mask:0xf bank_mask:0xf
	s_nop 1
	v_add_f32_dpp v186, v186, v186 row_mirror row_mask:0xf bank_mask:0xf
	v_fmamk_f32 v186, v186, 0x3c800000, v173
	v_rsq_f32_e32 v186, v186
	s_nop 0
	v_mul_f32_e32 v187, v178, v186
	v_mul_f32_e32 v188, v179, v186
	v_mul_f32_e32 v189, v180, v186
	v_mul_f32_e32 v190, v181, v186
	v_mul_f32_e32 v182, v169, v187
	v_mul_f32_e32 v183, v165, v188
	v_mul_f32_e32 v184, v5, v189
	v_mul_f32_e32 v185, v9, v190
	v_cvt_pk_bf16_f32 v192, v182, v183
	v_cvt_pk_bf16_f32 v193, v184, v185
	ds_write_b16 v170, v192 offset:7344
	ds_write_b16_d16_hi v170, v192 offset:7376
	ds_write_b16 v170, v193 offset:7408
	ds_write_b16_d16_hi v170, v193 offset:7440
	ds_read_b128 v[130:133], v171 offset:0
	ds_read_b128 v[134:137], v171 offset:1152
	ds_read_b128 v[138:141], v171 offset:2304
	ds_read_b128 v[142:145], v171 offset:3456
	ds_read_b128 v[146:149], v171 offset:4608
	ds_read_b128 v[150:153], v171 offset:5760
	ds_read_b128 v[154:157], v171 offset:6912
	ds_read_b128 v[158:161], v171 offset:8064
	s_waitcnt lgkmcnt(7)
	global_store_dwordx4 v172, v[130:133], s[44:45] offset:0
	s_waitcnt lgkmcnt(6)
	global_store_dwordx4 v172, v[134:137], s[44:45] offset:1024
	s_waitcnt lgkmcnt(5)
	global_store_dwordx4 v172, v[138:141], s[44:45] offset:2048
	s_waitcnt lgkmcnt(4)
	global_store_dwordx4 v172, v[142:145], s[44:45] offset:3072
	s_waitcnt lgkmcnt(3)
	global_store_dwordx4 v172, v[146:149], s[62:63] offset:0
	s_waitcnt lgkmcnt(2)
	global_store_dwordx4 v172, v[150:153], s[62:63] offset:1024
	s_waitcnt lgkmcnt(1)
	global_store_dwordx4 v172, v[154:157], s[62:63] offset:2048
	s_waitcnt lgkmcnt(0)
	global_store_dwordx4 v172, v[158:161], s[62:63] offset:3072
	s_branch .Lfe_done

; template <int EPI>
; DI void gemm_phase(const P& p, int l, const u16* __restrict__ A, const u16* __restrict__ Bt, int mpx, char* lds) {
;     ...
;   if (!has_next) break;
;   t = tn; m0 = m1; n0 = n1; Ag = Agn; Bg = Bgn;
.Lfe_done:
	v_mov_b32_e32 v236, 0x358637bd
	s_and_b64 vcc, exec, s[54:55]
	s_mov_b32 s46, s51
	s_mov_b32 s66, s56
	s_mov_b64 s[0:1], s[60:61]
	s_mov_b64 s[40:41], s[58:59]
	s_cbranch_vccnz .LBB0_811
	s_branch .LBB0_79
.LBB0_811:
	s_mov_b64 s[0:1], 0
